# GEMM k-loops: LDS-DMA pieces whose address temp is dead use scalar-base + 32-bit lane-offset form (drops a 64-bit VALU add per piece)
# baseline (speedup 1.0000x reference)
.LBB0_240:
	s_add_u32 s40, s38, 0xfff80080
	s_addc_u32 s41, s39, -1
	s_add_i32 s54, 0, 0x10000
	s_cmp_eq_u32 s53, 28
	s_cselect_b32 s43, s5, s41
	s_cselect_b32 s42, s7, s40
	s_cselect_b32 s41, s29, s52
	s_cselect_b32 s40, s31, s51
	s_add_i32 s56, 0, 0x14000
	v_add_u32_e32 v84, s54, v176
	v_add_u32_e32 v158, s56, v176
	ds_read_b128 v[64:67], v84
	ds_read_b128 v[68:71], v84 offset:1024
	ds_read_b128 v[80:83], v84 offset:2048
	ds_read_b128 v[84:87], v84 offset:3072
	ds_read_b128 v[154:157], v158
	ds_read_b128 v[172:175], v158 offset:1024
	ds_read_b128 v[180:183], v158 offset:2048
	ds_read_b128 v[184:187], v158 offset:3072
	v_lshl_add_u64 v[158:159], s[38:39], 0, v[150:151]
	s_add_i32 m0, s44, 0xc000
	ds_read_b128 v[196:199], v178
	ds_read_b128 v[200:203], v178 offset:1024
	ds_read_b128 v[204:207], v178 offset:2048
	ds_read_b128 v[234:237], v178 offset:3072
	ds_read_b128 v[238:241], v178 offset:4096
	ds_read_b128 v[242:245], v178 offset:5120
	ds_read_b128 v[246:249], v178 offset:6144
	ds_read_b128 v[208:211], v178 offset:7168
	global_load_lds_dwordx4 v[158:159], off
	v_lshl_add_u64 v[158:159], s[38:39], 0, v[152:153]
	s_add_i32 m0, s44, 0xe000
	s_nop 0
	global_load_lds_dwordx4 v[158:159], off
	s_waitcnt vmcnt(8)
	s_waitcnt lgkmcnt(0)
	s_barrier
	s_setprio 1
	s_waitcnt lgkmcnt(0)
	v_mfma_f32_16x16x32_bf16 v[140:143], v[64:67], v[196:199], v[140:143]
	v_mfma_f32_16x16x32_bf16 v[136:139], v[80:83], v[196:199], v[136:139]
	v_mfma_f32_16x16x32_bf16 v[124:127], v[64:67], v[204:207], v[124:127]
	v_mfma_f32_16x16x32_bf16 v[120:123], v[80:83], v[204:207], v[120:123]
	v_mfma_f32_16x16x32_bf16 v[108:111], v[64:67], v[238:241], v[108:111]
	v_mfma_f32_16x16x32_bf16 v[104:107], v[80:83], v[238:241], v[104:107]
	v_mfma_f32_16x16x32_bf16 v[92:95], v[64:67], v[246:249], v[92:95]
	v_mfma_f32_16x16x32_bf16 v[88:91], v[80:83], v[246:249], v[88:91]
	v_mfma_f32_16x16x32_bf16 v[140:143], v[68:71], v[200:203], v[140:143]
	v_mfma_f32_16x16x32_bf16 v[136:139], v[84:87], v[200:203], v[136:139]
	v_mfma_f32_16x16x32_bf16 v[124:127], v[68:71], v[234:237], v[124:127]
	v_mfma_f32_16x16x32_bf16 v[120:123], v[84:87], v[234:237], v[120:123]
	v_mfma_f32_16x16x32_bf16 v[108:111], v[68:71], v[242:245], v[108:111]
	v_mfma_f32_16x16x32_bf16 v[104:107], v[84:87], v[242:245], v[104:107]
	v_mfma_f32_16x16x32_bf16 v[92:95], v[68:71], v[208:211], v[92:95]
	v_mfma_f32_16x16x32_bf16 v[88:91], v[84:87], v[208:211], v[88:91]
	s_setprio 0
	s_setprio 1
	v_mfma_f32_16x16x32_bf16 v[132:135], v[154:157], v[196:199], v[132:135]
	v_mfma_f32_16x16x32_bf16 v[128:131], v[180:183], v[196:199], v[128:131]
	v_mfma_f32_16x16x32_bf16 v[116:119], v[154:157], v[204:207], v[116:119]
	v_mfma_f32_16x16x32_bf16 v[112:115], v[180:183], v[204:207], v[112:115]
	v_mfma_f32_16x16x32_bf16 v[100:103], v[154:157], v[238:241], v[100:103]
	v_mfma_f32_16x16x32_bf16 v[96:99], v[180:183], v[238:241], v[96:99]
	v_mfma_f32_16x16x32_bf16 v[76:79], v[154:157], v[246:249], v[76:79]
	v_mfma_f32_16x16x32_bf16 v[72:75], v[180:183], v[246:249], v[72:75]
	v_mfma_f32_16x16x32_bf16 v[132:135], v[172:175], v[200:203], v[132:135]
	v_mfma_f32_16x16x32_bf16 v[128:131], v[184:187], v[200:203], v[128:131]
	v_mfma_f32_16x16x32_bf16 v[116:119], v[172:175], v[234:237], v[116:119]
	v_mfma_f32_16x16x32_bf16 v[112:115], v[184:187], v[234:237], v[112:115]
	v_mfma_f32_16x16x32_bf16 v[100:103], v[172:175], v[242:245], v[100:103]
	v_mfma_f32_16x16x32_bf16 v[96:99], v[184:187], v[242:245], v[96:99]
	v_mfma_f32_16x16x32_bf16 v[76:79], v[172:175], v[208:211], v[76:79]
	v_mfma_f32_16x16x32_bf16 v[72:75], v[184:187], v[208:211], v[72:75]
	s_setprio 0
	s_barrier
	s_add_i32 s54, s54, s24
	v_lshl_add_u64 v[158:159], s[40:41], 0, v[160:161]
	s_mov_b32 m0, s54
	ds_read_b128 v[196:199], v178 offset:16384
	ds_read_b128 v[200:203], v178 offset:17408
	ds_read_b128 v[204:207], v178 offset:18432
	ds_read_b128 v[208:211], v178 offset:19456
	ds_read_b128 v[234:237], v178 offset:20480
	ds_read_b128 v[238:241], v178 offset:21504
	ds_read_b128 v[242:245], v178 offset:22528
	ds_read_b128 v[246:249], v178 offset:23552
	global_load_lds_dwordx4 v[158:159], off
	s_add_i32 m0, s54, 0x2000
	s_add_u32 s54, s40, 0x80000
	v_lshl_add_u64 v[188:189], s[40:41], 0, v[148:149]
	s_addc_u32 s55, s41, 0
	s_add_i32 s56, s56, s24
	global_load_lds_dwordx4 v[188:189], off
	s_mov_b32 m0, s56
	v_lshl_add_u64 v[214:215], s[42:43], 0, v[146:147]
	global_load_lds_dwordx4 v160, s[54:55]
	s_add_i32 m0, s56, 0x2000
	s_nop 0
	global_load_lds_dwordx4 v148, s[54:55]
	v_lshl_add_u64 v[212:213], s[42:43], 0, v[144:145]
	s_mov_b32 m0, s44
	s_nop 0
	global_load_lds_dwordx4 v[212:213], off
	s_mov_b32 m0, s45
	s_nop 0
	global_load_lds_dwordx4 v[214:215], off
	s_waitcnt vmcnt(8)
	s_waitcnt lgkmcnt(0)
	s_barrier
	s_setprio 1
	s_waitcnt lgkmcnt(0)
	v_mfma_f32_16x16x32_bf16 v[60:63], v[64:67], v[196:199], v[60:63]
	v_mfma_f32_16x16x32_bf16 v[56:59], v[80:83], v[196:199], v[56:59]
	v_mfma_f32_16x16x32_bf16 v[44:47], v[64:67], v[204:207], v[44:47]
	v_mfma_f32_16x16x32_bf16 v[40:43], v[80:83], v[204:207], v[40:43]
	v_mfma_f32_16x16x32_bf16 v[28:31], v[64:67], v[234:237], v[28:31]
	v_mfma_f32_16x16x32_bf16 v[24:27], v[80:83], v[234:237], v[24:27]
	v_mfma_f32_16x16x32_bf16 v[12:15], v[64:67], v[242:245], v[12:15]
	v_mfma_f32_16x16x32_bf16 v[8:11], v[80:83], v[242:245], v[8:11]
	v_mfma_f32_16x16x32_bf16 v[60:63], v[68:71], v[200:203], v[60:63]
	v_mfma_f32_16x16x32_bf16 v[56:59], v[84:87], v[200:203], v[56:59]
	v_mfma_f32_16x16x32_bf16 v[44:47], v[68:71], v[208:211], v[44:47]
	v_mfma_f32_16x16x32_bf16 v[40:43], v[84:87], v[208:211], v[40:43]
	v_mfma_f32_16x16x32_bf16 v[28:31], v[68:71], v[238:241], v[28:31]
	v_mfma_f32_16x16x32_bf16 v[24:27], v[84:87], v[238:241], v[24:27]
	v_mfma_f32_16x16x32_bf16 v[12:15], v[68:71], v[246:249], v[12:15]
	v_mfma_f32_16x16x32_bf16 v[8:11], v[84:87], v[246:249], v[8:11]
	s_setprio 0
	s_setprio 1
	v_mfma_f32_16x16x32_bf16 v[52:55], v[154:157], v[196:199], v[52:55]
	v_mfma_f32_16x16x32_bf16 v[48:51], v[180:183], v[196:199], v[48:51]
	v_mfma_f32_16x16x32_bf16 v[36:39], v[154:157], v[204:207], v[36:39]
	v_mfma_f32_16x16x32_bf16 v[32:35], v[180:183], v[204:207], v[32:35]
	v_mfma_f32_16x16x32_bf16 v[20:23], v[154:157], v[234:237], v[20:23]
	v_mfma_f32_16x16x32_bf16 v[16:19], v[180:183], v[234:237], v[16:19]
	v_mfma_f32_16x16x32_bf16 v[4:7], v[154:157], v[242:245], v[4:7]
	v_mfma_f32_16x16x32_bf16 v[0:3], v[180:183], v[242:245], v[0:3]
	v_mfma_f32_16x16x32_bf16 v[52:55], v[172:175], v[200:203], v[52:55]
	v_mfma_f32_16x16x32_bf16 v[48:51], v[184:187], v[200:203], v[48:51]
	v_mfma_f32_16x16x32_bf16 v[36:39], v[172:175], v[208:211], v[36:39]
	v_mfma_f32_16x16x32_bf16 v[32:35], v[184:187], v[208:211], v[32:35]
	v_mfma_f32_16x16x32_bf16 v[20:23], v[172:175], v[238:241], v[20:23]
	v_mfma_f32_16x16x32_bf16 v[16:19], v[184:187], v[238:241], v[16:19]
	v_mfma_f32_16x16x32_bf16 v[4:7], v[172:175], v[246:249], v[4:7]
	v_mfma_f32_16x16x32_bf16 v[0:3], v[184:187], v[246:249], v[0:3]
	s_setprio 0
	s_barrier
	s_add_i32 s54, 0, 0x18000
	s_add_i32 s55, 0, 0x1c000
	v_add_u32_e32 v84, s54, v176
	v_add_u32_e32 v179, s55, v176
	ds_read_b128 v[64:67], v84
	ds_read_b128 v[68:71], v84 offset:1024
	ds_read_b128 v[80:83], v84 offset:2048
	ds_read_b128 v[84:87], v84 offset:3072
	ds_read_b128 v[154:157], v179
	ds_read_b128 v[172:175], v179 offset:1024
	ds_read_b128 v[180:183], v179 offset:2048
	ds_read_b128 v[184:187], v179 offset:3072
	s_add_u32 s42, s42, 0x80000
	s_addc_u32 s43, s43, 0
	s_mov_b32 m0, s46
	ds_read_b128 v[196:199], v178 offset:32768
	ds_read_b128 v[200:203], v178 offset:33792
	ds_read_b128 v[204:207], v178 offset:34816
	ds_read_b128 v[208:211], v178 offset:35840
	ds_read_b128 v[234:237], v178 offset:36864
	ds_read_b128 v[238:241], v178 offset:37888
	ds_read_b128 v[242:245], v178 offset:38912
	ds_read_b128 v[246:249], v178 offset:39936
	global_load_lds_dwordx4 v144, s[42:43]
	s_mov_b32 m0, s47
	s_nop 0
	global_load_lds_dwordx4 v146, s[42:43]
	s_waitcnt vmcnt(8)
	s_waitcnt lgkmcnt(0)
	s_barrier
	s_setprio 1
	s_waitcnt lgkmcnt(0)
	v_mfma_f32_16x16x32_bf16 v[140:143], v[64:67], v[196:199], v[140:143]
	v_mfma_f32_16x16x32_bf16 v[136:139], v[80:83], v[196:199], v[136:139]
	v_mfma_f32_16x16x32_bf16 v[124:127], v[64:67], v[204:207], v[124:127]
	v_mfma_f32_16x16x32_bf16 v[120:123], v[80:83], v[204:207], v[120:123]
	v_mfma_f32_16x16x32_bf16 v[108:111], v[64:67], v[234:237], v[108:111]
	v_mfma_f32_16x16x32_bf16 v[104:107], v[80:83], v[234:237], v[104:107]
	v_mfma_f32_16x16x32_bf16 v[92:95], v[64:67], v[242:245], v[92:95]
	v_mfma_f32_16x16x32_bf16 v[88:91], v[80:83], v[242:245], v[88:91]
	v_mfma_f32_16x16x32_bf16 v[140:143], v[68:71], v[200:203], v[140:143]
	v_mfma_f32_16x16x32_bf16 v[136:139], v[84:87], v[200:203], v[136:139]
	v_mfma_f32_16x16x32_bf16 v[124:127], v[68:71], v[208:211], v[124:127]
	v_mfma_f32_16x16x32_bf16 v[120:123], v[84:87], v[208:211], v[120:123]
	v_mfma_f32_16x16x32_bf16 v[108:111], v[68:71], v[238:241], v[108:111]
	v_mfma_f32_16x16x32_bf16 v[104:107], v[84:87], v[238:241], v[104:107]
	v_mfma_f32_16x16x32_bf16 v[92:95], v[68:71], v[246:249], v[92:95]
	v_mfma_f32_16x16x32_bf16 v[88:91], v[84:87], v[246:249], v[88:91]
	s_setprio 0
	s_setprio 1
	v_mfma_f32_16x16x32_bf16 v[132:135], v[154:157], v[196:199], v[132:135]
	v_mfma_f32_16x16x32_bf16 v[128:131], v[180:183], v[196:199], v[128:131]
	v_mfma_f32_16x16x32_bf16 v[116:119], v[154:157], v[204:207], v[116:119]
	v_mfma_f32_16x16x32_bf16 v[112:115], v[180:183], v[204:207], v[112:115]
	v_mfma_f32_16x16x32_bf16 v[100:103], v[154:157], v[234:237], v[100:103]
	v_mfma_f32_16x16x32_bf16 v[96:99], v[180:183], v[234:237], v[96:99]
	v_mfma_f32_16x16x32_bf16 v[76:79], v[154:157], v[242:245], v[76:79]
	v_mfma_f32_16x16x32_bf16 v[72:75], v[180:183], v[242:245], v[72:75]
	v_mfma_f32_16x16x32_bf16 v[132:135], v[172:175], v[200:203], v[132:135]
	v_mfma_f32_16x16x32_bf16 v[128:131], v[184:187], v[200:203], v[128:131]
	v_mfma_f32_16x16x32_bf16 v[116:119], v[172:175], v[208:211], v[116:119]
	v_mfma_f32_16x16x32_bf16 v[112:115], v[184:187], v[208:211], v[112:115]
	v_mfma_f32_16x16x32_bf16 v[100:103], v[172:175], v[238:241], v[100:103]
	v_mfma_f32_16x16x32_bf16 v[96:99], v[184:187], v[238:241], v[96:99]
	v_mfma_f32_16x16x32_bf16 v[76:79], v[172:175], v[246:249], v[76:79]
	v_mfma_f32_16x16x32_bf16 v[72:75], v[184:187], v[246:249], v[72:75]
	s_setprio 0
	s_barrier
	s_add_i32 s42, s54, s24
	v_lshl_add_u64 v[158:159], v[158:159], 0, s[20:21]
	s_mov_b32 m0, s42
	ds_read_b128 v[196:199], v178 offset:49152
	ds_read_b128 v[200:203], v178 offset:50176
	ds_read_b128 v[204:207], v178 offset:51200
	ds_read_b128 v[208:211], v178 offset:52224
	ds_read_b128 v[234:237], v178 offset:53248
	ds_read_b128 v[238:241], v178 offset:54272
	ds_read_b128 v[242:245], v178 offset:55296
	ds_read_b128 v[246:249], v178 offset:56320
	global_load_lds_dwordx4 v[158:159], off
	s_add_i32 m0, s42, 0x2000
	s_add_u32 s40, s40, 0x80080
	v_lshl_add_u64 v[158:159], v[188:189], 0, s[20:21]
	s_addc_u32 s41, s41, 0
	s_add_i32 s42, s55, s24
	global_load_lds_dwordx4 v[158:159], off
	v_lshl_add_u64 v[158:159], s[40:41], 0, v[160:161]
	s_mov_b32 m0, s42
	s_nop 0
	global_load_lds_dwordx4 v[158:159], off
	v_lshl_add_u64 v[158:159], s[40:41], 0, v[148:149]
	s_add_i32 m0, s42, 0x2000
	s_nop 0
	global_load_lds_dwordx4 v[158:159], off
	v_lshl_add_u64 v[158:159], v[212:213], 0, s[20:21]
	s_mov_b32 m0, s48
	s_nop 0
	global_load_lds_dwordx4 v[158:159], off
	v_lshl_add_u64 v[158:159], v[214:215], 0, s[20:21]
	s_mov_b32 m0, s49
	s_nop 0
	global_load_lds_dwordx4 v[158:159], off
	s_waitcnt vmcnt(8)
	s_waitcnt lgkmcnt(0)
	s_barrier
	s_setprio 1
	s_waitcnt lgkmcnt(0)
	v_mfma_f32_16x16x32_bf16 v[60:63], v[64:67], v[196:199], v[60:63]
	v_mfma_f32_16x16x32_bf16 v[56:59], v[80:83], v[196:199], v[56:59]
	v_mfma_f32_16x16x32_bf16 v[44:47], v[64:67], v[204:207], v[44:47]
	v_mfma_f32_16x16x32_bf16 v[40:43], v[80:83], v[204:207], v[40:43]
	v_mfma_f32_16x16x32_bf16 v[28:31], v[64:67], v[234:237], v[28:31]
	v_mfma_f32_16x16x32_bf16 v[24:27], v[80:83], v[234:237], v[24:27]
	v_mfma_f32_16x16x32_bf16 v[12:15], v[64:67], v[242:245], v[12:15]
	v_mfma_f32_16x16x32_bf16 v[8:11], v[80:83], v[242:245], v[8:11]
	v_mfma_f32_16x16x32_bf16 v[60:63], v[68:71], v[200:203], v[60:63]
	v_mfma_f32_16x16x32_bf16 v[56:59], v[84:87], v[200:203], v[56:59]
	v_mfma_f32_16x16x32_bf16 v[44:47], v[68:71], v[208:211], v[44:47]
	v_mfma_f32_16x16x32_bf16 v[40:43], v[84:87], v[208:211], v[40:43]
	v_mfma_f32_16x16x32_bf16 v[28:31], v[68:71], v[238:241], v[28:31]
	v_mfma_f32_16x16x32_bf16 v[24:27], v[84:87], v[238:241], v[24:27]
	v_mfma_f32_16x16x32_bf16 v[12:15], v[68:71], v[246:249], v[12:15]
	v_mfma_f32_16x16x32_bf16 v[8:11], v[84:87], v[246:249], v[8:11]
	s_setprio 0
	s_setprio 1
	v_mfma_f32_16x16x32_bf16 v[52:55], v[154:157], v[196:199], v[52:55]
	v_mfma_f32_16x16x32_bf16 v[48:51], v[180:183], v[196:199], v[48:51]
	v_mfma_f32_16x16x32_bf16 v[36:39], v[154:157], v[204:207], v[36:39]
	v_mfma_f32_16x16x32_bf16 v[32:35], v[180:183], v[204:207], v[32:35]
	v_mfma_f32_16x16x32_bf16 v[20:23], v[154:157], v[234:237], v[20:23]
	v_mfma_f32_16x16x32_bf16 v[16:19], v[180:183], v[234:237], v[16:19]
	v_mfma_f32_16x16x32_bf16 v[4:7], v[154:157], v[242:245], v[4:7]
	v_mfma_f32_16x16x32_bf16 v[0:3], v[180:183], v[242:245], v[0:3]
	v_mfma_f32_16x16x32_bf16 v[52:55], v[172:175], v[200:203], v[52:55]
	v_mfma_f32_16x16x32_bf16 v[48:51], v[184:187], v[200:203], v[48:51]
	v_mfma_f32_16x16x32_bf16 v[36:39], v[172:175], v[208:211], v[36:39]
	v_mfma_f32_16x16x32_bf16 v[32:35], v[184:187], v[208:211], v[32:35]
	v_mfma_f32_16x16x32_bf16 v[20:23], v[172:175], v[238:241], v[20:23]
	v_mfma_f32_16x16x32_bf16 v[16:19], v[184:187], v[238:241], v[16:19]
	v_mfma_f32_16x16x32_bf16 v[4:7], v[172:175], v[246:249], v[4:7]
	v_mfma_f32_16x16x32_bf16 v[0:3], v[184:187], v[246:249], v[0:3]
	s_setprio 0
	s_barrier
	s_add_i32 s53, s53, 2
	s_add_u32 s38, s38, 0x100
	s_addc_u32 s39, s39, 0
	s_add_u32 s51, s51, 0x100
	s_addc_u32 s52, s52, 0
	s_cmp_gt_u32 s53, 29
	s_cbranch_scc0 .LBB0_240
	s_and_b64 vcc, exec, s[18:19]
	s_cbranch_vccz .LBB0_243
	s_barrier

.LBB0_352:
	s_add_u32 s30, s28, 0xfff80080
	s_addc_u32 s31, s29, -1
	s_add_i32 s52, 0, 0x10000
	s_cmp_eq_u32 s51, 28
	s_cselect_b32 s35, s15, s31
	s_cselect_b32 s34, s47, s30
	s_cselect_b32 s31, s13, s50
	s_cselect_b32 s30, s48, s49
	s_add_i32 s54, 0, 0x14000
	v_add_u32_e32 v154, s52, v143
	v_add_u32_e32 v158, s54, v143
	ds_read_b128 v[138:141], v154
	ds_read_b128 v[146:149], v154 offset:1024
	ds_read_b128 v[150:153], v154 offset:2048
	ds_read_b128 v[154:157], v154 offset:3072
	ds_read_b128 v[172:175], v158
	ds_read_b128 v[176:179], v158 offset:1024
	ds_read_b128 v[180:183], v158 offset:2048
	ds_read_b128 v[184:187], v158 offset:3072
	s_add_i32 m0, s38, 0xc000
	ds_read_b128 v[196:199], v145
	ds_read_b128 v[200:203], v145 offset:1024
	ds_read_b128 v[204:207], v145 offset:2048
	ds_read_b128 v[208:211], v145 offset:3072
	ds_read_b128 v[234:237], v145 offset:4096
	ds_read_b128 v[238:241], v145 offset:5120
	ds_read_b128 v[242:245], v145 offset:6144
	ds_read_b128 v[246:249], v145 offset:7168
	global_load_lds_dwordx4 v134, s[28:29]
	s_add_i32 m0, s38, 0xe000
	s_nop 0
	global_load_lds_dwordx4 v136, s[28:29]
	s_waitcnt vmcnt(8)
	s_waitcnt lgkmcnt(0)
	s_barrier
	s_setprio 1
	s_waitcnt lgkmcnt(0)
	v_mfma_f32_16x16x32_bf16 v[124:127], v[138:141], v[196:199], v[124:127]
	v_mfma_f32_16x16x32_bf16 v[120:123], v[150:153], v[196:199], v[120:123]
	v_mfma_f32_16x16x32_bf16 v[112:115], v[138:141], v[204:207], v[112:115]
	v_mfma_f32_16x16x32_bf16 v[104:107], v[150:153], v[204:207], v[104:107]
	v_mfma_f32_16x16x32_bf16 v[92:95], v[138:141], v[234:237], v[92:95]
	v_mfma_f32_16x16x32_bf16 v[88:91], v[150:153], v[234:237], v[88:91]
	v_mfma_f32_16x16x32_bf16 v[80:83], v[138:141], v[242:245], v[80:83]
	v_mfma_f32_16x16x32_bf16 v[72:75], v[150:153], v[242:245], v[72:75]
	v_mfma_f32_16x16x32_bf16 v[124:127], v[146:149], v[200:203], v[124:127]
	v_mfma_f32_16x16x32_bf16 v[120:123], v[154:157], v[200:203], v[120:123]
	v_mfma_f32_16x16x32_bf16 v[112:115], v[146:149], v[208:211], v[112:115]
	v_mfma_f32_16x16x32_bf16 v[104:107], v[154:157], v[208:211], v[104:107]
	v_mfma_f32_16x16x32_bf16 v[92:95], v[146:149], v[238:241], v[92:95]
	v_mfma_f32_16x16x32_bf16 v[88:91], v[154:157], v[238:241], v[88:91]
	v_mfma_f32_16x16x32_bf16 v[80:83], v[146:149], v[246:249], v[80:83]
	v_mfma_f32_16x16x32_bf16 v[72:75], v[154:157], v[246:249], v[72:75]
	s_setprio 0
	s_setprio 1
	v_mfma_f32_16x16x32_bf16 v[116:119], v[172:175], v[196:199], v[116:119]
	v_mfma_f32_16x16x32_bf16 v[108:111], v[180:183], v[196:199], v[108:111]
	v_mfma_f32_16x16x32_bf16 v[100:103], v[172:175], v[204:207], v[100:103]
	v_mfma_f32_16x16x32_bf16 v[96:99], v[180:183], v[204:207], v[96:99]
	v_mfma_f32_16x16x32_bf16 v[84:87], v[172:175], v[234:237], v[84:87]
	v_mfma_f32_16x16x32_bf16 v[76:79], v[180:183], v[234:237], v[76:79]
	v_mfma_f32_16x16x32_bf16 v[68:71], v[172:175], v[242:245], v[68:71]
	v_mfma_f32_16x16x32_bf16 v[64:67], v[180:183], v[242:245], v[64:67]
	v_mfma_f32_16x16x32_bf16 v[116:119], v[176:179], v[200:203], v[116:119]
	v_mfma_f32_16x16x32_bf16 v[108:111], v[184:187], v[200:203], v[108:111]
	v_mfma_f32_16x16x32_bf16 v[100:103], v[176:179], v[208:211], v[100:103]
	v_mfma_f32_16x16x32_bf16 v[96:99], v[184:187], v[208:211], v[96:99]
	v_mfma_f32_16x16x32_bf16 v[84:87], v[176:179], v[238:241], v[84:87]
	v_mfma_f32_16x16x32_bf16 v[76:79], v[184:187], v[238:241], v[76:79]
	v_mfma_f32_16x16x32_bf16 v[68:71], v[176:179], v[246:249], v[68:71]
	v_mfma_f32_16x16x32_bf16 v[64:67], v[184:187], v[246:249], v[64:67]
	s_setprio 0
	s_barrier
	s_add_i32 s52, s52, s37
	v_lshl_add_u64 v[158:159], s[30:31], 0, v[160:161]
	s_mov_b32 m0, s52
	ds_read_b128 v[196:199], v145 offset:16384
	ds_read_b128 v[200:203], v145 offset:17408
	ds_read_b128 v[204:207], v145 offset:18432
	ds_read_b128 v[208:211], v145 offset:19456
	ds_read_b128 v[234:237], v145 offset:20480
	ds_read_b128 v[238:241], v145 offset:21504
	ds_read_b128 v[242:245], v145 offset:22528
	ds_read_b128 v[246:249], v145 offset:23552
	global_load_lds_dwordx4 v[158:159], off
	s_add_i32 m0, s52, 0x2000
	s_add_u32 s52, s30, 0x80000
	v_lshl_add_u64 v[188:189], s[30:31], 0, v[128:129]
	s_addc_u32 s53, s31, 0
	s_add_i32 s54, s54, s37
	global_load_lds_dwordx4 v[188:189], off
	s_mov_b32 m0, s54
	v_lshl_add_u64 v[214:215], s[34:35], 0, v[130:131]
	global_load_lds_dwordx4 v160, s[52:53]
	s_add_i32 m0, s54, 0x2000
	s_nop 0
	global_load_lds_dwordx4 v128, s[52:53]
	v_lshl_add_u64 v[212:213], s[34:35], 0, v[132:133]
	s_mov_b32 m0, s38
	s_nop 0
	global_load_lds_dwordx4 v[212:213], off
	s_mov_b32 m0, s39
	s_nop 0
	global_load_lds_dwordx4 v[214:215], off
	s_waitcnt vmcnt(8)
	s_waitcnt lgkmcnt(0)
	s_barrier
	s_setprio 1
	s_waitcnt lgkmcnt(0)
	v_mfma_f32_16x16x32_bf16 v[60:63], v[138:141], v[196:199], v[60:63]
	v_mfma_f32_16x16x32_bf16 v[56:59], v[150:153], v[196:199], v[56:59]
	v_mfma_f32_16x16x32_bf16 v[48:51], v[138:141], v[204:207], v[48:51]
	v_mfma_f32_16x16x32_bf16 v[40:43], v[150:153], v[204:207], v[40:43]
	v_mfma_f32_16x16x32_bf16 v[28:31], v[138:141], v[234:237], v[28:31]
	v_mfma_f32_16x16x32_bf16 v[24:27], v[150:153], v[234:237], v[24:27]
	v_mfma_f32_16x16x32_bf16 v[16:19], v[138:141], v[242:245], v[16:19]
	v_mfma_f32_16x16x32_bf16 v[8:11], v[150:153], v[242:245], v[8:11]
	v_mfma_f32_16x16x32_bf16 v[60:63], v[146:149], v[200:203], v[60:63]
	v_mfma_f32_16x16x32_bf16 v[56:59], v[154:157], v[200:203], v[56:59]
	v_mfma_f32_16x16x32_bf16 v[48:51], v[146:149], v[208:211], v[48:51]
	v_mfma_f32_16x16x32_bf16 v[40:43], v[154:157], v[208:211], v[40:43]
	v_mfma_f32_16x16x32_bf16 v[28:31], v[146:149], v[238:241], v[28:31]
	v_mfma_f32_16x16x32_bf16 v[24:27], v[154:157], v[238:241], v[24:27]
	v_mfma_f32_16x16x32_bf16 v[16:19], v[146:149], v[246:249], v[16:19]
	v_mfma_f32_16x16x32_bf16 v[8:11], v[154:157], v[246:249], v[8:11]
	s_setprio 0
	s_setprio 1
	v_mfma_f32_16x16x32_bf16 v[52:55], v[172:175], v[196:199], v[52:55]
	v_mfma_f32_16x16x32_bf16 v[44:47], v[180:183], v[196:199], v[44:47]
	v_mfma_f32_16x16x32_bf16 v[36:39], v[172:175], v[204:207], v[36:39]
	v_mfma_f32_16x16x32_bf16 v[32:35], v[180:183], v[204:207], v[32:35]
	v_mfma_f32_16x16x32_bf16 v[20:23], v[172:175], v[234:237], v[20:23]
	v_mfma_f32_16x16x32_bf16 v[12:15], v[180:183], v[234:237], v[12:15]
	v_mfma_f32_16x16x32_bf16 v[4:7], v[172:175], v[242:245], v[4:7]
	v_mfma_f32_16x16x32_bf16 v[0:3], v[180:183], v[242:245], v[0:3]
	v_mfma_f32_16x16x32_bf16 v[52:55], v[176:179], v[200:203], v[52:55]
	v_mfma_f32_16x16x32_bf16 v[44:47], v[184:187], v[200:203], v[44:47]
	v_mfma_f32_16x16x32_bf16 v[36:39], v[176:179], v[208:211], v[36:39]
	v_mfma_f32_16x16x32_bf16 v[32:35], v[184:187], v[208:211], v[32:35]
	v_mfma_f32_16x16x32_bf16 v[20:23], v[176:179], v[238:241], v[20:23]
	v_mfma_f32_16x16x32_bf16 v[12:15], v[184:187], v[238:241], v[12:15]
	v_mfma_f32_16x16x32_bf16 v[4:7], v[176:179], v[246:249], v[4:7]
	v_mfma_f32_16x16x32_bf16 v[0:3], v[184:187], v[246:249], v[0:3]
	s_setprio 0
	s_barrier
	s_add_i32 s52, 0, 0x18000
	s_add_i32 s53, 0, 0x1c000
	v_add_u32_e32 v154, s52, v143
	v_add_u32_e32 v162, s53, v143
	ds_read_b128 v[138:141], v154
	ds_read_b128 v[146:149], v154 offset:1024
	ds_read_b128 v[150:153], v154 offset:2048
	ds_read_b128 v[154:157], v154 offset:3072
	ds_read_b128 v[172:175], v162
	ds_read_b128 v[176:179], v162 offset:1024
	ds_read_b128 v[180:183], v162 offset:2048
	ds_read_b128 v[184:187], v162 offset:3072
	s_add_u32 s34, s34, 0x80000
	s_addc_u32 s35, s35, 0
	s_mov_b32 m0, s40
	ds_read_b128 v[196:199], v145 offset:32768
	ds_read_b128 v[200:203], v145 offset:33792
	ds_read_b128 v[204:207], v145 offset:34816
	ds_read_b128 v[208:211], v145 offset:35840
	ds_read_b128 v[234:237], v145 offset:36864
	ds_read_b128 v[238:241], v145 offset:37888
	ds_read_b128 v[242:245], v145 offset:38912
	ds_read_b128 v[246:249], v145 offset:39936
	global_load_lds_dwordx4 v132, s[34:35]
	s_mov_b32 m0, s41
	s_nop 0
	global_load_lds_dwordx4 v130, s[34:35]
	s_waitcnt vmcnt(8)
	s_waitcnt lgkmcnt(0)
	s_barrier
	s_setprio 1
	s_waitcnt lgkmcnt(0)
	v_mfma_f32_16x16x32_bf16 v[124:127], v[138:141], v[196:199], v[124:127]
	v_mfma_f32_16x16x32_bf16 v[120:123], v[150:153], v[196:199], v[120:123]
	v_mfma_f32_16x16x32_bf16 v[112:115], v[138:141], v[204:207], v[112:115]
	v_mfma_f32_16x16x32_bf16 v[104:107], v[150:153], v[204:207], v[104:107]
	v_mfma_f32_16x16x32_bf16 v[92:95], v[138:141], v[234:237], v[92:95]
	v_mfma_f32_16x16x32_bf16 v[88:91], v[150:153], v[234:237], v[88:91]
	v_mfma_f32_16x16x32_bf16 v[80:83], v[138:141], v[242:245], v[80:83]
	v_mfma_f32_16x16x32_bf16 v[72:75], v[150:153], v[242:245], v[72:75]
	v_mfma_f32_16x16x32_bf16 v[124:127], v[146:149], v[200:203], v[124:127]
	v_mfma_f32_16x16x32_bf16 v[120:123], v[154:157], v[200:203], v[120:123]
	v_mfma_f32_16x16x32_bf16 v[112:115], v[146:149], v[208:211], v[112:115]
	v_mfma_f32_16x16x32_bf16 v[104:107], v[154:157], v[208:211], v[104:107]
	v_mfma_f32_16x16x32_bf16 v[92:95], v[146:149], v[238:241], v[92:95]
	v_mfma_f32_16x16x32_bf16 v[88:91], v[154:157], v[238:241], v[88:91]
	v_mfma_f32_16x16x32_bf16 v[80:83], v[146:149], v[246:249], v[80:83]
	v_mfma_f32_16x16x32_bf16 v[72:75], v[154:157], v[246:249], v[72:75]
	s_setprio 0
	s_setprio 1
	v_mfma_f32_16x16x32_bf16 v[116:119], v[172:175], v[196:199], v[116:119]
	v_mfma_f32_16x16x32_bf16 v[108:111], v[180:183], v[196:199], v[108:111]
	v_mfma_f32_16x16x32_bf16 v[100:103], v[172:175], v[204:207], v[100:103]
	v_mfma_f32_16x16x32_bf16 v[96:99], v[180:183], v[204:207], v[96:99]
	v_mfma_f32_16x16x32_bf16 v[84:87], v[172:175], v[234:237], v[84:87]
	v_mfma_f32_16x16x32_bf16 v[76:79], v[180:183], v[234:237], v[76:79]
	v_mfma_f32_16x16x32_bf16 v[68:71], v[172:175], v[242:245], v[68:71]
	v_mfma_f32_16x16x32_bf16 v[64:67], v[180:183], v[242:245], v[64:67]
	v_mfma_f32_16x16x32_bf16 v[116:119], v[176:179], v[200:203], v[116:119]
	v_mfma_f32_16x16x32_bf16 v[108:111], v[184:187], v[200:203], v[108:111]
	v_mfma_f32_16x16x32_bf16 v[100:103], v[176:179], v[208:211], v[100:103]
	v_mfma_f32_16x16x32_bf16 v[96:99], v[184:187], v[208:211], v[96:99]
	v_mfma_f32_16x16x32_bf16 v[84:87], v[176:179], v[238:241], v[84:87]
	v_mfma_f32_16x16x32_bf16 v[76:79], v[184:187], v[238:241], v[76:79]
	v_mfma_f32_16x16x32_bf16 v[68:71], v[176:179], v[246:249], v[68:71]
	v_mfma_f32_16x16x32_bf16 v[64:67], v[184:187], v[246:249], v[64:67]
	s_setprio 0
	s_barrier
	s_add_i32 s34, s52, s37
	v_lshl_add_u64 v[158:159], v[158:159], 0, s[20:21]
	s_mov_b32 m0, s34
	ds_read_b128 v[196:199], v145 offset:49152
	ds_read_b128 v[200:203], v145 offset:50176
	ds_read_b128 v[204:207], v145 offset:51200
	ds_read_b128 v[208:211], v145 offset:52224
	ds_read_b128 v[234:237], v145 offset:53248
	ds_read_b128 v[238:241], v145 offset:54272
	ds_read_b128 v[242:245], v145 offset:55296
	ds_read_b128 v[246:249], v145 offset:56320
	global_load_lds_dwordx4 v[158:159], off
	s_add_i32 m0, s34, 0x2000
	s_add_u32 s30, s30, 0x80080
	v_lshl_add_u64 v[158:159], v[188:189], 0, s[20:21]
	s_addc_u32 s31, s31, 0
	s_add_i32 s34, s53, s37
	global_load_lds_dwordx4 v[158:159], off
	s_mov_b32 m0, s34
	s_nop 0
	global_load_lds_dwordx4 v160, s[30:31]
	s_add_i32 m0, s34, 0x2000
	s_nop 0
	global_load_lds_dwordx4 v128, s[30:31]
	v_lshl_add_u64 v[158:159], v[212:213], 0, s[20:21]
	s_mov_b32 m0, s42
	s_nop 0
	global_load_lds_dwordx4 v[158:159], off
	v_lshl_add_u64 v[158:159], v[214:215], 0, s[20:21]
	s_mov_b32 m0, s43
	s_nop 0
	global_load_lds_dwordx4 v[158:159], off
	s_waitcnt vmcnt(8)
	s_waitcnt lgkmcnt(0)
	s_barrier
	s_setprio 1
	s_waitcnt lgkmcnt(0)
	v_mfma_f32_16x16x32_bf16 v[60:63], v[138:141], v[196:199], v[60:63]
	v_mfma_f32_16x16x32_bf16 v[56:59], v[150:153], v[196:199], v[56:59]
	v_mfma_f32_16x16x32_bf16 v[48:51], v[138:141], v[204:207], v[48:51]
	v_mfma_f32_16x16x32_bf16 v[40:43], v[150:153], v[204:207], v[40:43]
	v_mfma_f32_16x16x32_bf16 v[28:31], v[138:141], v[234:237], v[28:31]
	v_mfma_f32_16x16x32_bf16 v[24:27], v[150:153], v[234:237], v[24:27]
	v_mfma_f32_16x16x32_bf16 v[16:19], v[138:141], v[242:245], v[16:19]
	v_mfma_f32_16x16x32_bf16 v[8:11], v[150:153], v[242:245], v[8:11]
	v_mfma_f32_16x16x32_bf16 v[60:63], v[146:149], v[200:203], v[60:63]
	v_mfma_f32_16x16x32_bf16 v[56:59], v[154:157], v[200:203], v[56:59]
	v_mfma_f32_16x16x32_bf16 v[48:51], v[146:149], v[208:211], v[48:51]
	v_mfma_f32_16x16x32_bf16 v[40:43], v[154:157], v[208:211], v[40:43]
	v_mfma_f32_16x16x32_bf16 v[28:31], v[146:149], v[238:241], v[28:31]
	v_mfma_f32_16x16x32_bf16 v[24:27], v[154:157], v[238:241], v[24:27]
	v_mfma_f32_16x16x32_bf16 v[16:19], v[146:149], v[246:249], v[16:19]
	v_mfma_f32_16x16x32_bf16 v[8:11], v[154:157], v[246:249], v[8:11]
	s_setprio 0
	s_setprio 1
	v_mfma_f32_16x16x32_bf16 v[52:55], v[172:175], v[196:199], v[52:55]
	v_mfma_f32_16x16x32_bf16 v[44:47], v[180:183], v[196:199], v[44:47]
	v_mfma_f32_16x16x32_bf16 v[36:39], v[172:175], v[204:207], v[36:39]
	v_mfma_f32_16x16x32_bf16 v[32:35], v[180:183], v[204:207], v[32:35]
	v_mfma_f32_16x16x32_bf16 v[20:23], v[172:175], v[234:237], v[20:23]
	v_mfma_f32_16x16x32_bf16 v[12:15], v[180:183], v[234:237], v[12:15]
	v_mfma_f32_16x16x32_bf16 v[4:7], v[172:175], v[242:245], v[4:7]
	v_mfma_f32_16x16x32_bf16 v[0:3], v[180:183], v[242:245], v[0:3]
	v_mfma_f32_16x16x32_bf16 v[52:55], v[176:179], v[200:203], v[52:55]
	v_mfma_f32_16x16x32_bf16 v[44:47], v[184:187], v[200:203], v[44:47]
	v_mfma_f32_16x16x32_bf16 v[36:39], v[176:179], v[208:211], v[36:39]
	v_mfma_f32_16x16x32_bf16 v[32:35], v[184:187], v[208:211], v[32:35]
	v_mfma_f32_16x16x32_bf16 v[20:23], v[176:179], v[238:241], v[20:23]
	v_mfma_f32_16x16x32_bf16 v[12:15], v[184:187], v[238:241], v[12:15]
	v_mfma_f32_16x16x32_bf16 v[4:7], v[176:179], v[246:249], v[4:7]
	v_mfma_f32_16x16x32_bf16 v[0:3], v[184:187], v[246:249], v[0:3]
	s_setprio 0
	s_barrier
	s_add_i32 s51, s51, 2
	s_add_u32 s28, s28, 0x100
	s_addc_u32 s29, s29, 0
	s_add_u32 s49, s49, 0x100
	s_addc_u32 s50, s50, 0
	s_cmp_gt_u32 s51, 29
	s_cbranch_scc0 .LBB0_352
	s_and_b64 vcc, exec, s[10:11]
	s_cbranch_vccz .LBB0_355
	s_barrier

.LBB0_526:
	s_add_u32 s28, s18, 0xfff00080
	s_addc_u32 s29, s19, -1
	s_add_i32 s54, 0, 0x10000
	s_cmp_eq_u32 s53, 4
	s_cselect_b32 s31, s13, s29
	s_cselect_b32 s30, s49, s28
	s_cselect_b32 s29, s11, s52
	s_cselect_b32 s28, s50, s51
	s_add_i32 s56, 0, 0x14000
	v_add_u32_e32 v154, s54, v143
	v_add_u32_e32 v158, s56, v143
	ds_read_b128 v[138:141], v154
	ds_read_b128 v[146:149], v154 offset:1024
	ds_read_b128 v[150:153], v154 offset:2048
	ds_read_b128 v[154:157], v154 offset:3072
	ds_read_b128 v[172:175], v158
	ds_read_b128 v[176:179], v158 offset:1024
	ds_read_b128 v[180:183], v158 offset:2048
	ds_read_b128 v[184:187], v158 offset:3072
	s_add_i32 m0, s40, 0xc000
	ds_read_b128 v[196:199], v145
	ds_read_b128 v[200:203], v145 offset:1024
	ds_read_b128 v[204:207], v145 offset:2048
	ds_read_b128 v[208:211], v145 offset:3072
	ds_read_b128 v[234:237], v145 offset:4096
	ds_read_b128 v[238:241], v145 offset:5120
	ds_read_b128 v[242:245], v145 offset:6144
	ds_read_b128 v[246:249], v145 offset:7168
	global_load_lds_dwordx4 v134, s[18:19]
	s_add_i32 m0, s40, 0xe000
	s_nop 0
	global_load_lds_dwordx4 v136, s[18:19]
	s_waitcnt vmcnt(8)
	s_waitcnt lgkmcnt(0)
	s_barrier
	s_setprio 1
	s_waitcnt lgkmcnt(0)
	v_mfma_f32_16x16x32_bf16 v[124:127], v[138:141], v[196:199], v[124:127]
	v_mfma_f32_16x16x32_bf16 v[120:123], v[150:153], v[196:199], v[120:123]
	v_mfma_f32_16x16x32_bf16 v[116:119], v[138:141], v[204:207], v[116:119]
	v_mfma_f32_16x16x32_bf16 v[108:111], v[150:153], v[204:207], v[108:111]
	v_mfma_f32_16x16x32_bf16 v[100:103], v[138:141], v[234:237], v[100:103]
	v_mfma_f32_16x16x32_bf16 v[92:95], v[150:153], v[234:237], v[92:95]
	v_mfma_f32_16x16x32_bf16 v[84:87], v[138:141], v[242:245], v[84:87]
	v_mfma_f32_16x16x32_bf16 v[76:79], v[150:153], v[242:245], v[76:79]
	v_mfma_f32_16x16x32_bf16 v[124:127], v[146:149], v[200:203], v[124:127]
	v_mfma_f32_16x16x32_bf16 v[120:123], v[154:157], v[200:203], v[120:123]
	v_mfma_f32_16x16x32_bf16 v[116:119], v[146:149], v[208:211], v[116:119]
	v_mfma_f32_16x16x32_bf16 v[108:111], v[154:157], v[208:211], v[108:111]
	v_mfma_f32_16x16x32_bf16 v[100:103], v[146:149], v[238:241], v[100:103]
	v_mfma_f32_16x16x32_bf16 v[92:95], v[154:157], v[238:241], v[92:95]
	v_mfma_f32_16x16x32_bf16 v[84:87], v[146:149], v[246:249], v[84:87]
	v_mfma_f32_16x16x32_bf16 v[76:79], v[154:157], v[246:249], v[76:79]
	s_setprio 0
	s_setprio 1
	v_mfma_f32_16x16x32_bf16 v[112:115], v[172:175], v[196:199], v[112:115]
	v_mfma_f32_16x16x32_bf16 v[104:107], v[180:183], v[196:199], v[104:107]
	v_mfma_f32_16x16x32_bf16 v[96:99], v[172:175], v[204:207], v[96:99]
	v_mfma_f32_16x16x32_bf16 v[88:91], v[180:183], v[204:207], v[88:91]
	v_mfma_f32_16x16x32_bf16 v[80:83], v[172:175], v[234:237], v[80:83]
	v_mfma_f32_16x16x32_bf16 v[72:75], v[180:183], v[234:237], v[72:75]
	v_mfma_f32_16x16x32_bf16 v[68:71], v[172:175], v[242:245], v[68:71]
	v_mfma_f32_16x16x32_bf16 v[64:67], v[180:183], v[242:245], v[64:67]
	v_mfma_f32_16x16x32_bf16 v[112:115], v[176:179], v[200:203], v[112:115]
	v_mfma_f32_16x16x32_bf16 v[104:107], v[184:187], v[200:203], v[104:107]
	v_mfma_f32_16x16x32_bf16 v[96:99], v[176:179], v[208:211], v[96:99]
	v_mfma_f32_16x16x32_bf16 v[88:91], v[184:187], v[208:211], v[88:91]
	v_mfma_f32_16x16x32_bf16 v[80:83], v[176:179], v[238:241], v[80:83]
	v_mfma_f32_16x16x32_bf16 v[72:75], v[184:187], v[238:241], v[72:75]
	v_mfma_f32_16x16x32_bf16 v[68:71], v[176:179], v[246:249], v[68:71]
	v_mfma_f32_16x16x32_bf16 v[64:67], v[184:187], v[246:249], v[64:67]
	s_setprio 0
	s_barrier
	s_add_i32 s54, s54, s37
	v_lshl_add_u64 v[158:159], s[28:29], 0, v[160:161]
	s_mov_b32 m0, s54
	ds_read_b128 v[196:199], v145 offset:16384
	ds_read_b128 v[200:203], v145 offset:17408
	ds_read_b128 v[204:207], v145 offset:18432
	ds_read_b128 v[208:211], v145 offset:19456
	ds_read_b128 v[234:237], v145 offset:20480
	ds_read_b128 v[238:241], v145 offset:21504
	ds_read_b128 v[242:245], v145 offset:22528
	ds_read_b128 v[246:249], v145 offset:23552
	global_load_lds_dwordx4 v[158:159], off
	s_add_i32 m0, s54, 0x2000
	s_add_u32 s54, s28, 0x20000
	v_lshl_add_u64 v[188:189], s[28:29], 0, v[128:129]
	s_addc_u32 s55, s29, 0
	s_add_i32 s56, s56, s37
	global_load_lds_dwordx4 v[188:189], off
	s_mov_b32 m0, s56
	v_lshl_add_u64 v[214:215], s[30:31], 0, v[130:131]
	global_load_lds_dwordx4 v160, s[54:55]
	s_add_i32 m0, s56, 0x2000
	s_nop 0
	global_load_lds_dwordx4 v128, s[54:55]
	v_lshl_add_u64 v[212:213], s[30:31], 0, v[132:133]
	s_mov_b32 m0, s40
	s_nop 0
	global_load_lds_dwordx4 v[212:213], off
	s_mov_b32 m0, s41
	s_nop 0
	global_load_lds_dwordx4 v[214:215], off
	s_waitcnt vmcnt(8)
	s_waitcnt lgkmcnt(0)
	s_barrier
	s_setprio 1
	s_waitcnt lgkmcnt(0)
	v_mfma_f32_16x16x32_bf16 v[60:63], v[138:141], v[196:199], v[60:63]
	v_mfma_f32_16x16x32_bf16 v[56:59], v[150:153], v[196:199], v[56:59]
	v_mfma_f32_16x16x32_bf16 v[52:55], v[138:141], v[204:207], v[52:55]
	v_mfma_f32_16x16x32_bf16 v[44:47], v[150:153], v[204:207], v[44:47]
	v_mfma_f32_16x16x32_bf16 v[36:39], v[138:141], v[234:237], v[36:39]
	v_mfma_f32_16x16x32_bf16 v[28:31], v[150:153], v[234:237], v[28:31]
	v_mfma_f32_16x16x32_bf16 v[20:23], v[138:141], v[242:245], v[20:23]
	v_mfma_f32_16x16x32_bf16 v[12:15], v[150:153], v[242:245], v[12:15]
	v_mfma_f32_16x16x32_bf16 v[60:63], v[146:149], v[200:203], v[60:63]
	v_mfma_f32_16x16x32_bf16 v[56:59], v[154:157], v[200:203], v[56:59]
	v_mfma_f32_16x16x32_bf16 v[52:55], v[146:149], v[208:211], v[52:55]
	v_mfma_f32_16x16x32_bf16 v[44:47], v[154:157], v[208:211], v[44:47]
	v_mfma_f32_16x16x32_bf16 v[36:39], v[146:149], v[238:241], v[36:39]
	v_mfma_f32_16x16x32_bf16 v[28:31], v[154:157], v[238:241], v[28:31]
	v_mfma_f32_16x16x32_bf16 v[20:23], v[146:149], v[246:249], v[20:23]
	v_mfma_f32_16x16x32_bf16 v[12:15], v[154:157], v[246:249], v[12:15]
	s_setprio 0
	s_setprio 1
	v_mfma_f32_16x16x32_bf16 v[48:51], v[172:175], v[196:199], v[48:51]
	v_mfma_f32_16x16x32_bf16 v[40:43], v[180:183], v[196:199], v[40:43]
	v_mfma_f32_16x16x32_bf16 v[32:35], v[172:175], v[204:207], v[32:35]
	v_mfma_f32_16x16x32_bf16 v[24:27], v[180:183], v[204:207], v[24:27]
	v_mfma_f32_16x16x32_bf16 v[16:19], v[172:175], v[234:237], v[16:19]
	v_mfma_f32_16x16x32_bf16 v[8:11], v[180:183], v[234:237], v[8:11]
	v_mfma_f32_16x16x32_bf16 v[4:7], v[172:175], v[242:245], v[4:7]
	v_mfma_f32_16x16x32_bf16 v[0:3], v[180:183], v[242:245], v[0:3]
	v_mfma_f32_16x16x32_bf16 v[48:51], v[176:179], v[200:203], v[48:51]
	v_mfma_f32_16x16x32_bf16 v[40:43], v[184:187], v[200:203], v[40:43]
	v_mfma_f32_16x16x32_bf16 v[32:35], v[176:179], v[208:211], v[32:35]
	v_mfma_f32_16x16x32_bf16 v[24:27], v[184:187], v[208:211], v[24:27]
	v_mfma_f32_16x16x32_bf16 v[16:19], v[176:179], v[238:241], v[16:19]
	v_mfma_f32_16x16x32_bf16 v[8:11], v[184:187], v[238:241], v[8:11]
	v_mfma_f32_16x16x32_bf16 v[4:7], v[176:179], v[246:249], v[4:7]
	v_mfma_f32_16x16x32_bf16 v[0:3], v[184:187], v[246:249], v[0:3]
	s_setprio 0
	s_barrier
	s_add_i32 s54, 0, 0x18000
	s_add_i32 s55, 0, 0x1c000
	v_add_u32_e32 v154, s54, v143
	v_add_u32_e32 v162, s55, v143
	ds_read_b128 v[138:141], v154
	ds_read_b128 v[146:149], v154 offset:1024
	ds_read_b128 v[150:153], v154 offset:2048
	ds_read_b128 v[154:157], v154 offset:3072
	ds_read_b128 v[172:175], v162
	ds_read_b128 v[176:179], v162 offset:1024
	ds_read_b128 v[180:183], v162 offset:2048
	ds_read_b128 v[184:187], v162 offset:3072
	s_add_u32 s30, s30, 0x100000
	s_addc_u32 s31, s31, 0
	s_mov_b32 m0, s42
	ds_read_b128 v[196:199], v145 offset:32768
	ds_read_b128 v[200:203], v145 offset:33792
	ds_read_b128 v[204:207], v145 offset:34816
	ds_read_b128 v[208:211], v145 offset:35840
	ds_read_b128 v[234:237], v145 offset:36864
	ds_read_b128 v[238:241], v145 offset:37888
	ds_read_b128 v[242:245], v145 offset:38912
	ds_read_b128 v[246:249], v145 offset:39936
	global_load_lds_dwordx4 v132, s[30:31]
	s_mov_b32 m0, s43
	s_nop 0
	global_load_lds_dwordx4 v130, s[30:31]
	s_waitcnt vmcnt(8)
	s_waitcnt lgkmcnt(0)
	s_barrier
	s_setprio 1
	s_waitcnt lgkmcnt(0)
	v_mfma_f32_16x16x32_bf16 v[124:127], v[138:141], v[196:199], v[124:127]
	v_mfma_f32_16x16x32_bf16 v[120:123], v[150:153], v[196:199], v[120:123]
	v_mfma_f32_16x16x32_bf16 v[116:119], v[138:141], v[204:207], v[116:119]
	v_mfma_f32_16x16x32_bf16 v[108:111], v[150:153], v[204:207], v[108:111]
	v_mfma_f32_16x16x32_bf16 v[100:103], v[138:141], v[234:237], v[100:103]
	v_mfma_f32_16x16x32_bf16 v[92:95], v[150:153], v[234:237], v[92:95]
	v_mfma_f32_16x16x32_bf16 v[84:87], v[138:141], v[242:245], v[84:87]
	v_mfma_f32_16x16x32_bf16 v[76:79], v[150:153], v[242:245], v[76:79]
	v_mfma_f32_16x16x32_bf16 v[124:127], v[146:149], v[200:203], v[124:127]
	v_mfma_f32_16x16x32_bf16 v[120:123], v[154:157], v[200:203], v[120:123]
	v_mfma_f32_16x16x32_bf16 v[116:119], v[146:149], v[208:211], v[116:119]
	v_mfma_f32_16x16x32_bf16 v[108:111], v[154:157], v[208:211], v[108:111]
	v_mfma_f32_16x16x32_bf16 v[100:103], v[146:149], v[238:241], v[100:103]
	v_mfma_f32_16x16x32_bf16 v[92:95], v[154:157], v[238:241], v[92:95]
	v_mfma_f32_16x16x32_bf16 v[84:87], v[146:149], v[246:249], v[84:87]
	v_mfma_f32_16x16x32_bf16 v[76:79], v[154:157], v[246:249], v[76:79]
	s_setprio 0
	s_setprio 1
	v_mfma_f32_16x16x32_bf16 v[112:115], v[172:175], v[196:199], v[112:115]
	v_mfma_f32_16x16x32_bf16 v[104:107], v[180:183], v[196:199], v[104:107]
	v_mfma_f32_16x16x32_bf16 v[96:99], v[172:175], v[204:207], v[96:99]
	v_mfma_f32_16x16x32_bf16 v[88:91], v[180:183], v[204:207], v[88:91]
	v_mfma_f32_16x16x32_bf16 v[80:83], v[172:175], v[234:237], v[80:83]
	v_mfma_f32_16x16x32_bf16 v[72:75], v[180:183], v[234:237], v[72:75]
	v_mfma_f32_16x16x32_bf16 v[68:71], v[172:175], v[242:245], v[68:71]
	v_mfma_f32_16x16x32_bf16 v[64:67], v[180:183], v[242:245], v[64:67]
	v_mfma_f32_16x16x32_bf16 v[112:115], v[176:179], v[200:203], v[112:115]
	v_mfma_f32_16x16x32_bf16 v[104:107], v[184:187], v[200:203], v[104:107]
	v_mfma_f32_16x16x32_bf16 v[96:99], v[176:179], v[208:211], v[96:99]
	v_mfma_f32_16x16x32_bf16 v[88:91], v[184:187], v[208:211], v[88:91]
	v_mfma_f32_16x16x32_bf16 v[80:83], v[176:179], v[238:241], v[80:83]
	v_mfma_f32_16x16x32_bf16 v[72:75], v[184:187], v[238:241], v[72:75]
	v_mfma_f32_16x16x32_bf16 v[68:71], v[176:179], v[246:249], v[68:71]
	v_mfma_f32_16x16x32_bf16 v[64:67], v[184:187], v[246:249], v[64:67]
	s_setprio 0
	s_barrier
	s_add_i32 s30, s54, s37
	v_lshl_add_u64 v[158:159], v[158:159], 0, s[20:21]
	s_mov_b32 m0, s30
	ds_read_b128 v[196:199], v145 offset:49152
	ds_read_b128 v[200:203], v145 offset:50176
	ds_read_b128 v[204:207], v145 offset:51200
	ds_read_b128 v[208:211], v145 offset:52224
	ds_read_b128 v[234:237], v145 offset:53248
	ds_read_b128 v[238:241], v145 offset:54272
	ds_read_b128 v[242:245], v145 offset:55296
	ds_read_b128 v[246:249], v145 offset:56320
	global_load_lds_dwordx4 v[158:159], off
	s_add_i32 m0, s30, 0x2000
	s_add_u32 s28, s28, 0x20080
	v_lshl_add_u64 v[158:159], v[188:189], 0, s[20:21]
	s_addc_u32 s29, s29, 0
	s_add_i32 s30, s55, s37
	global_load_lds_dwordx4 v[158:159], off
	s_mov_b32 m0, s30
	s_nop 0
	global_load_lds_dwordx4 v160, s[28:29]
	s_add_i32 m0, s30, 0x2000
	s_nop 0
	global_load_lds_dwordx4 v128, s[28:29]
	v_lshl_add_u64 v[158:159], v[212:213], 0, s[20:21]
	s_mov_b32 m0, s44
	s_nop 0
	global_load_lds_dwordx4 v[158:159], off
	v_lshl_add_u64 v[158:159], v[214:215], 0, s[20:21]
	s_mov_b32 m0, s45
	s_nop 0
	global_load_lds_dwordx4 v[158:159], off
	s_waitcnt vmcnt(8)
	s_waitcnt lgkmcnt(0)
	s_barrier
	s_setprio 1
	s_waitcnt lgkmcnt(0)
	v_mfma_f32_16x16x32_bf16 v[60:63], v[138:141], v[196:199], v[60:63]
	v_mfma_f32_16x16x32_bf16 v[56:59], v[150:153], v[196:199], v[56:59]
	v_mfma_f32_16x16x32_bf16 v[52:55], v[138:141], v[204:207], v[52:55]
	v_mfma_f32_16x16x32_bf16 v[44:47], v[150:153], v[204:207], v[44:47]
	v_mfma_f32_16x16x32_bf16 v[36:39], v[138:141], v[234:237], v[36:39]
	v_mfma_f32_16x16x32_bf16 v[28:31], v[150:153], v[234:237], v[28:31]
	v_mfma_f32_16x16x32_bf16 v[20:23], v[138:141], v[242:245], v[20:23]
	v_mfma_f32_16x16x32_bf16 v[12:15], v[150:153], v[242:245], v[12:15]
	v_mfma_f32_16x16x32_bf16 v[60:63], v[146:149], v[200:203], v[60:63]
	v_mfma_f32_16x16x32_bf16 v[56:59], v[154:157], v[200:203], v[56:59]
	v_mfma_f32_16x16x32_bf16 v[52:55], v[146:149], v[208:211], v[52:55]
	v_mfma_f32_16x16x32_bf16 v[44:47], v[154:157], v[208:211], v[44:47]
	v_mfma_f32_16x16x32_bf16 v[36:39], v[146:149], v[238:241], v[36:39]
	v_mfma_f32_16x16x32_bf16 v[28:31], v[154:157], v[238:241], v[28:31]
	v_mfma_f32_16x16x32_bf16 v[20:23], v[146:149], v[246:249], v[20:23]
	v_mfma_f32_16x16x32_bf16 v[12:15], v[154:157], v[246:249], v[12:15]
	s_setprio 0
	s_setprio 1
	v_mfma_f32_16x16x32_bf16 v[48:51], v[172:175], v[196:199], v[48:51]
	v_mfma_f32_16x16x32_bf16 v[40:43], v[180:183], v[196:199], v[40:43]
	v_mfma_f32_16x16x32_bf16 v[32:35], v[172:175], v[204:207], v[32:35]
	v_mfma_f32_16x16x32_bf16 v[24:27], v[180:183], v[204:207], v[24:27]
	v_mfma_f32_16x16x32_bf16 v[16:19], v[172:175], v[234:237], v[16:19]
	v_mfma_f32_16x16x32_bf16 v[8:11], v[180:183], v[234:237], v[8:11]
	v_mfma_f32_16x16x32_bf16 v[4:7], v[172:175], v[242:245], v[4:7]
	v_mfma_f32_16x16x32_bf16 v[0:3], v[180:183], v[242:245], v[0:3]
	v_mfma_f32_16x16x32_bf16 v[48:51], v[176:179], v[200:203], v[48:51]
	v_mfma_f32_16x16x32_bf16 v[40:43], v[184:187], v[200:203], v[40:43]
	v_mfma_f32_16x16x32_bf16 v[32:35], v[176:179], v[208:211], v[32:35]
	v_mfma_f32_16x16x32_bf16 v[24:27], v[184:187], v[208:211], v[24:27]
	v_mfma_f32_16x16x32_bf16 v[16:19], v[176:179], v[238:241], v[16:19]
	v_mfma_f32_16x16x32_bf16 v[8:11], v[184:187], v[238:241], v[8:11]
	v_mfma_f32_16x16x32_bf16 v[4:7], v[176:179], v[246:249], v[4:7]
	v_mfma_f32_16x16x32_bf16 v[0:3], v[184:187], v[246:249], v[0:3]
	s_setprio 0
	s_barrier
	s_add_i32 s53, s53, 2
	s_add_u32 s18, s18, 0x100
	s_addc_u32 s19, s19, 0
	s_add_u32 s51, s51, 0x100
	s_addc_u32 s52, s52, 0
	s_cmp_gt_u32 s53, 5
	s_cbranch_scc0 .LBB0_526
	s_and_b64 vcc, exec, s[8:9]
	s_cbranch_vccz .LBB0_529
	s_barrier

.LBB0_542:
	s_add_u32 s28, s26, 0xfff00080
	s_addc_u32 s29, s27, -1
	s_add_i32 s54, 0, 0x10000
	s_cmp_eq_u32 s53, 4
	s_cselect_b32 s31, s15, s29
	s_cselect_b32 s30, s49, s28
	v_add_u32_e32 v140, s54, v143
	s_cselect_b32 s29, s13, s52
	s_cselect_b32 s28, s50, s51
	s_add_i32 s56, 0, 0x14000
	ds_read_b128 v[146:149], v140
	ds_read_b128 v[150:153], v140 offset:1024
	ds_read_b128 v[154:157], v140 offset:2048
	ds_read_b128 v[172:175], v140 offset:3072
	v_add_u32_e32 v140, s56, v143
	ds_read_b128 v[176:179], v140
	ds_read_b128 v[180:183], v140 offset:1024
	ds_read_b128 v[184:187], v140 offset:2048
	ds_read_b128 v[196:199], v140 offset:3072
	s_add_i32 m0, s40, 0xc000
	ds_read_b128 v[200:203], v144
	ds_read_b128 v[204:207], v144 offset:1024
	ds_read_b128 v[208:211], v144 offset:2048
	ds_read_b128 v[234:237], v144 offset:3072
	ds_read_b128 v[238:241], v144 offset:4096
	ds_read_b128 v[242:245], v144 offset:5120
	ds_read_b128 v[246:249], v144 offset:6144
	ds_read_b128 v[212:215], v144 offset:7168
	global_load_lds_dwordx4 v136, s[26:27]
	s_add_i32 m0, s40, 0xe000
	s_nop 0
	global_load_lds_dwordx4 v138, s[26:27]
	s_waitcnt vmcnt(8)
	s_waitcnt lgkmcnt(0)
	s_barrier
	s_setprio 1
	s_waitcnt lgkmcnt(0)
	v_mfma_f32_16x16x32_bf16 v[124:127], v[146:149], v[200:203], v[124:127]
	v_mfma_f32_16x16x32_bf16 v[120:123], v[154:157], v[200:203], v[120:123]
	v_mfma_f32_16x16x32_bf16 v[116:119], v[146:149], v[208:211], v[116:119]
	v_mfma_f32_16x16x32_bf16 v[108:111], v[154:157], v[208:211], v[108:111]
	v_mfma_f32_16x16x32_bf16 v[100:103], v[146:149], v[238:241], v[100:103]
	v_mfma_f32_16x16x32_bf16 v[92:95], v[154:157], v[238:241], v[92:95]
	v_mfma_f32_16x16x32_bf16 v[84:87], v[146:149], v[246:249], v[84:87]
	v_mfma_f32_16x16x32_bf16 v[76:79], v[154:157], v[246:249], v[76:79]
	v_mfma_f32_16x16x32_bf16 v[124:127], v[150:153], v[204:207], v[124:127]
	v_mfma_f32_16x16x32_bf16 v[120:123], v[172:175], v[204:207], v[120:123]
	v_mfma_f32_16x16x32_bf16 v[116:119], v[150:153], v[234:237], v[116:119]
	v_mfma_f32_16x16x32_bf16 v[108:111], v[172:175], v[234:237], v[108:111]
	v_mfma_f32_16x16x32_bf16 v[100:103], v[150:153], v[242:245], v[100:103]
	v_mfma_f32_16x16x32_bf16 v[92:95], v[172:175], v[242:245], v[92:95]
	v_mfma_f32_16x16x32_bf16 v[84:87], v[150:153], v[212:215], v[84:87]
	v_mfma_f32_16x16x32_bf16 v[76:79], v[172:175], v[212:215], v[76:79]
	s_setprio 0
	s_setprio 1
	v_mfma_f32_16x16x32_bf16 v[112:115], v[176:179], v[200:203], v[112:115]
	v_mfma_f32_16x16x32_bf16 v[104:107], v[184:187], v[200:203], v[104:107]
	v_mfma_f32_16x16x32_bf16 v[96:99], v[176:179], v[208:211], v[96:99]
	v_mfma_f32_16x16x32_bf16 v[88:91], v[184:187], v[208:211], v[88:91]
	v_mfma_f32_16x16x32_bf16 v[80:83], v[176:179], v[238:241], v[80:83]
	v_mfma_f32_16x16x32_bf16 v[72:75], v[184:187], v[238:241], v[72:75]
	v_mfma_f32_16x16x32_bf16 v[68:71], v[176:179], v[246:249], v[68:71]
	v_mfma_f32_16x16x32_bf16 v[64:67], v[184:187], v[246:249], v[64:67]
	v_mfma_f32_16x16x32_bf16 v[112:115], v[180:183], v[204:207], v[112:115]
	v_mfma_f32_16x16x32_bf16 v[104:107], v[196:199], v[204:207], v[104:107]
	v_mfma_f32_16x16x32_bf16 v[96:99], v[180:183], v[234:237], v[96:99]
	v_mfma_f32_16x16x32_bf16 v[88:91], v[196:199], v[234:237], v[88:91]
	v_mfma_f32_16x16x32_bf16 v[80:83], v[180:183], v[242:245], v[80:83]
	v_mfma_f32_16x16x32_bf16 v[72:75], v[196:199], v[242:245], v[72:75]
	v_mfma_f32_16x16x32_bf16 v[68:71], v[180:183], v[212:215], v[68:71]
	v_mfma_f32_16x16x32_bf16 v[64:67], v[196:199], v[212:215], v[64:67]
	s_setprio 0
	s_barrier
	s_add_i32 s54, s54, s37
	v_lshl_add_u64 v[140:141], s[28:29], 0, v[132:133]
	s_mov_b32 m0, s54
	ds_read_b128 v[200:203], v144 offset:16384
	ds_read_b128 v[204:207], v144 offset:17408
	ds_read_b128 v[208:211], v144 offset:18432
	ds_read_b128 v[212:215], v144 offset:19456
	ds_read_b128 v[234:237], v144 offset:20480
	ds_read_b128 v[238:241], v144 offset:21504
	ds_read_b128 v[242:245], v144 offset:22528
	ds_read_b128 v[246:249], v144 offset:23552
	global_load_lds_dwordx4 v[140:141], off
	s_add_i32 m0, s54, 0x2000
	s_add_u32 s54, s28, 0x20000
	v_lshl_add_u64 v[158:159], s[28:29], 0, v[128:129]
	s_addc_u32 s55, s29, 0
	s_add_i32 s56, s56, s37
	global_load_lds_dwordx4 v[158:159], off
	s_mov_b32 m0, s56
	v_lshl_add_u64 v[250:251], s[30:31], 0, v[130:131]
	global_load_lds_dwordx4 v132, s[54:55]
	s_add_i32 m0, s56, 0x2000
	s_nop 0
	global_load_lds_dwordx4 v128, s[54:55]
	v_lshl_add_u64 v[188:189], s[30:31], 0, v[134:135]
	s_mov_b32 m0, s40
	s_nop 0
	global_load_lds_dwordx4 v[188:189], off
	s_mov_b32 m0, s41
	s_nop 0
	global_load_lds_dwordx4 v[250:251], off
	s_waitcnt vmcnt(8)
	s_waitcnt lgkmcnt(0)
	s_barrier
	s_setprio 1
	s_waitcnt lgkmcnt(0)
	v_mfma_f32_16x16x32_bf16 v[60:63], v[146:149], v[200:203], v[60:63]
	v_mfma_f32_16x16x32_bf16 v[56:59], v[154:157], v[200:203], v[56:59]
	v_mfma_f32_16x16x32_bf16 v[52:55], v[146:149], v[208:211], v[52:55]
	v_mfma_f32_16x16x32_bf16 v[44:47], v[154:157], v[208:211], v[44:47]
	v_mfma_f32_16x16x32_bf16 v[36:39], v[146:149], v[234:237], v[36:39]
	v_mfma_f32_16x16x32_bf16 v[28:31], v[154:157], v[234:237], v[28:31]
	v_mfma_f32_16x16x32_bf16 v[20:23], v[146:149], v[242:245], v[20:23]
	v_mfma_f32_16x16x32_bf16 v[12:15], v[154:157], v[242:245], v[12:15]
	v_mfma_f32_16x16x32_bf16 v[60:63], v[150:153], v[204:207], v[60:63]
	v_mfma_f32_16x16x32_bf16 v[56:59], v[172:175], v[204:207], v[56:59]
	v_mfma_f32_16x16x32_bf16 v[52:55], v[150:153], v[212:215], v[52:55]
	v_mfma_f32_16x16x32_bf16 v[44:47], v[172:175], v[212:215], v[44:47]
	v_mfma_f32_16x16x32_bf16 v[36:39], v[150:153], v[238:241], v[36:39]
	v_mfma_f32_16x16x32_bf16 v[28:31], v[172:175], v[238:241], v[28:31]
	v_mfma_f32_16x16x32_bf16 v[20:23], v[150:153], v[246:249], v[20:23]
	v_mfma_f32_16x16x32_bf16 v[12:15], v[172:175], v[246:249], v[12:15]
	s_setprio 0
	s_setprio 1
	v_mfma_f32_16x16x32_bf16 v[48:51], v[176:179], v[200:203], v[48:51]
	v_mfma_f32_16x16x32_bf16 v[40:43], v[184:187], v[200:203], v[40:43]
	v_mfma_f32_16x16x32_bf16 v[32:35], v[176:179], v[208:211], v[32:35]
	v_mfma_f32_16x16x32_bf16 v[24:27], v[184:187], v[208:211], v[24:27]
	v_mfma_f32_16x16x32_bf16 v[16:19], v[176:179], v[234:237], v[16:19]
	v_mfma_f32_16x16x32_bf16 v[8:11], v[184:187], v[234:237], v[8:11]
	v_mfma_f32_16x16x32_bf16 v[4:7], v[176:179], v[242:245], v[4:7]
	v_mfma_f32_16x16x32_bf16 v[0:3], v[184:187], v[242:245], v[0:3]
	v_mfma_f32_16x16x32_bf16 v[48:51], v[180:183], v[204:207], v[48:51]
	v_mfma_f32_16x16x32_bf16 v[40:43], v[196:199], v[204:207], v[40:43]
	v_mfma_f32_16x16x32_bf16 v[32:35], v[180:183], v[212:215], v[32:35]
	v_mfma_f32_16x16x32_bf16 v[24:27], v[196:199], v[212:215], v[24:27]
	v_mfma_f32_16x16x32_bf16 v[16:19], v[180:183], v[238:241], v[16:19]
	v_mfma_f32_16x16x32_bf16 v[8:11], v[196:199], v[238:241], v[8:11]
	v_mfma_f32_16x16x32_bf16 v[4:7], v[180:183], v[246:249], v[4:7]
	v_mfma_f32_16x16x32_bf16 v[0:3], v[196:199], v[246:249], v[0:3]
	s_setprio 0
	s_barrier
	s_add_i32 s54, 0, 0x18000
	v_add_u32_e32 v145, s54, v143
	s_add_i32 s55, 0, 0x1c000
	ds_read_b128 v[146:149], v145
	ds_read_b128 v[150:153], v145 offset:1024
	ds_read_b128 v[154:157], v145 offset:2048
	ds_read_b128 v[172:175], v145 offset:3072
	v_add_u32_e32 v145, s55, v143
	ds_read_b128 v[176:179], v145
	ds_read_b128 v[180:183], v145 offset:1024
	ds_read_b128 v[184:187], v145 offset:2048
	ds_read_b128 v[196:199], v145 offset:3072
	s_add_u32 s30, s30, 0x100000
	s_addc_u32 s31, s31, 0
	s_mov_b32 m0, s42
	ds_read_b128 v[200:203], v144 offset:32768
	ds_read_b128 v[204:207], v144 offset:33792
	ds_read_b128 v[208:211], v144 offset:34816
	ds_read_b128 v[212:215], v144 offset:35840
	ds_read_b128 v[234:237], v144 offset:36864
	ds_read_b128 v[238:241], v144 offset:37888
	ds_read_b128 v[242:245], v144 offset:38912
	ds_read_b128 v[246:249], v144 offset:39936
	global_load_lds_dwordx4 v134, s[30:31]
	s_mov_b32 m0, s43
	s_nop 0
	global_load_lds_dwordx4 v130, s[30:31]
	s_waitcnt vmcnt(8)
	s_waitcnt lgkmcnt(0)
	s_barrier
	s_setprio 1
	s_waitcnt lgkmcnt(0)
	v_mfma_f32_16x16x32_bf16 v[124:127], v[146:149], v[200:203], v[124:127]
	v_mfma_f32_16x16x32_bf16 v[120:123], v[154:157], v[200:203], v[120:123]
	v_mfma_f32_16x16x32_bf16 v[116:119], v[146:149], v[208:211], v[116:119]
	v_mfma_f32_16x16x32_bf16 v[108:111], v[154:157], v[208:211], v[108:111]
	v_mfma_f32_16x16x32_bf16 v[100:103], v[146:149], v[234:237], v[100:103]
	v_mfma_f32_16x16x32_bf16 v[92:95], v[154:157], v[234:237], v[92:95]
	v_mfma_f32_16x16x32_bf16 v[84:87], v[146:149], v[242:245], v[84:87]
	v_mfma_f32_16x16x32_bf16 v[76:79], v[154:157], v[242:245], v[76:79]
	v_mfma_f32_16x16x32_bf16 v[124:127], v[150:153], v[204:207], v[124:127]
	v_mfma_f32_16x16x32_bf16 v[120:123], v[172:175], v[204:207], v[120:123]
	v_mfma_f32_16x16x32_bf16 v[116:119], v[150:153], v[212:215], v[116:119]
	v_mfma_f32_16x16x32_bf16 v[108:111], v[172:175], v[212:215], v[108:111]
	v_mfma_f32_16x16x32_bf16 v[100:103], v[150:153], v[238:241], v[100:103]
	v_mfma_f32_16x16x32_bf16 v[92:95], v[172:175], v[238:241], v[92:95]
	v_mfma_f32_16x16x32_bf16 v[84:87], v[150:153], v[246:249], v[84:87]
	v_mfma_f32_16x16x32_bf16 v[76:79], v[172:175], v[246:249], v[76:79]
	s_setprio 0
	s_setprio 1
	v_mfma_f32_16x16x32_bf16 v[112:115], v[176:179], v[200:203], v[112:115]
	v_mfma_f32_16x16x32_bf16 v[104:107], v[184:187], v[200:203], v[104:107]
	v_mfma_f32_16x16x32_bf16 v[96:99], v[176:179], v[208:211], v[96:99]
	v_mfma_f32_16x16x32_bf16 v[88:91], v[184:187], v[208:211], v[88:91]
	v_mfma_f32_16x16x32_bf16 v[80:83], v[176:179], v[234:237], v[80:83]
	v_mfma_f32_16x16x32_bf16 v[72:75], v[184:187], v[234:237], v[72:75]
	v_mfma_f32_16x16x32_bf16 v[68:71], v[176:179], v[242:245], v[68:71]
	v_mfma_f32_16x16x32_bf16 v[64:67], v[184:187], v[242:245], v[64:67]
	v_mfma_f32_16x16x32_bf16 v[112:115], v[180:183], v[204:207], v[112:115]
	v_mfma_f32_16x16x32_bf16 v[104:107], v[196:199], v[204:207], v[104:107]
	v_mfma_f32_16x16x32_bf16 v[96:99], v[180:183], v[212:215], v[96:99]
	v_mfma_f32_16x16x32_bf16 v[88:91], v[196:199], v[212:215], v[88:91]
	v_mfma_f32_16x16x32_bf16 v[80:83], v[180:183], v[238:241], v[80:83]
	v_mfma_f32_16x16x32_bf16 v[72:75], v[196:199], v[238:241], v[72:75]
	v_mfma_f32_16x16x32_bf16 v[68:71], v[180:183], v[246:249], v[68:71]
	v_mfma_f32_16x16x32_bf16 v[64:67], v[196:199], v[246:249], v[64:67]
	s_setprio 0
	s_barrier
	s_add_i32 s30, s54, s37
	v_lshl_add_u64 v[140:141], v[140:141], 0, s[20:21]
	s_mov_b32 m0, s30
	ds_read_b128 v[200:203], v144 offset:49152
	ds_read_b128 v[204:207], v144 offset:50176
	ds_read_b128 v[208:211], v144 offset:51200
	ds_read_b128 v[212:215], v144 offset:52224
	ds_read_b128 v[234:237], v144 offset:53248
	ds_read_b128 v[238:241], v144 offset:54272
	ds_read_b128 v[242:245], v144 offset:55296
	ds_read_b128 v[246:249], v144 offset:56320
	global_load_lds_dwordx4 v[140:141], off
	s_add_i32 m0, s30, 0x2000
	s_add_u32 s28, s28, 0x20080
	v_lshl_add_u64 v[140:141], v[158:159], 0, s[20:21]
	s_addc_u32 s29, s29, 0
	s_add_i32 s30, s55, s37
	global_load_lds_dwordx4 v[140:141], off
	s_mov_b32 m0, s30
	s_nop 0
	global_load_lds_dwordx4 v132, s[28:29]
	s_add_i32 m0, s30, 0x2000
	s_nop 0
	global_load_lds_dwordx4 v128, s[28:29]
	v_lshl_add_u64 v[140:141], v[188:189], 0, s[20:21]
	s_mov_b32 m0, s44
	s_nop 0
	global_load_lds_dwordx4 v[140:141], off
	v_lshl_add_u64 v[140:141], v[250:251], 0, s[20:21]
	s_mov_b32 m0, s45
	s_nop 0
	global_load_lds_dwordx4 v[140:141], off
	s_waitcnt vmcnt(8)
	s_waitcnt lgkmcnt(0)
	s_barrier
	s_setprio 1
	s_waitcnt lgkmcnt(0)
	v_mfma_f32_16x16x32_bf16 v[60:63], v[146:149], v[200:203], v[60:63]
	v_mfma_f32_16x16x32_bf16 v[56:59], v[154:157], v[200:203], v[56:59]
	v_mfma_f32_16x16x32_bf16 v[52:55], v[146:149], v[208:211], v[52:55]
	v_mfma_f32_16x16x32_bf16 v[44:47], v[154:157], v[208:211], v[44:47]
	v_mfma_f32_16x16x32_bf16 v[36:39], v[146:149], v[234:237], v[36:39]
	v_mfma_f32_16x16x32_bf16 v[28:31], v[154:157], v[234:237], v[28:31]
	v_mfma_f32_16x16x32_bf16 v[20:23], v[146:149], v[242:245], v[20:23]
	v_mfma_f32_16x16x32_bf16 v[12:15], v[154:157], v[242:245], v[12:15]
	v_mfma_f32_16x16x32_bf16 v[60:63], v[150:153], v[204:207], v[60:63]
	v_mfma_f32_16x16x32_bf16 v[56:59], v[172:175], v[204:207], v[56:59]
	v_mfma_f32_16x16x32_bf16 v[52:55], v[150:153], v[212:215], v[52:55]
	v_mfma_f32_16x16x32_bf16 v[44:47], v[172:175], v[212:215], v[44:47]
	v_mfma_f32_16x16x32_bf16 v[36:39], v[150:153], v[238:241], v[36:39]
	v_mfma_f32_16x16x32_bf16 v[28:31], v[172:175], v[238:241], v[28:31]
	v_mfma_f32_16x16x32_bf16 v[20:23], v[150:153], v[246:249], v[20:23]
	v_mfma_f32_16x16x32_bf16 v[12:15], v[172:175], v[246:249], v[12:15]
	s_setprio 0
	s_setprio 1
	v_mfma_f32_16x16x32_bf16 v[48:51], v[176:179], v[200:203], v[48:51]
	v_mfma_f32_16x16x32_bf16 v[40:43], v[184:187], v[200:203], v[40:43]
	v_mfma_f32_16x16x32_bf16 v[32:35], v[176:179], v[208:211], v[32:35]
	v_mfma_f32_16x16x32_bf16 v[24:27], v[184:187], v[208:211], v[24:27]
	v_mfma_f32_16x16x32_bf16 v[16:19], v[176:179], v[234:237], v[16:19]
	v_mfma_f32_16x16x32_bf16 v[8:11], v[184:187], v[234:237], v[8:11]
	v_mfma_f32_16x16x32_bf16 v[4:7], v[176:179], v[242:245], v[4:7]
	v_mfma_f32_16x16x32_bf16 v[0:3], v[184:187], v[242:245], v[0:3]
	v_mfma_f32_16x16x32_bf16 v[48:51], v[180:183], v[204:207], v[48:51]
	v_mfma_f32_16x16x32_bf16 v[40:43], v[196:199], v[204:207], v[40:43]
	v_mfma_f32_16x16x32_bf16 v[32:35], v[180:183], v[212:215], v[32:35]
	v_mfma_f32_16x16x32_bf16 v[24:27], v[196:199], v[212:215], v[24:27]
	v_mfma_f32_16x16x32_bf16 v[16:19], v[180:183], v[238:241], v[16:19]
	v_mfma_f32_16x16x32_bf16 v[8:11], v[196:199], v[238:241], v[8:11]
	v_mfma_f32_16x16x32_bf16 v[4:7], v[180:183], v[246:249], v[4:7]
	v_mfma_f32_16x16x32_bf16 v[0:3], v[196:199], v[246:249], v[0:3]
	s_setprio 0
	s_barrier
	s_add_i32 s53, s53, 2
	s_add_u32 s26, s26, 0x100
	s_addc_u32 s27, s27, 0
	s_add_u32 s51, s51, 0x100
	s_addc_u32 s52, s52, 0
	s_cmp_gt_u32 s53, 5
	s_cbranch_scc0 .LBB0_542
	s_and_b64 vcc, exec, s[10:11]
	s_cbranch_vccz .LBB0_545
	s_barrier

.LBB0_558:
	s_add_u32 s26, s18, 0xfffe0080
	s_addc_u32 s27, s19, -1
	s_add_i32 s52, 0, 0x10000
	s_cmp_eq_u32 s51, 4
	s_cselect_b32 s29, s13, s27
	s_cselect_b32 s28, s47, s26
	s_cselect_b32 s27, s11, s50
	s_cselect_b32 s26, s48, s49
	s_add_i32 s54, 0, 0x14000
	v_add_u32_e32 v154, s52, v139
	v_add_u32_e32 v158, s54, v139
	ds_read_b128 v[142:145], v154
	ds_read_b128 v[146:149], v154 offset:1024
	ds_read_b128 v[150:153], v154 offset:2048
	ds_read_b128 v[154:157], v154 offset:3072
	ds_read_b128 v[172:175], v158
	ds_read_b128 v[176:179], v158 offset:1024
	ds_read_b128 v[180:183], v158 offset:2048
	ds_read_b128 v[184:187], v158 offset:3072
	s_add_i32 m0, s36, 0xc000
	ds_read_b128 v[196:199], v141
	ds_read_b128 v[200:203], v141 offset:1024
	ds_read_b128 v[204:207], v141 offset:2048
	ds_read_b128 v[208:211], v141 offset:3072
	ds_read_b128 v[212:215], v141 offset:4096
	ds_read_b128 v[234:237], v141 offset:5120
	ds_read_b128 v[238:241], v141 offset:6144
	ds_read_b128 v[242:245], v141 offset:7168
	global_load_lds_dwordx4 v134, s[18:19]
	s_add_i32 m0, s36, 0xe000
	s_nop 0
	global_load_lds_dwordx4 v136, s[18:19]
	s_waitcnt vmcnt(8)
	s_waitcnt lgkmcnt(0)
	s_barrier
	s_setprio 1
	s_waitcnt lgkmcnt(0)
	v_mfma_f32_16x16x32_bf16 v[124:127], v[142:145], v[196:199], v[124:127]
	v_mfma_f32_16x16x32_bf16 v[120:123], v[150:153], v[196:199], v[120:123]
	v_mfma_f32_16x16x32_bf16 v[112:115], v[142:145], v[204:207], v[112:115]
	v_mfma_f32_16x16x32_bf16 v[104:107], v[150:153], v[204:207], v[104:107]
	v_mfma_f32_16x16x32_bf16 v[96:99], v[142:145], v[212:215], v[96:99]
	v_mfma_f32_16x16x32_bf16 v[88:91], v[150:153], v[212:215], v[88:91]
	v_mfma_f32_16x16x32_bf16 v[80:83], v[142:145], v[238:241], v[80:83]
	v_mfma_f32_16x16x32_bf16 v[72:75], v[150:153], v[238:241], v[72:75]
	v_mfma_f32_16x16x32_bf16 v[124:127], v[146:149], v[200:203], v[124:127]
	v_mfma_f32_16x16x32_bf16 v[120:123], v[154:157], v[200:203], v[120:123]
	v_mfma_f32_16x16x32_bf16 v[112:115], v[146:149], v[208:211], v[112:115]
	v_mfma_f32_16x16x32_bf16 v[104:107], v[154:157], v[208:211], v[104:107]
	v_mfma_f32_16x16x32_bf16 v[96:99], v[146:149], v[234:237], v[96:99]
	v_mfma_f32_16x16x32_bf16 v[88:91], v[154:157], v[234:237], v[88:91]
	v_mfma_f32_16x16x32_bf16 v[80:83], v[146:149], v[242:245], v[80:83]
	v_mfma_f32_16x16x32_bf16 v[72:75], v[154:157], v[242:245], v[72:75]
	s_setprio 0
	s_setprio 1
	v_mfma_f32_16x16x32_bf16 v[116:119], v[172:175], v[196:199], v[116:119]
	v_mfma_f32_16x16x32_bf16 v[108:111], v[180:183], v[196:199], v[108:111]
	v_mfma_f32_16x16x32_bf16 v[100:103], v[172:175], v[204:207], v[100:103]
	v_mfma_f32_16x16x32_bf16 v[92:95], v[180:183], v[204:207], v[92:95]
	v_mfma_f32_16x16x32_bf16 v[84:87], v[172:175], v[212:215], v[84:87]
	v_mfma_f32_16x16x32_bf16 v[76:79], v[180:183], v[212:215], v[76:79]
	v_mfma_f32_16x16x32_bf16 v[68:71], v[172:175], v[238:241], v[68:71]
	v_mfma_f32_16x16x32_bf16 v[64:67], v[180:183], v[238:241], v[64:67]
	v_mfma_f32_16x16x32_bf16 v[116:119], v[176:179], v[200:203], v[116:119]
	v_mfma_f32_16x16x32_bf16 v[108:111], v[184:187], v[200:203], v[108:111]
	v_mfma_f32_16x16x32_bf16 v[100:103], v[176:179], v[208:211], v[100:103]
	v_mfma_f32_16x16x32_bf16 v[92:95], v[184:187], v[208:211], v[92:95]
	v_mfma_f32_16x16x32_bf16 v[84:87], v[176:179], v[234:237], v[84:87]
	v_mfma_f32_16x16x32_bf16 v[76:79], v[184:187], v[234:237], v[76:79]
	v_mfma_f32_16x16x32_bf16 v[68:71], v[176:179], v[242:245], v[68:71]
	v_mfma_f32_16x16x32_bf16 v[64:67], v[184:187], v[242:245], v[64:67]
	s_setprio 0
	s_barrier
	s_add_i32 s52, s52, s35
	v_lshl_add_u64 v[158:159], s[26:27], 0, v[160:161]
	s_mov_b32 m0, s52
	ds_read_b128 v[196:199], v141 offset:16384
	ds_read_b128 v[200:203], v141 offset:17408
	ds_read_b128 v[204:207], v141 offset:18432
	ds_read_b128 v[208:211], v141 offset:19456
	ds_read_b128 v[212:215], v141 offset:20480
	ds_read_b128 v[234:237], v141 offset:21504
	ds_read_b128 v[238:241], v141 offset:22528
	ds_read_b128 v[242:245], v141 offset:23552
	global_load_lds_dwordx4 v[158:159], off
	s_add_i32 m0, s52, 0x2000
	s_add_u32 s52, s26, 0x100000
	v_lshl_add_u64 v[188:189], s[26:27], 0, v[128:129]
	s_addc_u32 s53, s27, 0
	s_add_i32 s54, s54, s35
	global_load_lds_dwordx4 v[188:189], off
	s_mov_b32 m0, s54
	v_lshl_add_u64 v[246:247], s[28:29], 0, v[130:131]
	global_load_lds_dwordx4 v160, s[52:53]
	s_add_i32 m0, s54, 0x2000
	s_nop 0
	global_load_lds_dwordx4 v128, s[52:53]
	v_lshl_add_u64 v[216:217], s[28:29], 0, v[132:133]
	s_mov_b32 m0, s36
	s_nop 0
	global_load_lds_dwordx4 v[216:217], off
	s_mov_b32 m0, s37
	s_nop 0
	global_load_lds_dwordx4 v[246:247], off
	s_waitcnt vmcnt(8)
	s_waitcnt lgkmcnt(0)
	s_barrier
	s_setprio 1
	s_waitcnt lgkmcnt(0)
	v_mfma_f32_16x16x32_bf16 v[60:63], v[142:145], v[196:199], v[60:63]
	v_mfma_f32_16x16x32_bf16 v[56:59], v[150:153], v[196:199], v[56:59]
	v_mfma_f32_16x16x32_bf16 v[48:51], v[142:145], v[204:207], v[48:51]
	v_mfma_f32_16x16x32_bf16 v[40:43], v[150:153], v[204:207], v[40:43]
	v_mfma_f32_16x16x32_bf16 v[32:35], v[142:145], v[212:215], v[32:35]
	v_mfma_f32_16x16x32_bf16 v[24:27], v[150:153], v[212:215], v[24:27]
	v_mfma_f32_16x16x32_bf16 v[16:19], v[142:145], v[238:241], v[16:19]
	v_mfma_f32_16x16x32_bf16 v[8:11], v[150:153], v[238:241], v[8:11]
	v_mfma_f32_16x16x32_bf16 v[60:63], v[146:149], v[200:203], v[60:63]
	v_mfma_f32_16x16x32_bf16 v[56:59], v[154:157], v[200:203], v[56:59]
	v_mfma_f32_16x16x32_bf16 v[48:51], v[146:149], v[208:211], v[48:51]
	v_mfma_f32_16x16x32_bf16 v[40:43], v[154:157], v[208:211], v[40:43]
	v_mfma_f32_16x16x32_bf16 v[32:35], v[146:149], v[234:237], v[32:35]
	v_mfma_f32_16x16x32_bf16 v[24:27], v[154:157], v[234:237], v[24:27]
	v_mfma_f32_16x16x32_bf16 v[16:19], v[146:149], v[242:245], v[16:19]
	v_mfma_f32_16x16x32_bf16 v[8:11], v[154:157], v[242:245], v[8:11]
	s_setprio 0
	s_setprio 1
	v_mfma_f32_16x16x32_bf16 v[52:55], v[172:175], v[196:199], v[52:55]
	v_mfma_f32_16x16x32_bf16 v[44:47], v[180:183], v[196:199], v[44:47]
	v_mfma_f32_16x16x32_bf16 v[36:39], v[172:175], v[204:207], v[36:39]
	v_mfma_f32_16x16x32_bf16 v[28:31], v[180:183], v[204:207], v[28:31]
	v_mfma_f32_16x16x32_bf16 v[20:23], v[172:175], v[212:215], v[20:23]
	v_mfma_f32_16x16x32_bf16 v[12:15], v[180:183], v[212:215], v[12:15]
	v_mfma_f32_16x16x32_bf16 v[4:7], v[172:175], v[238:241], v[4:7]
	v_mfma_f32_16x16x32_bf16 v[0:3], v[180:183], v[238:241], v[0:3]
	v_mfma_f32_16x16x32_bf16 v[52:55], v[176:179], v[200:203], v[52:55]
	v_mfma_f32_16x16x32_bf16 v[44:47], v[184:187], v[200:203], v[44:47]
	v_mfma_f32_16x16x32_bf16 v[36:39], v[176:179], v[208:211], v[36:39]
	v_mfma_f32_16x16x32_bf16 v[28:31], v[184:187], v[208:211], v[28:31]
	v_mfma_f32_16x16x32_bf16 v[20:23], v[176:179], v[234:237], v[20:23]
	v_mfma_f32_16x16x32_bf16 v[12:15], v[184:187], v[234:237], v[12:15]
	v_mfma_f32_16x16x32_bf16 v[4:7], v[176:179], v[242:245], v[4:7]
	v_mfma_f32_16x16x32_bf16 v[0:3], v[184:187], v[242:245], v[0:3]
	s_setprio 0
	s_barrier
	s_add_i32 s52, 0, 0x18000
	s_add_i32 s53, 0, 0x1c000
	v_add_u32_e32 v154, s52, v139
	v_add_u32_e32 v162, s53, v139
	ds_read_b128 v[142:145], v154
	ds_read_b128 v[146:149], v154 offset:1024
	ds_read_b128 v[150:153], v154 offset:2048
	ds_read_b128 v[154:157], v154 offset:3072
	ds_read_b128 v[172:175], v162
	ds_read_b128 v[176:179], v162 offset:1024
	ds_read_b128 v[180:183], v162 offset:2048
	ds_read_b128 v[184:187], v162 offset:3072
	s_add_u32 s28, s28, 0x20000
	s_addc_u32 s29, s29, 0
	s_mov_b32 m0, s40
	ds_read_b128 v[196:199], v141 offset:32768
	ds_read_b128 v[200:203], v141 offset:33792
	ds_read_b128 v[204:207], v141 offset:34816
	ds_read_b128 v[208:211], v141 offset:35840
	ds_read_b128 v[212:215], v141 offset:36864
	ds_read_b128 v[234:237], v141 offset:37888
	ds_read_b128 v[238:241], v141 offset:38912
	ds_read_b128 v[242:245], v141 offset:39936
	global_load_lds_dwordx4 v132, s[28:29]
	s_mov_b32 m0, s41
	s_nop 0
	global_load_lds_dwordx4 v130, s[28:29]
	s_waitcnt vmcnt(8)
	s_waitcnt lgkmcnt(0)
	s_barrier
	s_setprio 1
	s_waitcnt lgkmcnt(0)
	v_mfma_f32_16x16x32_bf16 v[124:127], v[142:145], v[196:199], v[124:127]
	v_mfma_f32_16x16x32_bf16 v[120:123], v[150:153], v[196:199], v[120:123]
	v_mfma_f32_16x16x32_bf16 v[112:115], v[142:145], v[204:207], v[112:115]
	v_mfma_f32_16x16x32_bf16 v[104:107], v[150:153], v[204:207], v[104:107]
	v_mfma_f32_16x16x32_bf16 v[96:99], v[142:145], v[212:215], v[96:99]
	v_mfma_f32_16x16x32_bf16 v[88:91], v[150:153], v[212:215], v[88:91]
	v_mfma_f32_16x16x32_bf16 v[80:83], v[142:145], v[238:241], v[80:83]
	v_mfma_f32_16x16x32_bf16 v[72:75], v[150:153], v[238:241], v[72:75]
	v_mfma_f32_16x16x32_bf16 v[124:127], v[146:149], v[200:203], v[124:127]
	v_mfma_f32_16x16x32_bf16 v[120:123], v[154:157], v[200:203], v[120:123]
	v_mfma_f32_16x16x32_bf16 v[112:115], v[146:149], v[208:211], v[112:115]
	v_mfma_f32_16x16x32_bf16 v[104:107], v[154:157], v[208:211], v[104:107]
	v_mfma_f32_16x16x32_bf16 v[96:99], v[146:149], v[234:237], v[96:99]
	v_mfma_f32_16x16x32_bf16 v[88:91], v[154:157], v[234:237], v[88:91]
	v_mfma_f32_16x16x32_bf16 v[80:83], v[146:149], v[242:245], v[80:83]
	v_mfma_f32_16x16x32_bf16 v[72:75], v[154:157], v[242:245], v[72:75]
	s_setprio 0
	s_setprio 1
	v_mfma_f32_16x16x32_bf16 v[116:119], v[172:175], v[196:199], v[116:119]
	v_mfma_f32_16x16x32_bf16 v[108:111], v[180:183], v[196:199], v[108:111]
	v_mfma_f32_16x16x32_bf16 v[100:103], v[172:175], v[204:207], v[100:103]
	v_mfma_f32_16x16x32_bf16 v[92:95], v[180:183], v[204:207], v[92:95]
	v_mfma_f32_16x16x32_bf16 v[84:87], v[172:175], v[212:215], v[84:87]
	v_mfma_f32_16x16x32_bf16 v[76:79], v[180:183], v[212:215], v[76:79]
	v_mfma_f32_16x16x32_bf16 v[68:71], v[172:175], v[238:241], v[68:71]
	v_mfma_f32_16x16x32_bf16 v[64:67], v[180:183], v[238:241], v[64:67]
	v_mfma_f32_16x16x32_bf16 v[116:119], v[176:179], v[200:203], v[116:119]
	v_mfma_f32_16x16x32_bf16 v[108:111], v[184:187], v[200:203], v[108:111]
	v_mfma_f32_16x16x32_bf16 v[100:103], v[176:179], v[208:211], v[100:103]
	v_mfma_f32_16x16x32_bf16 v[92:95], v[184:187], v[208:211], v[92:95]
	v_mfma_f32_16x16x32_bf16 v[84:87], v[176:179], v[234:237], v[84:87]
	v_mfma_f32_16x16x32_bf16 v[76:79], v[184:187], v[234:237], v[76:79]
	v_mfma_f32_16x16x32_bf16 v[68:71], v[176:179], v[242:245], v[68:71]
	v_mfma_f32_16x16x32_bf16 v[64:67], v[184:187], v[242:245], v[64:67]
	s_setprio 0
	s_barrier
	s_add_i32 s28, s52, s35
	v_lshl_add_u64 v[158:159], v[158:159], 0, s[20:21]
	s_mov_b32 m0, s28
	ds_read_b128 v[196:199], v141 offset:49152
	ds_read_b128 v[200:203], v141 offset:50176
	ds_read_b128 v[204:207], v141 offset:51200
	ds_read_b128 v[208:211], v141 offset:52224
	ds_read_b128 v[212:215], v141 offset:53248
	ds_read_b128 v[234:237], v141 offset:54272
	ds_read_b128 v[238:241], v141 offset:55296
	ds_read_b128 v[242:245], v141 offset:56320
	global_load_lds_dwordx4 v[158:159], off
	s_add_i32 m0, s28, 0x2000
	s_add_u32 s26, s26, 0x100080
	v_lshl_add_u64 v[158:159], v[188:189], 0, s[20:21]
	s_addc_u32 s27, s27, 0
	s_add_i32 s28, s53, s35
	global_load_lds_dwordx4 v[158:159], off
	s_mov_b32 m0, s28
	s_nop 0
	global_load_lds_dwordx4 v160, s[26:27]
	s_add_i32 m0, s28, 0x2000
	s_nop 0
	global_load_lds_dwordx4 v128, s[26:27]
	v_lshl_add_u64 v[158:159], v[216:217], 0, s[20:21]
	s_mov_b32 m0, s42
	s_nop 0
	global_load_lds_dwordx4 v[158:159], off
	v_lshl_add_u64 v[158:159], v[246:247], 0, s[20:21]
	s_mov_b32 m0, s43
	s_nop 0
	global_load_lds_dwordx4 v[158:159], off
	s_waitcnt vmcnt(8)
	s_waitcnt lgkmcnt(0)
	s_barrier
	s_setprio 1
	s_waitcnt lgkmcnt(0)
	v_mfma_f32_16x16x32_bf16 v[60:63], v[142:145], v[196:199], v[60:63]
	v_mfma_f32_16x16x32_bf16 v[56:59], v[150:153], v[196:199], v[56:59]
	v_mfma_f32_16x16x32_bf16 v[48:51], v[142:145], v[204:207], v[48:51]
	v_mfma_f32_16x16x32_bf16 v[40:43], v[150:153], v[204:207], v[40:43]
	v_mfma_f32_16x16x32_bf16 v[32:35], v[142:145], v[212:215], v[32:35]
	v_mfma_f32_16x16x32_bf16 v[24:27], v[150:153], v[212:215], v[24:27]
	v_mfma_f32_16x16x32_bf16 v[16:19], v[142:145], v[238:241], v[16:19]
	v_mfma_f32_16x16x32_bf16 v[8:11], v[150:153], v[238:241], v[8:11]
	v_mfma_f32_16x16x32_bf16 v[60:63], v[146:149], v[200:203], v[60:63]
	v_mfma_f32_16x16x32_bf16 v[56:59], v[154:157], v[200:203], v[56:59]
	v_mfma_f32_16x16x32_bf16 v[48:51], v[146:149], v[208:211], v[48:51]
	v_mfma_f32_16x16x32_bf16 v[40:43], v[154:157], v[208:211], v[40:43]
	v_mfma_f32_16x16x32_bf16 v[32:35], v[146:149], v[234:237], v[32:35]
	v_mfma_f32_16x16x32_bf16 v[24:27], v[154:157], v[234:237], v[24:27]
	v_mfma_f32_16x16x32_bf16 v[16:19], v[146:149], v[242:245], v[16:19]
	v_mfma_f32_16x16x32_bf16 v[8:11], v[154:157], v[242:245], v[8:11]
	s_setprio 0
	s_setprio 1
	v_mfma_f32_16x16x32_bf16 v[52:55], v[172:175], v[196:199], v[52:55]
	v_mfma_f32_16x16x32_bf16 v[44:47], v[180:183], v[196:199], v[44:47]
	v_mfma_f32_16x16x32_bf16 v[36:39], v[172:175], v[204:207], v[36:39]
	v_mfma_f32_16x16x32_bf16 v[28:31], v[180:183], v[204:207], v[28:31]
	v_mfma_f32_16x16x32_bf16 v[20:23], v[172:175], v[212:215], v[20:23]
	v_mfma_f32_16x16x32_bf16 v[12:15], v[180:183], v[212:215], v[12:15]
	v_mfma_f32_16x16x32_bf16 v[4:7], v[172:175], v[238:241], v[4:7]
	v_mfma_f32_16x16x32_bf16 v[0:3], v[180:183], v[238:241], v[0:3]
	v_mfma_f32_16x16x32_bf16 v[52:55], v[176:179], v[200:203], v[52:55]
	v_mfma_f32_16x16x32_bf16 v[44:47], v[184:187], v[200:203], v[44:47]
	v_mfma_f32_16x16x32_bf16 v[36:39], v[176:179], v[208:211], v[36:39]
	v_mfma_f32_16x16x32_bf16 v[28:31], v[184:187], v[208:211], v[28:31]
	v_mfma_f32_16x16x32_bf16 v[20:23], v[176:179], v[234:237], v[20:23]
	v_mfma_f32_16x16x32_bf16 v[12:15], v[184:187], v[234:237], v[12:15]
	v_mfma_f32_16x16x32_bf16 v[4:7], v[176:179], v[242:245], v[4:7]
	v_mfma_f32_16x16x32_bf16 v[0:3], v[184:187], v[242:245], v[0:3]
	s_setprio 0
	s_barrier
	s_add_i32 s51, s51, 2
	s_add_u32 s18, s18, 0x100
	s_addc_u32 s19, s19, 0
	s_add_u32 s49, s49, 0x100
	s_addc_u32 s50, s50, 0
	s_cmp_gt_u32 s51, 5
	s_cbranch_scc0 .LBB0_558
	s_and_b64 vcc, exec, s[8:9]
	s_cbranch_vccz .LBB0_561
	s_barrier

.LBB0_1024:
	s_add_u32 s30, s28, 0xfffc0080
	s_addc_u32 s31, s29, -1
	s_add_i32 s59, 0, 0x10000
	s_cmp_eq_u32 s58, 12
	s_cselect_b32 s35, s15, s31
	s_cselect_b32 s34, s54, s30
	s_cselect_b32 s31, s13, s57
	s_cselect_b32 s30, s55, s56
	s_add_i32 s62, 0, 0x14000
	v_add_u32_e32 v36, s59, v186
	v_add_u32_e32 v178, s62, v186
	ds_read_b128 v[16:19], v36
	ds_read_b128 v[20:23], v36 offset:1024
	ds_read_b128 v[32:35], v36 offset:2048
	ds_read_b128 v[36:39], v36 offset:3072
	ds_read_b128 v[128:131], v178
	ds_read_b128 v[140:143], v178 offset:1024
	ds_read_b128 v[152:155], v178 offset:2048
	ds_read_b128 v[178:181], v178 offset:3072
	s_add_i32 m0, s47, 0xc000
	ds_read_b128 v[182:185], v188
	ds_read_b128 v[196:199], v188 offset:1024
	ds_read_b128 v[200:203], v188 offset:2048
	ds_read_b128 v[204:207], v188 offset:3072
	ds_read_b128 v[208:211], v188 offset:4096
	ds_read_b128 v[212:215], v188 offset:5120
	ds_read_b128 v[234:237], v188 offset:6144
	ds_read_b128 v[238:241], v188 offset:7168
	global_load_lds_dwordx4 v174, s[28:29]
	s_add_i32 m0, s47, 0xe000
	s_nop 0
	global_load_lds_dwordx4 v176, s[28:29]
	s_waitcnt vmcnt(8)
	s_waitcnt lgkmcnt(0)
	s_barrier
	s_setprio 1
	s_waitcnt lgkmcnt(0)
	v_mfma_f32_16x16x32_bf16 v[148:151], v[16:19], v[182:185], v[148:151]
	v_mfma_f32_16x16x32_bf16 v[144:147], v[32:35], v[182:185], v[144:147]
	v_mfma_f32_16x16x32_bf16 v[124:127], v[16:19], v[200:203], v[124:127]
	v_mfma_f32_16x16x32_bf16 v[120:123], v[32:35], v[200:203], v[120:123]
	v_mfma_f32_16x16x32_bf16 v[108:111], v[16:19], v[208:211], v[108:111]
	v_mfma_f32_16x16x32_bf16 v[104:107], v[32:35], v[208:211], v[104:107]
	v_mfma_f32_16x16x32_bf16 v[92:95], v[16:19], v[234:237], v[92:95]
	v_mfma_f32_16x16x32_bf16 v[88:91], v[32:35], v[234:237], v[88:91]
	v_mfma_f32_16x16x32_bf16 v[148:151], v[20:23], v[196:199], v[148:151]
	v_mfma_f32_16x16x32_bf16 v[144:147], v[36:39], v[196:199], v[144:147]
	v_mfma_f32_16x16x32_bf16 v[124:127], v[20:23], v[204:207], v[124:127]
	v_mfma_f32_16x16x32_bf16 v[120:123], v[36:39], v[204:207], v[120:123]
	v_mfma_f32_16x16x32_bf16 v[108:111], v[20:23], v[212:215], v[108:111]
	v_mfma_f32_16x16x32_bf16 v[104:107], v[36:39], v[212:215], v[104:107]
	v_mfma_f32_16x16x32_bf16 v[92:95], v[20:23], v[238:241], v[92:95]
	v_mfma_f32_16x16x32_bf16 v[88:91], v[36:39], v[238:241], v[88:91]
	s_setprio 0
	s_setprio 1
	v_mfma_f32_16x16x32_bf16 v[136:139], v[128:131], v[182:185], v[136:139]
	v_mfma_f32_16x16x32_bf16 v[132:135], v[152:155], v[182:185], v[132:135]
	v_mfma_f32_16x16x32_bf16 v[116:119], v[128:131], v[200:203], v[116:119]
	v_mfma_f32_16x16x32_bf16 v[112:115], v[152:155], v[200:203], v[112:115]
	v_mfma_f32_16x16x32_bf16 v[100:103], v[128:131], v[208:211], v[100:103]
	v_mfma_f32_16x16x32_bf16 v[96:99], v[152:155], v[208:211], v[96:99]
	v_mfma_f32_16x16x32_bf16 v[84:87], v[128:131], v[234:237], v[84:87]
	v_mfma_f32_16x16x32_bf16 v[80:83], v[152:155], v[234:237], v[80:83]
	v_mfma_f32_16x16x32_bf16 v[136:139], v[140:143], v[196:199], v[136:139]
	v_mfma_f32_16x16x32_bf16 v[132:135], v[178:181], v[196:199], v[132:135]
	v_mfma_f32_16x16x32_bf16 v[116:119], v[140:143], v[204:207], v[116:119]
	v_mfma_f32_16x16x32_bf16 v[112:115], v[178:181], v[204:207], v[112:115]
	v_mfma_f32_16x16x32_bf16 v[100:103], v[140:143], v[212:215], v[100:103]
	v_mfma_f32_16x16x32_bf16 v[96:99], v[178:181], v[212:215], v[96:99]
	v_mfma_f32_16x16x32_bf16 v[84:87], v[140:143], v[238:241], v[84:87]
	v_mfma_f32_16x16x32_bf16 v[80:83], v[178:181], v[238:241], v[80:83]
	s_setprio 0
	s_barrier
	s_add_i32 s59, s59, s44
	v_lshl_add_u64 v[216:217], s[30:31], 0, v[160:161]
	s_mov_b32 m0, s59
	ds_read_b128 v[182:185], v188 offset:16384
	ds_read_b128 v[196:199], v188 offset:17408
	ds_read_b128 v[200:203], v188 offset:18432
	ds_read_b128 v[204:207], v188 offset:19456
	ds_read_b128 v[208:211], v188 offset:20480
	ds_read_b128 v[212:215], v188 offset:21504
	ds_read_b128 v[234:237], v188 offset:22528
	ds_read_b128 v[238:241], v188 offset:23552
	global_load_lds_dwordx4 v[216:217], off
	s_add_i32 m0, s59, 0x2000
	s_add_u32 s60, s30, 0x40000
	v_lshl_add_u64 v[242:243], s[30:31], 0, v[156:157]
	s_addc_u32 s61, s31, 0
	s_add_i32 s59, s62, s44
	global_load_lds_dwordx4 v[242:243], off
	s_mov_b32 m0, s59
	v_lshl_add_u64 v[246:247], s[34:35], 0, v[158:159]
	global_load_lds_dwordx4 v160, s[60:61]
	s_add_i32 m0, s59, 0x2000
	s_nop 0
	global_load_lds_dwordx4 v156, s[60:61]
	v_lshl_add_u64 v[244:245], s[34:35], 0, v[172:173]
	s_mov_b32 m0, s47
	s_nop 0
	global_load_lds_dwordx4 v[244:245], off
	s_mov_b32 m0, s48
	s_nop 0
	global_load_lds_dwordx4 v[246:247], off
	s_waitcnt vmcnt(8)
	s_waitcnt lgkmcnt(0)
	s_barrier
	s_setprio 1
	s_waitcnt lgkmcnt(0)
	v_mfma_f32_16x16x32_bf16 v[76:79], v[16:19], v[182:185], v[76:79]
	v_mfma_f32_16x16x32_bf16 v[72:75], v[32:35], v[182:185], v[72:75]
	v_mfma_f32_16x16x32_bf16 v[60:63], v[16:19], v[200:203], v[60:63]
	v_mfma_f32_16x16x32_bf16 v[56:59], v[32:35], v[200:203], v[56:59]
	v_mfma_f32_16x16x32_bf16 v[44:47], v[16:19], v[208:211], v[44:47]
	v_mfma_f32_16x16x32_bf16 v[40:43], v[32:35], v[208:211], v[40:43]
	v_mfma_f32_16x16x32_bf16 v[12:15], v[16:19], v[234:237], v[12:15]
	v_mfma_f32_16x16x32_bf16 v[8:11], v[32:35], v[234:237], v[8:11]
	v_mfma_f32_16x16x32_bf16 v[76:79], v[20:23], v[196:199], v[76:79]
	v_mfma_f32_16x16x32_bf16 v[72:75], v[36:39], v[196:199], v[72:75]
	v_mfma_f32_16x16x32_bf16 v[60:63], v[20:23], v[204:207], v[60:63]
	v_mfma_f32_16x16x32_bf16 v[56:59], v[36:39], v[204:207], v[56:59]
	v_mfma_f32_16x16x32_bf16 v[44:47], v[20:23], v[212:215], v[44:47]
	v_mfma_f32_16x16x32_bf16 v[40:43], v[36:39], v[212:215], v[40:43]
	v_mfma_f32_16x16x32_bf16 v[12:15], v[20:23], v[238:241], v[12:15]
	v_mfma_f32_16x16x32_bf16 v[8:11], v[36:39], v[238:241], v[8:11]
	s_setprio 0
	s_setprio 1
	v_mfma_f32_16x16x32_bf16 v[28:31], v[128:131], v[208:211], v[28:31]
	v_mfma_f32_16x16x32_bf16 v[24:27], v[152:155], v[208:211], v[24:27]
	v_mfma_f32_16x16x32_bf16 v[4:7], v[128:131], v[234:237], v[4:7]
	v_mfma_f32_16x16x32_bf16 v[0:3], v[152:155], v[234:237], v[0:3]
	v_mfma_f32_16x16x32_bf16 v[16:19], v[128:131], v[182:185], v[68:71]
	v_mfma_f32_16x16x32_bf16 v[20:23], v[152:155], v[182:185], v[64:67]
	v_mfma_f32_16x16x32_bf16 v[32:35], v[128:131], v[200:203], v[52:55]
	v_mfma_f32_16x16x32_bf16 v[36:39], v[152:155], v[200:203], v[48:51]
	v_mfma_f32_16x16x32_bf16 v[28:31], v[140:143], v[212:215], v[28:31]
	v_mfma_f32_16x16x32_bf16 v[24:27], v[178:181], v[212:215], v[24:27]
	v_mfma_f32_16x16x32_bf16 v[4:7], v[140:143], v[238:241], v[4:7]
	v_mfma_f32_16x16x32_bf16 v[0:3], v[178:181], v[238:241], v[0:3]
	v_mfma_f32_16x16x32_bf16 v[16:19], v[140:143], v[196:199], v[16:19]
	v_mfma_f32_16x16x32_bf16 v[20:23], v[178:181], v[196:199], v[20:23]
	v_mfma_f32_16x16x32_bf16 v[32:35], v[140:143], v[204:207], v[32:35]
	v_mfma_f32_16x16x32_bf16 v[36:39], v[178:181], v[204:207], v[36:39]
	s_setprio 0
	s_barrier
	s_add_i32 s59, 0, 0x18000
	s_add_i32 s60, 0, 0x1c000
	v_add_u32_e32 v68, s59, v186
	v_add_u32_e32 v178, s60, v186
	ds_read_b128 v[48:51], v68
	ds_read_b128 v[52:55], v68 offset:1024
	ds_read_b128 v[64:67], v68 offset:2048
	ds_read_b128 v[68:71], v68 offset:3072
	ds_read_b128 v[128:131], v178
	ds_read_b128 v[140:143], v178 offset:1024
	ds_read_b128 v[152:155], v178 offset:2048
	ds_read_b128 v[178:181], v178 offset:3072
	s_add_u32 s34, s34, 0x40000
	s_addc_u32 s35, s35, 0
	s_mov_b32 m0, s49
	ds_read_b128 v[182:185], v188 offset:32768
	ds_read_b128 v[196:199], v188 offset:33792
	ds_read_b128 v[200:203], v188 offset:34816
	ds_read_b128 v[204:207], v188 offset:35840
	ds_read_b128 v[208:211], v188 offset:36864
	ds_read_b128 v[212:215], v188 offset:37888
	ds_read_b128 v[234:237], v188 offset:38912
	ds_read_b128 v[238:241], v188 offset:39936
	global_load_lds_dwordx4 v172, s[34:35]
	s_mov_b32 m0, s50
	s_nop 0
	global_load_lds_dwordx4 v158, s[34:35]
	s_waitcnt vmcnt(8)
	s_waitcnt lgkmcnt(0)
	s_barrier
	s_setprio 1
	s_waitcnt lgkmcnt(0)
	v_mfma_f32_16x16x32_bf16 v[148:151], v[48:51], v[182:185], v[148:151]
	v_mfma_f32_16x16x32_bf16 v[144:147], v[64:67], v[182:185], v[144:147]
	v_mfma_f32_16x16x32_bf16 v[124:127], v[48:51], v[200:203], v[124:127]
	v_mfma_f32_16x16x32_bf16 v[120:123], v[64:67], v[200:203], v[120:123]
	v_mfma_f32_16x16x32_bf16 v[108:111], v[48:51], v[208:211], v[108:111]
	v_mfma_f32_16x16x32_bf16 v[104:107], v[64:67], v[208:211], v[104:107]
	v_mfma_f32_16x16x32_bf16 v[92:95], v[48:51], v[234:237], v[92:95]
	v_mfma_f32_16x16x32_bf16 v[88:91], v[64:67], v[234:237], v[88:91]
	v_mfma_f32_16x16x32_bf16 v[148:151], v[52:55], v[196:199], v[148:151]
	v_mfma_f32_16x16x32_bf16 v[144:147], v[68:71], v[196:199], v[144:147]
	v_mfma_f32_16x16x32_bf16 v[124:127], v[52:55], v[204:207], v[124:127]
	v_mfma_f32_16x16x32_bf16 v[120:123], v[68:71], v[204:207], v[120:123]
	v_mfma_f32_16x16x32_bf16 v[108:111], v[52:55], v[212:215], v[108:111]
	v_mfma_f32_16x16x32_bf16 v[104:107], v[68:71], v[212:215], v[104:107]
	v_mfma_f32_16x16x32_bf16 v[92:95], v[52:55], v[238:241], v[92:95]
	v_mfma_f32_16x16x32_bf16 v[88:91], v[68:71], v[238:241], v[88:91]
	s_setprio 0
	s_setprio 1
	v_mfma_f32_16x16x32_bf16 v[136:139], v[128:131], v[182:185], v[136:139]
	v_mfma_f32_16x16x32_bf16 v[132:135], v[152:155], v[182:185], v[132:135]
	v_mfma_f32_16x16x32_bf16 v[116:119], v[128:131], v[200:203], v[116:119]
	v_mfma_f32_16x16x32_bf16 v[112:115], v[152:155], v[200:203], v[112:115]
	v_mfma_f32_16x16x32_bf16 v[100:103], v[128:131], v[208:211], v[100:103]
	v_mfma_f32_16x16x32_bf16 v[96:99], v[152:155], v[208:211], v[96:99]
	v_mfma_f32_16x16x32_bf16 v[84:87], v[128:131], v[234:237], v[84:87]
	v_mfma_f32_16x16x32_bf16 v[80:83], v[152:155], v[234:237], v[80:83]
	v_mfma_f32_16x16x32_bf16 v[136:139], v[140:143], v[196:199], v[136:139]
	v_mfma_f32_16x16x32_bf16 v[132:135], v[178:181], v[196:199], v[132:135]
	v_mfma_f32_16x16x32_bf16 v[116:119], v[140:143], v[204:207], v[116:119]
	v_mfma_f32_16x16x32_bf16 v[112:115], v[178:181], v[204:207], v[112:115]
	v_mfma_f32_16x16x32_bf16 v[100:103], v[140:143], v[212:215], v[100:103]
	v_mfma_f32_16x16x32_bf16 v[96:99], v[178:181], v[212:215], v[96:99]
	v_mfma_f32_16x16x32_bf16 v[84:87], v[140:143], v[238:241], v[84:87]
	v_mfma_f32_16x16x32_bf16 v[80:83], v[178:181], v[238:241], v[80:83]
	s_setprio 0
	s_barrier
	s_add_i32 s34, s59, s44
	v_lshl_add_u64 v[216:217], v[216:217], 0, s[20:21]
	s_mov_b32 m0, s34
	ds_read_b128 v[182:185], v188 offset:49152
	ds_read_b128 v[196:199], v188 offset:50176
	ds_read_b128 v[200:203], v188 offset:51200
	ds_read_b128 v[204:207], v188 offset:52224
	ds_read_b128 v[208:211], v188 offset:53248
	ds_read_b128 v[212:215], v188 offset:54272
	ds_read_b128 v[234:237], v188 offset:55296
	ds_read_b128 v[238:241], v188 offset:56320
	global_load_lds_dwordx4 v[216:217], off
	s_add_i32 m0, s34, 0x2000
	s_add_u32 s30, s30, 0x40080
	v_lshl_add_u64 v[216:217], v[242:243], 0, s[20:21]
	s_addc_u32 s31, s31, 0
	s_add_i32 s34, s60, s44
	global_load_lds_dwordx4 v[216:217], off
	s_mov_b32 m0, s34
	s_nop 0
	global_load_lds_dwordx4 v160, s[30:31]
	s_add_i32 m0, s34, 0x2000
	s_nop 0
	global_load_lds_dwordx4 v156, s[30:31]
	v_lshl_add_u64 v[216:217], v[244:245], 0, s[20:21]
	s_mov_b32 m0, s51
	s_nop 0
	global_load_lds_dwordx4 v[216:217], off
	v_lshl_add_u64 v[216:217], v[246:247], 0, s[20:21]
	s_mov_b32 m0, s52
	s_nop 0
	global_load_lds_dwordx4 v[216:217], off
	s_waitcnt vmcnt(8)
	s_waitcnt lgkmcnt(0)
	s_barrier
	s_setprio 1
	s_waitcnt lgkmcnt(0)
	v_mfma_f32_16x16x32_bf16 v[76:79], v[48:51], v[182:185], v[76:79]
	v_mfma_f32_16x16x32_bf16 v[72:75], v[64:67], v[182:185], v[72:75]
	v_mfma_f32_16x16x32_bf16 v[60:63], v[48:51], v[200:203], v[60:63]
	v_mfma_f32_16x16x32_bf16 v[56:59], v[64:67], v[200:203], v[56:59]
	v_mfma_f32_16x16x32_bf16 v[44:47], v[48:51], v[208:211], v[44:47]
	v_mfma_f32_16x16x32_bf16 v[40:43], v[64:67], v[208:211], v[40:43]
	v_mfma_f32_16x16x32_bf16 v[12:15], v[48:51], v[234:237], v[12:15]
	v_mfma_f32_16x16x32_bf16 v[8:11], v[64:67], v[234:237], v[8:11]
	v_mfma_f32_16x16x32_bf16 v[76:79], v[52:55], v[196:199], v[76:79]
	v_mfma_f32_16x16x32_bf16 v[72:75], v[68:71], v[196:199], v[72:75]
	v_mfma_f32_16x16x32_bf16 v[60:63], v[52:55], v[204:207], v[60:63]
	v_mfma_f32_16x16x32_bf16 v[56:59], v[68:71], v[204:207], v[56:59]
	v_mfma_f32_16x16x32_bf16 v[44:47], v[52:55], v[212:215], v[44:47]
	v_mfma_f32_16x16x32_bf16 v[40:43], v[68:71], v[212:215], v[40:43]
	v_mfma_f32_16x16x32_bf16 v[12:15], v[52:55], v[238:241], v[12:15]
	v_mfma_f32_16x16x32_bf16 v[8:11], v[68:71], v[238:241], v[8:11]
	s_setprio 0
	s_setprio 1
	v_mfma_f32_16x16x32_bf16 v[16:19], v[128:131], v[182:185], v[16:19]
	v_mfma_f32_16x16x32_bf16 v[68:71], v[140:143], v[196:199], v[16:19]
	v_mfma_f32_16x16x32_bf16 v[16:19], v[152:155], v[182:185], v[20:23]
	v_mfma_f32_16x16x32_bf16 v[64:67], v[178:181], v[196:199], v[16:19]
	v_mfma_f32_16x16x32_bf16 v[16:19], v[128:131], v[200:203], v[32:35]
	v_mfma_f32_16x16x32_bf16 v[52:55], v[140:143], v[204:207], v[16:19]
	v_mfma_f32_16x16x32_bf16 v[16:19], v[152:155], v[200:203], v[36:39]
	v_mfma_f32_16x16x32_bf16 v[48:51], v[178:181], v[204:207], v[16:19]
	v_mfma_f32_16x16x32_bf16 v[16:19], v[128:131], v[208:211], v[28:31]
	v_mfma_f32_16x16x32_bf16 v[28:31], v[140:143], v[212:215], v[16:19]
	v_mfma_f32_16x16x32_bf16 v[16:19], v[152:155], v[208:211], v[24:27]
	v_mfma_f32_16x16x32_bf16 v[4:7], v[128:131], v[234:237], v[4:7]
	v_mfma_f32_16x16x32_bf16 v[0:3], v[152:155], v[234:237], v[0:3]
	v_mfma_f32_16x16x32_bf16 v[24:27], v[178:181], v[212:215], v[16:19]
	v_mfma_f32_16x16x32_bf16 v[4:7], v[140:143], v[238:241], v[4:7]
	v_mfma_f32_16x16x32_bf16 v[0:3], v[178:181], v[238:241], v[0:3]
	s_setprio 0
	s_barrier
	s_add_i32 s58, s58, 2
	s_add_u32 s28, s28, 0x100
	s_addc_u32 s29, s29, 0
	s_add_u32 s56, s56, 0x100
	s_addc_u32 s57, s57, 0
	s_cmp_gt_u32 s58, 13
	s_cbranch_scc0 .LBB0_1024
	s_and_b64 vcc, exec, s[10:11]
	s_cbranch_vccz .LBB0_1027
	s_barrier

.LBB0_1097:
	s_add_u32 s28, s26, 0xfff80080
	s_addc_u32 s29, s27, -1
	s_add_i32 s55, 0, 0x10000
	s_cmp_eq_u32 s54, 28
	s_cselect_b32 s31, s13, s29
	s_cselect_b32 s30, s50, s28
	s_cselect_b32 s29, s11, s53
	s_cselect_b32 s28, s51, s52
	s_add_i32 s58, 0, 0x14000
	v_add_u32_e32 v36, s55, v157
	v_add_u32_e32 v154, s58, v157
	ds_read_b128 v[16:19], v36
	ds_read_b128 v[20:23], v36 offset:1024
	ds_read_b128 v[32:35], v36 offset:2048
	ds_read_b128 v[36:39], v36 offset:3072
	ds_read_b128 v[172:175], v154
	ds_read_b128 v[176:179], v154 offset:1024
	ds_read_b128 v[180:183], v154 offset:2048
	ds_read_b128 v[184:187], v154 offset:3072
	v_lshl_add_u64 v[154:155], s[26:27], 0, v[150:151]
	s_add_i32 m0, s43, 0xc000
	ds_read_b128 v[196:199], v159
	ds_read_b128 v[200:203], v159 offset:1024
	ds_read_b128 v[204:207], v159 offset:2048
	ds_read_b128 v[208:211], v159 offset:3072
	ds_read_b128 v[212:215], v159 offset:4096
	ds_read_b128 v[234:237], v159 offset:5120
	ds_read_b128 v[238:241], v159 offset:6144
	ds_read_b128 v[242:245], v159 offset:7168
	global_load_lds_dwordx4 v[154:155], off
	v_lshl_add_u64 v[154:155], s[26:27], 0, v[152:153]
	s_add_i32 m0, s43, 0xe000
	s_nop 0
	global_load_lds_dwordx4 v[154:155], off
	s_waitcnt vmcnt(8)
	s_waitcnt lgkmcnt(0)
	s_barrier
	s_setprio 1
	s_waitcnt lgkmcnt(0)
	v_mfma_f32_16x16x32_bf16 v[140:143], v[16:19], v[196:199], v[140:143]
	v_mfma_f32_16x16x32_bf16 v[136:139], v[32:35], v[196:199], v[136:139]
	v_mfma_f32_16x16x32_bf16 v[124:127], v[16:19], v[204:207], v[124:127]
	v_mfma_f32_16x16x32_bf16 v[120:123], v[32:35], v[204:207], v[120:123]
	v_mfma_f32_16x16x32_bf16 v[108:111], v[16:19], v[212:215], v[108:111]
	v_mfma_f32_16x16x32_bf16 v[104:107], v[32:35], v[212:215], v[104:107]
	v_mfma_f32_16x16x32_bf16 v[92:95], v[16:19], v[238:241], v[92:95]
	v_mfma_f32_16x16x32_bf16 v[88:91], v[32:35], v[238:241], v[88:91]
	v_mfma_f32_16x16x32_bf16 v[140:143], v[20:23], v[200:203], v[140:143]
	v_mfma_f32_16x16x32_bf16 v[136:139], v[36:39], v[200:203], v[136:139]
	v_mfma_f32_16x16x32_bf16 v[124:127], v[20:23], v[208:211], v[124:127]
	v_mfma_f32_16x16x32_bf16 v[120:123], v[36:39], v[208:211], v[120:123]
	v_mfma_f32_16x16x32_bf16 v[108:111], v[20:23], v[234:237], v[108:111]
	v_mfma_f32_16x16x32_bf16 v[104:107], v[36:39], v[234:237], v[104:107]
	v_mfma_f32_16x16x32_bf16 v[92:95], v[20:23], v[242:245], v[92:95]
	v_mfma_f32_16x16x32_bf16 v[88:91], v[36:39], v[242:245], v[88:91]
	s_setprio 0
	s_setprio 1
	v_mfma_f32_16x16x32_bf16 v[132:135], v[172:175], v[196:199], v[132:135]
	v_mfma_f32_16x16x32_bf16 v[128:131], v[180:183], v[196:199], v[128:131]
	v_mfma_f32_16x16x32_bf16 v[116:119], v[172:175], v[204:207], v[116:119]
	v_mfma_f32_16x16x32_bf16 v[112:115], v[180:183], v[204:207], v[112:115]
	v_mfma_f32_16x16x32_bf16 v[100:103], v[172:175], v[212:215], v[100:103]
	v_mfma_f32_16x16x32_bf16 v[96:99], v[180:183], v[212:215], v[96:99]
	v_mfma_f32_16x16x32_bf16 v[84:87], v[172:175], v[238:241], v[84:87]
	v_mfma_f32_16x16x32_bf16 v[80:83], v[180:183], v[238:241], v[80:83]
	v_mfma_f32_16x16x32_bf16 v[132:135], v[176:179], v[200:203], v[132:135]
	v_mfma_f32_16x16x32_bf16 v[128:131], v[184:187], v[200:203], v[128:131]
	v_mfma_f32_16x16x32_bf16 v[116:119], v[176:179], v[208:211], v[116:119]
	v_mfma_f32_16x16x32_bf16 v[112:115], v[184:187], v[208:211], v[112:115]
	v_mfma_f32_16x16x32_bf16 v[100:103], v[176:179], v[234:237], v[100:103]
	v_mfma_f32_16x16x32_bf16 v[96:99], v[184:187], v[234:237], v[96:99]
	v_mfma_f32_16x16x32_bf16 v[84:87], v[176:179], v[242:245], v[84:87]
	v_mfma_f32_16x16x32_bf16 v[80:83], v[184:187], v[242:245], v[80:83]
	s_setprio 0
	s_barrier
	s_add_i32 s55, s55, s37
	v_lshl_add_u64 v[154:155], s[28:29], 0, v[160:161]
	s_mov_b32 m0, s55
	ds_read_b128 v[196:199], v159 offset:16384
	ds_read_b128 v[200:203], v159 offset:17408
	ds_read_b128 v[204:207], v159 offset:18432
	ds_read_b128 v[208:211], v159 offset:19456
	ds_read_b128 v[212:215], v159 offset:20480
	ds_read_b128 v[234:237], v159 offset:21504
	ds_read_b128 v[238:241], v159 offset:22528
	ds_read_b128 v[242:245], v159 offset:23552
	global_load_lds_dwordx4 v[154:155], off
	s_add_i32 m0, s55, 0x2000
	s_add_u32 s56, s28, 0x80000
	v_lshl_add_u64 v[188:189], s[28:29], 0, v[144:145]
	s_addc_u32 s57, s29, 0
	s_add_i32 s55, s58, s37
	global_load_lds_dwordx4 v[188:189], off
	s_mov_b32 m0, s55
	v_lshl_add_u64 v[246:247], s[30:31], 0, v[146:147]
	global_load_lds_dwordx4 v160, s[56:57]
	s_add_i32 m0, s55, 0x2000
	s_nop 0
	global_load_lds_dwordx4 v144, s[56:57]
	v_lshl_add_u64 v[216:217], s[30:31], 0, v[148:149]
	s_mov_b32 m0, s43
	s_nop 0
	global_load_lds_dwordx4 v[216:217], off
	s_mov_b32 m0, s44
	s_nop 0
	global_load_lds_dwordx4 v[246:247], off
	s_waitcnt vmcnt(8)
	s_waitcnt lgkmcnt(0)
	s_barrier
	s_setprio 1
	s_waitcnt lgkmcnt(0)
	v_mfma_f32_16x16x32_bf16 v[76:79], v[16:19], v[196:199], v[76:79]
	v_mfma_f32_16x16x32_bf16 v[72:75], v[32:35], v[196:199], v[72:75]
	v_mfma_f32_16x16x32_bf16 v[60:63], v[16:19], v[204:207], v[60:63]
	v_mfma_f32_16x16x32_bf16 v[56:59], v[32:35], v[204:207], v[56:59]
	v_mfma_f32_16x16x32_bf16 v[44:47], v[16:19], v[212:215], v[44:47]
	v_mfma_f32_16x16x32_bf16 v[40:43], v[32:35], v[212:215], v[40:43]
	v_mfma_f32_16x16x32_bf16 v[12:15], v[16:19], v[238:241], v[12:15]
	v_mfma_f32_16x16x32_bf16 v[8:11], v[32:35], v[238:241], v[8:11]
	v_mfma_f32_16x16x32_bf16 v[76:79], v[20:23], v[200:203], v[76:79]
	v_mfma_f32_16x16x32_bf16 v[72:75], v[36:39], v[200:203], v[72:75]
	v_mfma_f32_16x16x32_bf16 v[60:63], v[20:23], v[208:211], v[60:63]
	v_mfma_f32_16x16x32_bf16 v[56:59], v[36:39], v[208:211], v[56:59]
	v_mfma_f32_16x16x32_bf16 v[44:47], v[20:23], v[234:237], v[44:47]
	v_mfma_f32_16x16x32_bf16 v[40:43], v[36:39], v[234:237], v[40:43]
	v_mfma_f32_16x16x32_bf16 v[12:15], v[20:23], v[242:245], v[12:15]
	v_mfma_f32_16x16x32_bf16 v[8:11], v[36:39], v[242:245], v[8:11]
	s_setprio 0
	s_setprio 1
	v_mfma_f32_16x16x32_bf16 v[28:31], v[172:175], v[212:215], v[28:31]
	v_mfma_f32_16x16x32_bf16 v[24:27], v[180:183], v[212:215], v[24:27]
	v_mfma_f32_16x16x32_bf16 v[4:7], v[172:175], v[238:241], v[4:7]
	v_mfma_f32_16x16x32_bf16 v[0:3], v[180:183], v[238:241], v[0:3]
	v_mfma_f32_16x16x32_bf16 v[16:19], v[172:175], v[196:199], v[68:71]
	v_mfma_f32_16x16x32_bf16 v[20:23], v[180:183], v[196:199], v[64:67]
	v_mfma_f32_16x16x32_bf16 v[32:35], v[172:175], v[204:207], v[52:55]
	v_mfma_f32_16x16x32_bf16 v[36:39], v[180:183], v[204:207], v[48:51]
	v_mfma_f32_16x16x32_bf16 v[28:31], v[176:179], v[234:237], v[28:31]
	v_mfma_f32_16x16x32_bf16 v[24:27], v[184:187], v[234:237], v[24:27]
	v_mfma_f32_16x16x32_bf16 v[4:7], v[176:179], v[242:245], v[4:7]
	v_mfma_f32_16x16x32_bf16 v[0:3], v[184:187], v[242:245], v[0:3]
	v_mfma_f32_16x16x32_bf16 v[16:19], v[176:179], v[200:203], v[16:19]
	v_mfma_f32_16x16x32_bf16 v[20:23], v[184:187], v[200:203], v[20:23]
	v_mfma_f32_16x16x32_bf16 v[32:35], v[176:179], v[208:211], v[32:35]
	v_mfma_f32_16x16x32_bf16 v[36:39], v[184:187], v[208:211], v[36:39]
	s_setprio 0
	s_barrier
	s_add_i32 s55, 0, 0x18000
	s_add_i32 s56, 0, 0x1c000
	v_add_u32_e32 v68, s55, v157
	v_add_u32_e32 v162, s56, v157
	ds_read_b128 v[48:51], v68
	ds_read_b128 v[52:55], v68 offset:1024
	ds_read_b128 v[64:67], v68 offset:2048
	ds_read_b128 v[68:71], v68 offset:3072
	ds_read_b128 v[172:175], v162
	ds_read_b128 v[176:179], v162 offset:1024
	ds_read_b128 v[180:183], v162 offset:2048
	ds_read_b128 v[184:187], v162 offset:3072
	s_add_u32 s30, s30, 0x80000
	s_addc_u32 s31, s31, 0
	s_mov_b32 m0, s45
	ds_read_b128 v[196:199], v159 offset:32768
	ds_read_b128 v[200:203], v159 offset:33792
	ds_read_b128 v[204:207], v159 offset:34816
	ds_read_b128 v[208:211], v159 offset:35840
	ds_read_b128 v[212:215], v159 offset:36864
	ds_read_b128 v[234:237], v159 offset:37888
	ds_read_b128 v[238:241], v159 offset:38912
	ds_read_b128 v[242:245], v159 offset:39936
	global_load_lds_dwordx4 v148, s[30:31]
	s_mov_b32 m0, s46
	s_nop 0
	global_load_lds_dwordx4 v146, s[30:31]
	s_waitcnt vmcnt(8)
	s_waitcnt lgkmcnt(0)
	s_barrier
	s_setprio 1
	s_waitcnt lgkmcnt(0)
	v_mfma_f32_16x16x32_bf16 v[140:143], v[48:51], v[196:199], v[140:143]
	v_mfma_f32_16x16x32_bf16 v[136:139], v[64:67], v[196:199], v[136:139]
	v_mfma_f32_16x16x32_bf16 v[124:127], v[48:51], v[204:207], v[124:127]
	v_mfma_f32_16x16x32_bf16 v[120:123], v[64:67], v[204:207], v[120:123]
	v_mfma_f32_16x16x32_bf16 v[108:111], v[48:51], v[212:215], v[108:111]
	v_mfma_f32_16x16x32_bf16 v[104:107], v[64:67], v[212:215], v[104:107]
	v_mfma_f32_16x16x32_bf16 v[92:95], v[48:51], v[238:241], v[92:95]
	v_mfma_f32_16x16x32_bf16 v[88:91], v[64:67], v[238:241], v[88:91]
	v_mfma_f32_16x16x32_bf16 v[140:143], v[52:55], v[200:203], v[140:143]
	v_mfma_f32_16x16x32_bf16 v[136:139], v[68:71], v[200:203], v[136:139]
	v_mfma_f32_16x16x32_bf16 v[124:127], v[52:55], v[208:211], v[124:127]
	v_mfma_f32_16x16x32_bf16 v[120:123], v[68:71], v[208:211], v[120:123]
	v_mfma_f32_16x16x32_bf16 v[108:111], v[52:55], v[234:237], v[108:111]
	v_mfma_f32_16x16x32_bf16 v[104:107], v[68:71], v[234:237], v[104:107]
	v_mfma_f32_16x16x32_bf16 v[92:95], v[52:55], v[242:245], v[92:95]
	v_mfma_f32_16x16x32_bf16 v[88:91], v[68:71], v[242:245], v[88:91]
	s_setprio 0
	s_setprio 1
	v_mfma_f32_16x16x32_bf16 v[132:135], v[172:175], v[196:199], v[132:135]
	v_mfma_f32_16x16x32_bf16 v[128:131], v[180:183], v[196:199], v[128:131]
	v_mfma_f32_16x16x32_bf16 v[116:119], v[172:175], v[204:207], v[116:119]
	v_mfma_f32_16x16x32_bf16 v[112:115], v[180:183], v[204:207], v[112:115]
	v_mfma_f32_16x16x32_bf16 v[100:103], v[172:175], v[212:215], v[100:103]
	v_mfma_f32_16x16x32_bf16 v[96:99], v[180:183], v[212:215], v[96:99]
	v_mfma_f32_16x16x32_bf16 v[84:87], v[172:175], v[238:241], v[84:87]
	v_mfma_f32_16x16x32_bf16 v[80:83], v[180:183], v[238:241], v[80:83]
	v_mfma_f32_16x16x32_bf16 v[132:135], v[176:179], v[200:203], v[132:135]
	v_mfma_f32_16x16x32_bf16 v[128:131], v[184:187], v[200:203], v[128:131]
	v_mfma_f32_16x16x32_bf16 v[116:119], v[176:179], v[208:211], v[116:119]
	v_mfma_f32_16x16x32_bf16 v[112:115], v[184:187], v[208:211], v[112:115]
	v_mfma_f32_16x16x32_bf16 v[100:103], v[176:179], v[234:237], v[100:103]
	v_mfma_f32_16x16x32_bf16 v[96:99], v[184:187], v[234:237], v[96:99]
	v_mfma_f32_16x16x32_bf16 v[84:87], v[176:179], v[242:245], v[84:87]
	v_mfma_f32_16x16x32_bf16 v[80:83], v[184:187], v[242:245], v[80:83]
	s_setprio 0
	s_barrier
	s_add_i32 s30, s55, s37
	v_lshl_add_u64 v[154:155], v[154:155], 0, s[20:21]
	s_mov_b32 m0, s30
	ds_read_b128 v[196:199], v159 offset:49152
	ds_read_b128 v[200:203], v159 offset:50176
	ds_read_b128 v[204:207], v159 offset:51200
	ds_read_b128 v[208:211], v159 offset:52224
	ds_read_b128 v[212:215], v159 offset:53248
	ds_read_b128 v[234:237], v159 offset:54272
	ds_read_b128 v[238:241], v159 offset:55296
	ds_read_b128 v[242:245], v159 offset:56320
	global_load_lds_dwordx4 v[154:155], off
	s_add_i32 m0, s30, 0x2000
	s_add_u32 s28, s28, 0x80080
	v_lshl_add_u64 v[154:155], v[188:189], 0, s[20:21]
	s_addc_u32 s29, s29, 0
	s_add_i32 s30, s56, s37
	global_load_lds_dwordx4 v[154:155], off
	v_lshl_add_u64 v[154:155], s[28:29], 0, v[160:161]
	s_mov_b32 m0, s30
	s_nop 0
	global_load_lds_dwordx4 v[154:155], off
	v_lshl_add_u64 v[154:155], s[28:29], 0, v[144:145]
	s_add_i32 m0, s30, 0x2000
	s_nop 0
	global_load_lds_dwordx4 v[154:155], off
	v_lshl_add_u64 v[154:155], v[216:217], 0, s[20:21]
	s_mov_b32 m0, s47
	s_nop 0
	global_load_lds_dwordx4 v[154:155], off
	v_lshl_add_u64 v[154:155], v[246:247], 0, s[20:21]
	s_mov_b32 m0, s48
	s_nop 0
	global_load_lds_dwordx4 v[154:155], off
	s_waitcnt vmcnt(8)
	s_waitcnt lgkmcnt(0)
	s_barrier
	s_setprio 1
	s_waitcnt lgkmcnt(0)
	v_mfma_f32_16x16x32_bf16 v[76:79], v[48:51], v[196:199], v[76:79]
	v_mfma_f32_16x16x32_bf16 v[72:75], v[64:67], v[196:199], v[72:75]
	v_mfma_f32_16x16x32_bf16 v[60:63], v[48:51], v[204:207], v[60:63]
	v_mfma_f32_16x16x32_bf16 v[56:59], v[64:67], v[204:207], v[56:59]
	v_mfma_f32_16x16x32_bf16 v[44:47], v[48:51], v[212:215], v[44:47]
	v_mfma_f32_16x16x32_bf16 v[40:43], v[64:67], v[212:215], v[40:43]
	v_mfma_f32_16x16x32_bf16 v[12:15], v[48:51], v[238:241], v[12:15]
	v_mfma_f32_16x16x32_bf16 v[8:11], v[64:67], v[238:241], v[8:11]
	v_mfma_f32_16x16x32_bf16 v[76:79], v[52:55], v[200:203], v[76:79]
	v_mfma_f32_16x16x32_bf16 v[72:75], v[68:71], v[200:203], v[72:75]
	v_mfma_f32_16x16x32_bf16 v[60:63], v[52:55], v[208:211], v[60:63]
	v_mfma_f32_16x16x32_bf16 v[56:59], v[68:71], v[208:211], v[56:59]
	v_mfma_f32_16x16x32_bf16 v[44:47], v[52:55], v[234:237], v[44:47]
	v_mfma_f32_16x16x32_bf16 v[40:43], v[68:71], v[234:237], v[40:43]
	v_mfma_f32_16x16x32_bf16 v[12:15], v[52:55], v[242:245], v[12:15]
	v_mfma_f32_16x16x32_bf16 v[8:11], v[68:71], v[242:245], v[8:11]
	s_setprio 0
	s_setprio 1
	v_mfma_f32_16x16x32_bf16 v[16:19], v[172:175], v[196:199], v[16:19]
	v_mfma_f32_16x16x32_bf16 v[68:71], v[176:179], v[200:203], v[16:19]
	v_mfma_f32_16x16x32_bf16 v[16:19], v[180:183], v[196:199], v[20:23]
	v_mfma_f32_16x16x32_bf16 v[64:67], v[184:187], v[200:203], v[16:19]
	v_mfma_f32_16x16x32_bf16 v[16:19], v[172:175], v[204:207], v[32:35]
	v_mfma_f32_16x16x32_bf16 v[52:55], v[176:179], v[208:211], v[16:19]
	v_mfma_f32_16x16x32_bf16 v[16:19], v[180:183], v[204:207], v[36:39]
	v_mfma_f32_16x16x32_bf16 v[48:51], v[184:187], v[208:211], v[16:19]
	v_mfma_f32_16x16x32_bf16 v[16:19], v[172:175], v[212:215], v[28:31]
	v_mfma_f32_16x16x32_bf16 v[28:31], v[176:179], v[234:237], v[16:19]
	v_mfma_f32_16x16x32_bf16 v[16:19], v[180:183], v[212:215], v[24:27]
	v_mfma_f32_16x16x32_bf16 v[4:7], v[172:175], v[238:241], v[4:7]
	v_mfma_f32_16x16x32_bf16 v[0:3], v[180:183], v[238:241], v[0:3]
	v_mfma_f32_16x16x32_bf16 v[24:27], v[184:187], v[234:237], v[16:19]
	v_mfma_f32_16x16x32_bf16 v[4:7], v[176:179], v[242:245], v[4:7]
	v_mfma_f32_16x16x32_bf16 v[0:3], v[184:187], v[242:245], v[0:3]
	s_setprio 0
	s_barrier
	s_add_i32 s54, s54, 2
	s_add_u32 s26, s26, 0x100
	s_addc_u32 s27, s27, 0
	s_add_u32 s52, s52, 0x100
	s_addc_u32 s53, s53, 0
	s_cmp_gt_u32 s54, 29
	s_cbranch_scc0 .LBB0_1097
	s_and_b64 vcc, exec, s[8:9]
	s_cbranch_vccz .LBB0_1100
	s_barrier

.LBB0_1176:
	s_add_u32 s34, s4, 0xfffc0080
	s_addc_u32 s35, s5, -1
	s_add_i32 s55, 0, 0x10000
	s_cmp_eq_u32 s31, 12
	s_cselect_b32 s37, s19, s35
	s_cselect_b32 s36, s18, s34
	s_cselect_b32 s35, s13, s29
	s_cselect_b32 s34, s15, s17
	s_add_i32 s58, 0, 0x14000
	v_add_u32_e32 v88, s55, v192
	v_add_u32_e32 v156, s58, v192
	ds_read_b128 v[64:67], v88
	ds_read_b128 v[68:71], v88 offset:1024
	ds_read_b128 v[80:83], v88 offset:2048
	ds_read_b128 v[88:91], v88 offset:3072
	ds_read_b128 v[144:147], v156
	ds_read_b128 v[148:151], v156 offset:1024
	ds_read_b128 v[152:155], v156 offset:2048
	ds_read_b128 v[156:159], v156 offset:3072
	s_add_i32 m0, s45, 0xc000
	ds_read_b128 v[182:185], v197
	ds_read_b128 v[186:189], v197 offset:1024
	ds_read_b128 v[198:201], v197 offset:2048
	ds_read_b128 v[202:205], v197 offset:3072
	ds_read_b128 v[206:209], v197 offset:4096
	ds_read_b128 v[210:213], v197 offset:5120
	ds_read_b128 v[234:237], v197 offset:6144
	ds_read_b128 v[238:241], v197 offset:7168
	global_load_lds_dwordx4 v178, s[4:5]
	s_add_i32 m0, s45, 0xe000
	s_nop 0
	global_load_lds_dwordx4 v180, s[4:5]
	s_waitcnt vmcnt(8)
	s_waitcnt lgkmcnt(0)
	s_barrier
	s_setprio 1
	s_waitcnt lgkmcnt(0)
	v_mfma_f32_16x16x32_bf16 v[140:143], v[64:67], v[182:185], v[140:143]
	v_mfma_f32_16x16x32_bf16 v[136:139], v[80:83], v[182:185], v[136:139]
	v_mfma_f32_16x16x32_bf16 v[124:127], v[64:67], v[198:201], v[124:127]
	v_mfma_f32_16x16x32_bf16 v[120:123], v[80:83], v[198:201], v[120:123]
	v_mfma_f32_16x16x32_bf16 v[108:111], v[64:67], v[206:209], v[108:111]
	v_mfma_f32_16x16x32_bf16 v[104:107], v[80:83], v[206:209], v[104:107]
	v_mfma_f32_16x16x32_bf16 v[92:95], v[64:67], v[234:237], v[92:95]
	v_mfma_f32_16x16x32_bf16 v[84:87], v[80:83], v[234:237], v[84:87]
	v_mfma_f32_16x16x32_bf16 v[140:143], v[68:71], v[186:189], v[140:143]
	v_mfma_f32_16x16x32_bf16 v[136:139], v[88:91], v[186:189], v[136:139]
	v_mfma_f32_16x16x32_bf16 v[124:127], v[68:71], v[202:205], v[124:127]
	v_mfma_f32_16x16x32_bf16 v[120:123], v[88:91], v[202:205], v[120:123]
	v_mfma_f32_16x16x32_bf16 v[108:111], v[68:71], v[210:213], v[108:111]
	v_mfma_f32_16x16x32_bf16 v[104:107], v[88:91], v[210:213], v[104:107]
	v_mfma_f32_16x16x32_bf16 v[92:95], v[68:71], v[238:241], v[92:95]
	v_mfma_f32_16x16x32_bf16 v[84:87], v[88:91], v[238:241], v[84:87]
	s_setprio 0
	s_setprio 1
	v_mfma_f32_16x16x32_bf16 v[132:135], v[144:147], v[182:185], v[132:135]
	v_mfma_f32_16x16x32_bf16 v[128:131], v[152:155], v[182:185], v[128:131]
	v_mfma_f32_16x16x32_bf16 v[116:119], v[144:147], v[198:201], v[116:119]
	v_mfma_f32_16x16x32_bf16 v[112:115], v[152:155], v[198:201], v[112:115]
	v_mfma_f32_16x16x32_bf16 v[100:103], v[144:147], v[206:209], v[100:103]
	v_mfma_f32_16x16x32_bf16 v[96:99], v[152:155], v[206:209], v[96:99]
	v_mfma_f32_16x16x32_bf16 v[76:79], v[144:147], v[234:237], v[76:79]
	v_mfma_f32_16x16x32_bf16 v[72:75], v[152:155], v[234:237], v[72:75]
	v_mfma_f32_16x16x32_bf16 v[132:135], v[148:151], v[186:189], v[132:135]
	v_mfma_f32_16x16x32_bf16 v[128:131], v[156:159], v[186:189], v[128:131]
	v_mfma_f32_16x16x32_bf16 v[116:119], v[148:151], v[202:205], v[116:119]
	v_mfma_f32_16x16x32_bf16 v[112:115], v[156:159], v[202:205], v[112:115]
	v_mfma_f32_16x16x32_bf16 v[100:103], v[148:151], v[210:213], v[100:103]
	v_mfma_f32_16x16x32_bf16 v[96:99], v[156:159], v[210:213], v[96:99]
	v_mfma_f32_16x16x32_bf16 v[76:79], v[148:151], v[238:241], v[76:79]
	v_mfma_f32_16x16x32_bf16 v[72:75], v[156:159], v[238:241], v[72:75]
	s_setprio 0
	s_barrier
	s_add_i32 s55, s55, s44
	v_lshl_add_u64 v[214:215], s[34:35], 0, v[160:161]
	s_mov_b32 m0, s55
	ds_read_b128 v[182:185], v197 offset:16384
	ds_read_b128 v[186:189], v197 offset:17408
	ds_read_b128 v[198:201], v197 offset:18432
	ds_read_b128 v[202:205], v197 offset:19456
	ds_read_b128 v[206:209], v197 offset:20480
	ds_read_b128 v[210:213], v197 offset:21504
	ds_read_b128 v[234:237], v197 offset:22528
	ds_read_b128 v[238:241], v197 offset:23552
	global_load_lds_dwordx4 v[214:215], off
	s_add_i32 m0, s55, 0x2000
	s_add_u32 s56, s34, 0x40000
	v_lshl_add_u64 v[216:217], s[34:35], 0, v[176:177]
	s_addc_u32 s57, s35, 0
	s_add_i32 s55, s58, s44
	global_load_lds_dwordx4 v[216:217], off
	s_mov_b32 m0, s55
	v_lshl_add_u64 v[244:245], s[36:37], 0, v[174:175]
	global_load_lds_dwordx4 v160, s[56:57]
	s_add_i32 m0, s55, 0x2000
	s_nop 0
	global_load_lds_dwordx4 v176, s[56:57]
	v_lshl_add_u64 v[242:243], s[36:37], 0, v[172:173]
	s_mov_b32 m0, s45
	s_nop 0
	global_load_lds_dwordx4 v[242:243], off
	s_mov_b32 m0, s46
	s_nop 0
	global_load_lds_dwordx4 v[244:245], off
	s_waitcnt vmcnt(8)
	s_waitcnt lgkmcnt(0)
	s_barrier
	s_setprio 1
	s_waitcnt lgkmcnt(0)
	v_mfma_f32_16x16x32_bf16 v[60:63], v[64:67], v[182:185], v[60:63]
	v_mfma_f32_16x16x32_bf16 v[56:59], v[80:83], v[182:185], v[56:59]
	v_mfma_f32_16x16x32_bf16 v[44:47], v[64:67], v[198:201], v[44:47]
	v_mfma_f32_16x16x32_bf16 v[40:43], v[80:83], v[198:201], v[40:43]
	v_mfma_f32_16x16x32_bf16 v[28:31], v[64:67], v[206:209], v[28:31]
	v_mfma_f32_16x16x32_bf16 v[24:27], v[80:83], v[206:209], v[24:27]
	v_mfma_f32_16x16x32_bf16 v[12:15], v[64:67], v[234:237], v[12:15]
	v_mfma_f32_16x16x32_bf16 v[8:11], v[80:83], v[234:237], v[8:11]
	v_mfma_f32_16x16x32_bf16 v[60:63], v[68:71], v[186:189], v[60:63]
	v_mfma_f32_16x16x32_bf16 v[56:59], v[88:91], v[186:189], v[56:59]
	v_mfma_f32_16x16x32_bf16 v[44:47], v[68:71], v[202:205], v[44:47]
	v_mfma_f32_16x16x32_bf16 v[40:43], v[88:91], v[202:205], v[40:43]
	v_mfma_f32_16x16x32_bf16 v[28:31], v[68:71], v[210:213], v[28:31]
	v_mfma_f32_16x16x32_bf16 v[24:27], v[88:91], v[210:213], v[24:27]
	v_mfma_f32_16x16x32_bf16 v[12:15], v[68:71], v[238:241], v[12:15]
	v_mfma_f32_16x16x32_bf16 v[8:11], v[88:91], v[238:241], v[8:11]
	s_setprio 0
	s_setprio 1
	v_mfma_f32_16x16x32_bf16 v[52:55], v[144:147], v[182:185], v[52:55]
	v_mfma_f32_16x16x32_bf16 v[48:51], v[152:155], v[182:185], v[48:51]
	v_mfma_f32_16x16x32_bf16 v[36:39], v[144:147], v[198:201], v[36:39]
	v_mfma_f32_16x16x32_bf16 v[32:35], v[152:155], v[198:201], v[32:35]
	v_mfma_f32_16x16x32_bf16 v[20:23], v[144:147], v[206:209], v[20:23]
	v_mfma_f32_16x16x32_bf16 v[16:19], v[152:155], v[206:209], v[16:19]
	v_mfma_f32_16x16x32_bf16 v[4:7], v[144:147], v[234:237], v[4:7]
	v_mfma_f32_16x16x32_bf16 v[0:3], v[152:155], v[234:237], v[0:3]
	v_mfma_f32_16x16x32_bf16 v[52:55], v[148:151], v[186:189], v[52:55]
	v_mfma_f32_16x16x32_bf16 v[48:51], v[156:159], v[186:189], v[48:51]
	v_mfma_f32_16x16x32_bf16 v[36:39], v[148:151], v[202:205], v[36:39]
	v_mfma_f32_16x16x32_bf16 v[32:35], v[156:159], v[202:205], v[32:35]
	v_mfma_f32_16x16x32_bf16 v[20:23], v[148:151], v[210:213], v[20:23]
	v_mfma_f32_16x16x32_bf16 v[16:19], v[156:159], v[210:213], v[16:19]
	v_mfma_f32_16x16x32_bf16 v[4:7], v[148:151], v[238:241], v[4:7]
	v_mfma_f32_16x16x32_bf16 v[0:3], v[156:159], v[238:241], v[0:3]
	s_setprio 0
	s_barrier
	s_add_i32 s55, 0, 0x18000
	s_add_i32 s56, 0, 0x1c000
	v_add_u32_e32 v88, s55, v192
	v_add_u32_e32 v156, s56, v192
	ds_read_b128 v[64:67], v88
	ds_read_b128 v[68:71], v88 offset:1024
	ds_read_b128 v[80:83], v88 offset:2048
	ds_read_b128 v[88:91], v88 offset:3072
	ds_read_b128 v[144:147], v156
	ds_read_b128 v[148:151], v156 offset:1024
	ds_read_b128 v[152:155], v156 offset:2048
	ds_read_b128 v[156:159], v156 offset:3072
	s_add_u32 s36, s36, 0x40000
	s_addc_u32 s37, s37, 0
	s_mov_b32 m0, s47
	ds_read_b128 v[182:185], v197 offset:32768
	ds_read_b128 v[186:189], v197 offset:33792
	ds_read_b128 v[198:201], v197 offset:34816
	ds_read_b128 v[202:205], v197 offset:35840
	ds_read_b128 v[206:209], v197 offset:36864
	ds_read_b128 v[210:213], v197 offset:37888
	ds_read_b128 v[234:237], v197 offset:38912
	ds_read_b128 v[238:241], v197 offset:39936
	global_load_lds_dwordx4 v172, s[36:37]
	s_mov_b32 m0, s48
	s_nop 0
	global_load_lds_dwordx4 v174, s[36:37]
	s_waitcnt vmcnt(8)
	s_waitcnt lgkmcnt(0)
	s_barrier
	s_setprio 1
	s_waitcnt lgkmcnt(0)
	v_mfma_f32_16x16x32_bf16 v[140:143], v[64:67], v[182:185], v[140:143]
	v_mfma_f32_16x16x32_bf16 v[136:139], v[80:83], v[182:185], v[136:139]
	v_mfma_f32_16x16x32_bf16 v[124:127], v[64:67], v[198:201], v[124:127]
	v_mfma_f32_16x16x32_bf16 v[120:123], v[80:83], v[198:201], v[120:123]
	v_mfma_f32_16x16x32_bf16 v[108:111], v[64:67], v[206:209], v[108:111]
	v_mfma_f32_16x16x32_bf16 v[104:107], v[80:83], v[206:209], v[104:107]
	v_mfma_f32_16x16x32_bf16 v[92:95], v[64:67], v[234:237], v[92:95]
	v_mfma_f32_16x16x32_bf16 v[84:87], v[80:83], v[234:237], v[84:87]
	v_mfma_f32_16x16x32_bf16 v[140:143], v[68:71], v[186:189], v[140:143]
	v_mfma_f32_16x16x32_bf16 v[136:139], v[88:91], v[186:189], v[136:139]
	v_mfma_f32_16x16x32_bf16 v[124:127], v[68:71], v[202:205], v[124:127]
	v_mfma_f32_16x16x32_bf16 v[120:123], v[88:91], v[202:205], v[120:123]
	v_mfma_f32_16x16x32_bf16 v[108:111], v[68:71], v[210:213], v[108:111]
	v_mfma_f32_16x16x32_bf16 v[104:107], v[88:91], v[210:213], v[104:107]
	v_mfma_f32_16x16x32_bf16 v[92:95], v[68:71], v[238:241], v[92:95]
	v_mfma_f32_16x16x32_bf16 v[84:87], v[88:91], v[238:241], v[84:87]
	s_setprio 0
	s_setprio 1
	v_mfma_f32_16x16x32_bf16 v[132:135], v[144:147], v[182:185], v[132:135]
	v_mfma_f32_16x16x32_bf16 v[128:131], v[152:155], v[182:185], v[128:131]
	v_mfma_f32_16x16x32_bf16 v[116:119], v[144:147], v[198:201], v[116:119]
	v_mfma_f32_16x16x32_bf16 v[112:115], v[152:155], v[198:201], v[112:115]
	v_mfma_f32_16x16x32_bf16 v[100:103], v[144:147], v[206:209], v[100:103]
	v_mfma_f32_16x16x32_bf16 v[96:99], v[152:155], v[206:209], v[96:99]
	v_mfma_f32_16x16x32_bf16 v[76:79], v[144:147], v[234:237], v[76:79]
	v_mfma_f32_16x16x32_bf16 v[72:75], v[152:155], v[234:237], v[72:75]
	v_mfma_f32_16x16x32_bf16 v[132:135], v[148:151], v[186:189], v[132:135]
	v_mfma_f32_16x16x32_bf16 v[128:131], v[156:159], v[186:189], v[128:131]
	v_mfma_f32_16x16x32_bf16 v[116:119], v[148:151], v[202:205], v[116:119]
	v_mfma_f32_16x16x32_bf16 v[112:115], v[156:159], v[202:205], v[112:115]
	v_mfma_f32_16x16x32_bf16 v[100:103], v[148:151], v[210:213], v[100:103]
	v_mfma_f32_16x16x32_bf16 v[96:99], v[156:159], v[210:213], v[96:99]
	v_mfma_f32_16x16x32_bf16 v[76:79], v[148:151], v[238:241], v[76:79]
	v_mfma_f32_16x16x32_bf16 v[72:75], v[156:159], v[238:241], v[72:75]
	s_setprio 0
	s_barrier
	s_add_i32 s36, s55, s44
	v_lshl_add_u64 v[214:215], v[214:215], 0, s[20:21]
	s_mov_b32 m0, s36
	ds_read_b128 v[182:185], v197 offset:49152
	ds_read_b128 v[186:189], v197 offset:50176
	ds_read_b128 v[198:201], v197 offset:51200
	ds_read_b128 v[202:205], v197 offset:52224
	ds_read_b128 v[206:209], v197 offset:53248
	ds_read_b128 v[210:213], v197 offset:54272
	ds_read_b128 v[234:237], v197 offset:55296
	ds_read_b128 v[238:241], v197 offset:56320
	global_load_lds_dwordx4 v[214:215], off
	s_add_i32 m0, s36, 0x2000
	s_add_u32 s34, s34, 0x40080
	v_lshl_add_u64 v[214:215], v[216:217], 0, s[20:21]
	s_addc_u32 s35, s35, 0
	s_add_i32 s36, s56, s44
	global_load_lds_dwordx4 v[214:215], off
	s_mov_b32 m0, s36
	s_nop 0
	global_load_lds_dwordx4 v160, s[34:35]
	s_add_i32 m0, s36, 0x2000
	s_nop 0
	global_load_lds_dwordx4 v176, s[34:35]
	v_lshl_add_u64 v[214:215], v[242:243], 0, s[20:21]
	s_mov_b32 m0, s51
	s_nop 0
	global_load_lds_dwordx4 v[214:215], off
	v_lshl_add_u64 v[214:215], v[244:245], 0, s[20:21]
	s_mov_b32 m0, s52
	s_nop 0
	global_load_lds_dwordx4 v[214:215], off
	s_waitcnt vmcnt(8)
	s_waitcnt lgkmcnt(0)
	s_barrier
	s_setprio 1
	s_waitcnt lgkmcnt(0)
	v_mfma_f32_16x16x32_bf16 v[60:63], v[64:67], v[182:185], v[60:63]
	v_mfma_f32_16x16x32_bf16 v[56:59], v[80:83], v[182:185], v[56:59]
	v_mfma_f32_16x16x32_bf16 v[44:47], v[64:67], v[198:201], v[44:47]
	v_mfma_f32_16x16x32_bf16 v[40:43], v[80:83], v[198:201], v[40:43]
	v_mfma_f32_16x16x32_bf16 v[28:31], v[64:67], v[206:209], v[28:31]
	v_mfma_f32_16x16x32_bf16 v[24:27], v[80:83], v[206:209], v[24:27]
	v_mfma_f32_16x16x32_bf16 v[12:15], v[64:67], v[234:237], v[12:15]
	v_mfma_f32_16x16x32_bf16 v[8:11], v[80:83], v[234:237], v[8:11]
	v_mfma_f32_16x16x32_bf16 v[60:63], v[68:71], v[186:189], v[60:63]
	v_mfma_f32_16x16x32_bf16 v[56:59], v[88:91], v[186:189], v[56:59]
	v_mfma_f32_16x16x32_bf16 v[44:47], v[68:71], v[202:205], v[44:47]
	v_mfma_f32_16x16x32_bf16 v[40:43], v[88:91], v[202:205], v[40:43]
	v_mfma_f32_16x16x32_bf16 v[28:31], v[68:71], v[210:213], v[28:31]
	v_mfma_f32_16x16x32_bf16 v[24:27], v[88:91], v[210:213], v[24:27]
	v_mfma_f32_16x16x32_bf16 v[12:15], v[68:71], v[238:241], v[12:15]
	v_mfma_f32_16x16x32_bf16 v[8:11], v[88:91], v[238:241], v[8:11]
	s_setprio 0
	s_setprio 1
	v_mfma_f32_16x16x32_bf16 v[52:55], v[144:147], v[182:185], v[52:55]
	v_mfma_f32_16x16x32_bf16 v[48:51], v[152:155], v[182:185], v[48:51]
	v_mfma_f32_16x16x32_bf16 v[36:39], v[144:147], v[198:201], v[36:39]
	v_mfma_f32_16x16x32_bf16 v[32:35], v[152:155], v[198:201], v[32:35]
	v_mfma_f32_16x16x32_bf16 v[20:23], v[144:147], v[206:209], v[20:23]
	v_mfma_f32_16x16x32_bf16 v[16:19], v[152:155], v[206:209], v[16:19]
	v_mfma_f32_16x16x32_bf16 v[4:7], v[144:147], v[234:237], v[4:7]
	v_mfma_f32_16x16x32_bf16 v[0:3], v[152:155], v[234:237], v[0:3]
	v_mfma_f32_16x16x32_bf16 v[52:55], v[148:151], v[186:189], v[52:55]
	v_mfma_f32_16x16x32_bf16 v[48:51], v[156:159], v[186:189], v[48:51]
	v_mfma_f32_16x16x32_bf16 v[36:39], v[148:151], v[202:205], v[36:39]
	v_mfma_f32_16x16x32_bf16 v[32:35], v[156:159], v[202:205], v[32:35]
	v_mfma_f32_16x16x32_bf16 v[20:23], v[148:151], v[210:213], v[20:23]
	v_mfma_f32_16x16x32_bf16 v[16:19], v[156:159], v[210:213], v[16:19]
	v_mfma_f32_16x16x32_bf16 v[4:7], v[148:151], v[238:241], v[4:7]
	v_mfma_f32_16x16x32_bf16 v[0:3], v[156:159], v[238:241], v[0:3]
	s_setprio 0
	s_barrier
	s_add_i32 s31, s31, 2
	s_add_u32 s4, s4, 0x100
	s_addc_u32 s5, s5, 0
	s_add_u32 s17, s17, 0x100
	s_addc_u32 s29, s29, 0
	s_cmp_gt_u32 s31, 13
	s_cbranch_scc0 .LBB0_1176
	s_and_b64 vcc, exec, s[10:11]
	s_cbranch_vccz .LBB0_1179
	s_barrier

.LBB0_1314:
	s_add_u32 s28, s26, 0xfff80080
	s_addc_u32 s29, s27, -1
	s_add_i32 s52, 0, 0x10000
	s_cmp_eq_u32 s51, 28
	s_cselect_b32 s31, s15, s29
	s_cselect_b32 s30, s47, s28
	s_cselect_b32 s29, s13, s50
	s_cselect_b32 s28, s48, s49
	s_add_i32 s54, 0, 0x14000
	v_add_u32_e32 v140, s52, v157
	v_add_u32_e32 v154, s54, v157
	ds_read_b128 v[128:131], v140
	ds_read_b128 v[132:135], v140 offset:1024
	ds_read_b128 v[136:139], v140 offset:2048
	ds_read_b128 v[140:143], v140 offset:3072
	ds_read_b128 v[172:175], v154
	ds_read_b128 v[176:179], v154 offset:1024
	ds_read_b128 v[180:183], v154 offset:2048
	ds_read_b128 v[184:187], v154 offset:3072
	s_add_i32 m0, s39, 0xc000
	ds_read_b128 v[196:199], v159
	ds_read_b128 v[200:203], v159 offset:1024
	ds_read_b128 v[204:207], v159 offset:2048
	ds_read_b128 v[208:211], v159 offset:3072
	ds_read_b128 v[212:215], v159 offset:4096
	ds_read_b128 v[234:237], v159 offset:5120
	ds_read_b128 v[238:241], v159 offset:6144
	ds_read_b128 v[242:245], v159 offset:7168
	global_load_lds_dwordx4 v150, s[26:27]
	s_add_i32 m0, s39, 0xe000
	s_nop 0
	global_load_lds_dwordx4 v152, s[26:27]
	s_waitcnt vmcnt(8)
	s_waitcnt lgkmcnt(0)
	s_barrier
	s_setprio 1
	s_waitcnt lgkmcnt(0)
	v_mfma_f32_16x16x32_bf16 v[124:127], v[128:131], v[196:199], v[124:127]
	v_mfma_f32_16x16x32_bf16 v[120:123], v[136:139], v[196:199], v[120:123]
	v_mfma_f32_16x16x32_bf16 v[112:115], v[128:131], v[204:207], v[112:115]
	v_mfma_f32_16x16x32_bf16 v[104:107], v[136:139], v[204:207], v[104:107]
	v_mfma_f32_16x16x32_bf16 v[92:95], v[128:131], v[212:215], v[92:95]
	v_mfma_f32_16x16x32_bf16 v[88:91], v[136:139], v[212:215], v[88:91]
	v_mfma_f32_16x16x32_bf16 v[80:83], v[128:131], v[238:241], v[80:83]
	v_mfma_f32_16x16x32_bf16 v[72:75], v[136:139], v[238:241], v[72:75]
	v_mfma_f32_16x16x32_bf16 v[124:127], v[132:135], v[200:203], v[124:127]
	v_mfma_f32_16x16x32_bf16 v[120:123], v[140:143], v[200:203], v[120:123]
	v_mfma_f32_16x16x32_bf16 v[112:115], v[132:135], v[208:211], v[112:115]
	v_mfma_f32_16x16x32_bf16 v[104:107], v[140:143], v[208:211], v[104:107]
	v_mfma_f32_16x16x32_bf16 v[92:95], v[132:135], v[234:237], v[92:95]
	v_mfma_f32_16x16x32_bf16 v[88:91], v[140:143], v[234:237], v[88:91]
	v_mfma_f32_16x16x32_bf16 v[80:83], v[132:135], v[242:245], v[80:83]
	v_mfma_f32_16x16x32_bf16 v[72:75], v[140:143], v[242:245], v[72:75]
	s_setprio 0
	s_setprio 1
	v_mfma_f32_16x16x32_bf16 v[116:119], v[172:175], v[196:199], v[116:119]
	v_mfma_f32_16x16x32_bf16 v[108:111], v[180:183], v[196:199], v[108:111]
	v_mfma_f32_16x16x32_bf16 v[100:103], v[172:175], v[204:207], v[100:103]
	v_mfma_f32_16x16x32_bf16 v[96:99], v[180:183], v[204:207], v[96:99]
	v_mfma_f32_16x16x32_bf16 v[84:87], v[172:175], v[212:215], v[84:87]
	v_mfma_f32_16x16x32_bf16 v[76:79], v[180:183], v[212:215], v[76:79]
	v_mfma_f32_16x16x32_bf16 v[68:71], v[172:175], v[238:241], v[68:71]
	v_mfma_f32_16x16x32_bf16 v[64:67], v[180:183], v[238:241], v[64:67]
	v_mfma_f32_16x16x32_bf16 v[116:119], v[176:179], v[200:203], v[116:119]
	v_mfma_f32_16x16x32_bf16 v[108:111], v[184:187], v[200:203], v[108:111]
	v_mfma_f32_16x16x32_bf16 v[100:103], v[176:179], v[208:211], v[100:103]
	v_mfma_f32_16x16x32_bf16 v[96:99], v[184:187], v[208:211], v[96:99]
	v_mfma_f32_16x16x32_bf16 v[84:87], v[176:179], v[234:237], v[84:87]
	v_mfma_f32_16x16x32_bf16 v[76:79], v[184:187], v[234:237], v[76:79]
	v_mfma_f32_16x16x32_bf16 v[68:71], v[176:179], v[242:245], v[68:71]
	v_mfma_f32_16x16x32_bf16 v[64:67], v[184:187], v[242:245], v[64:67]
	s_setprio 0
	s_barrier
	s_add_i32 s52, s52, s37
	v_lshl_add_u64 v[154:155], s[28:29], 0, v[160:161]
	s_mov_b32 m0, s52
	ds_read_b128 v[196:199], v159 offset:16384
	ds_read_b128 v[200:203], v159 offset:17408
	ds_read_b128 v[204:207], v159 offset:18432
	ds_read_b128 v[208:211], v159 offset:19456
	ds_read_b128 v[212:215], v159 offset:20480
	ds_read_b128 v[234:237], v159 offset:21504
	ds_read_b128 v[238:241], v159 offset:22528
	ds_read_b128 v[242:245], v159 offset:23552
	global_load_lds_dwordx4 v[154:155], off
	s_add_i32 m0, s52, 0x2000
	s_add_u32 s52, s28, 0x80000
	v_lshl_add_u64 v[188:189], s[28:29], 0, v[144:145]
	s_addc_u32 s53, s29, 0
	s_add_i32 s54, s54, s37
	global_load_lds_dwordx4 v[188:189], off
	v_lshl_add_u64 v[216:217], s[52:53], 0, v[160:161]
	s_mov_b32 m0, s54
	v_lshl_add_u64 v[246:247], s[30:31], 0, v[146:147]
	global_load_lds_dwordx4 v[216:217], off
	v_lshl_add_u64 v[216:217], s[52:53], 0, v[144:145]
	s_add_i32 m0, s54, 0x2000
	s_nop 0
	global_load_lds_dwordx4 v[216:217], off
	v_lshl_add_u64 v[216:217], s[30:31], 0, v[148:149]
	s_mov_b32 m0, s39
	s_nop 0
	global_load_lds_dwordx4 v[216:217], off
	s_mov_b32 m0, s41
	s_nop 0
	global_load_lds_dwordx4 v[246:247], off
	s_waitcnt vmcnt(8)
	s_waitcnt lgkmcnt(0)
	s_barrier
	s_setprio 1
	s_waitcnt lgkmcnt(0)
	v_mfma_f32_16x16x32_bf16 v[60:63], v[128:131], v[196:199], v[60:63]
	v_mfma_f32_16x16x32_bf16 v[56:59], v[136:139], v[196:199], v[56:59]
	v_mfma_f32_16x16x32_bf16 v[48:51], v[128:131], v[204:207], v[48:51]
	v_mfma_f32_16x16x32_bf16 v[40:43], v[136:139], v[204:207], v[40:43]
	v_mfma_f32_16x16x32_bf16 v[28:31], v[128:131], v[212:215], v[28:31]
	v_mfma_f32_16x16x32_bf16 v[24:27], v[136:139], v[212:215], v[24:27]
	v_mfma_f32_16x16x32_bf16 v[16:19], v[128:131], v[238:241], v[16:19]
	v_mfma_f32_16x16x32_bf16 v[8:11], v[136:139], v[238:241], v[8:11]
	v_mfma_f32_16x16x32_bf16 v[60:63], v[132:135], v[200:203], v[60:63]
	v_mfma_f32_16x16x32_bf16 v[56:59], v[140:143], v[200:203], v[56:59]
	v_mfma_f32_16x16x32_bf16 v[48:51], v[132:135], v[208:211], v[48:51]
	v_mfma_f32_16x16x32_bf16 v[40:43], v[140:143], v[208:211], v[40:43]
	v_mfma_f32_16x16x32_bf16 v[28:31], v[132:135], v[234:237], v[28:31]
	v_mfma_f32_16x16x32_bf16 v[24:27], v[140:143], v[234:237], v[24:27]
	v_mfma_f32_16x16x32_bf16 v[16:19], v[132:135], v[242:245], v[16:19]
	v_mfma_f32_16x16x32_bf16 v[8:11], v[140:143], v[242:245], v[8:11]
	s_setprio 0
	s_setprio 1
	v_mfma_f32_16x16x32_bf16 v[52:55], v[172:175], v[196:199], v[52:55]
	v_mfma_f32_16x16x32_bf16 v[44:47], v[180:183], v[196:199], v[44:47]
	v_mfma_f32_16x16x32_bf16 v[36:39], v[172:175], v[204:207], v[36:39]
	v_mfma_f32_16x16x32_bf16 v[32:35], v[180:183], v[204:207], v[32:35]
	v_mfma_f32_16x16x32_bf16 v[20:23], v[172:175], v[212:215], v[20:23]
	v_mfma_f32_16x16x32_bf16 v[12:15], v[180:183], v[212:215], v[12:15]
	v_mfma_f32_16x16x32_bf16 v[4:7], v[172:175], v[238:241], v[4:7]
	v_mfma_f32_16x16x32_bf16 v[0:3], v[180:183], v[238:241], v[0:3]
	v_mfma_f32_16x16x32_bf16 v[52:55], v[176:179], v[200:203], v[52:55]
	v_mfma_f32_16x16x32_bf16 v[44:47], v[184:187], v[200:203], v[44:47]
	v_mfma_f32_16x16x32_bf16 v[36:39], v[176:179], v[208:211], v[36:39]
	v_mfma_f32_16x16x32_bf16 v[32:35], v[184:187], v[208:211], v[32:35]
	v_mfma_f32_16x16x32_bf16 v[20:23], v[176:179], v[234:237], v[20:23]
	v_mfma_f32_16x16x32_bf16 v[12:15], v[184:187], v[234:237], v[12:15]
	v_mfma_f32_16x16x32_bf16 v[4:7], v[176:179], v[242:245], v[4:7]
	v_mfma_f32_16x16x32_bf16 v[0:3], v[184:187], v[242:245], v[0:3]
	s_setprio 0
	s_barrier
	s_add_i32 s52, 0, 0x18000
	s_add_i32 s53, 0, 0x1c000
	v_add_u32_e32 v140, s52, v157
	v_add_u32_e32 v162, s53, v157
	ds_read_b128 v[128:131], v140
	ds_read_b128 v[132:135], v140 offset:1024
	ds_read_b128 v[136:139], v140 offset:2048
	ds_read_b128 v[140:143], v140 offset:3072
	ds_read_b128 v[172:175], v162
	ds_read_b128 v[176:179], v162 offset:1024
	ds_read_b128 v[180:183], v162 offset:2048
	ds_read_b128 v[184:187], v162 offset:3072
	s_add_u32 s30, s30, 0x80000
	s_addc_u32 s31, s31, 0
	s_mov_b32 m0, s42
	ds_read_b128 v[196:199], v159 offset:32768
	ds_read_b128 v[200:203], v159 offset:33792
	ds_read_b128 v[204:207], v159 offset:34816
	ds_read_b128 v[208:211], v159 offset:35840
	ds_read_b128 v[212:215], v159 offset:36864
	ds_read_b128 v[234:237], v159 offset:37888
	ds_read_b128 v[238:241], v159 offset:38912
	ds_read_b128 v[242:245], v159 offset:39936
	global_load_lds_dwordx4 v148, s[30:31]
	s_mov_b32 m0, s43
	s_nop 0
	global_load_lds_dwordx4 v146, s[30:31]
	s_waitcnt vmcnt(8)
	s_waitcnt lgkmcnt(0)
	s_barrier
	s_setprio 1
	s_waitcnt lgkmcnt(0)
	v_mfma_f32_16x16x32_bf16 v[124:127], v[128:131], v[196:199], v[124:127]
	v_mfma_f32_16x16x32_bf16 v[120:123], v[136:139], v[196:199], v[120:123]
	v_mfma_f32_16x16x32_bf16 v[112:115], v[128:131], v[204:207], v[112:115]
	v_mfma_f32_16x16x32_bf16 v[104:107], v[136:139], v[204:207], v[104:107]
	v_mfma_f32_16x16x32_bf16 v[92:95], v[128:131], v[212:215], v[92:95]
	v_mfma_f32_16x16x32_bf16 v[88:91], v[136:139], v[212:215], v[88:91]
	v_mfma_f32_16x16x32_bf16 v[80:83], v[128:131], v[238:241], v[80:83]
	v_mfma_f32_16x16x32_bf16 v[72:75], v[136:139], v[238:241], v[72:75]
	v_mfma_f32_16x16x32_bf16 v[124:127], v[132:135], v[200:203], v[124:127]
	v_mfma_f32_16x16x32_bf16 v[120:123], v[140:143], v[200:203], v[120:123]
	v_mfma_f32_16x16x32_bf16 v[112:115], v[132:135], v[208:211], v[112:115]
	v_mfma_f32_16x16x32_bf16 v[104:107], v[140:143], v[208:211], v[104:107]
	v_mfma_f32_16x16x32_bf16 v[92:95], v[132:135], v[234:237], v[92:95]
	v_mfma_f32_16x16x32_bf16 v[88:91], v[140:143], v[234:237], v[88:91]
	v_mfma_f32_16x16x32_bf16 v[80:83], v[132:135], v[242:245], v[80:83]
	v_mfma_f32_16x16x32_bf16 v[72:75], v[140:143], v[242:245], v[72:75]
	s_setprio 0
	s_setprio 1
	v_mfma_f32_16x16x32_bf16 v[116:119], v[172:175], v[196:199], v[116:119]
	v_mfma_f32_16x16x32_bf16 v[108:111], v[180:183], v[196:199], v[108:111]
	v_mfma_f32_16x16x32_bf16 v[100:103], v[172:175], v[204:207], v[100:103]
	v_mfma_f32_16x16x32_bf16 v[96:99], v[180:183], v[204:207], v[96:99]
	v_mfma_f32_16x16x32_bf16 v[84:87], v[172:175], v[212:215], v[84:87]
	v_mfma_f32_16x16x32_bf16 v[76:79], v[180:183], v[212:215], v[76:79]
	v_mfma_f32_16x16x32_bf16 v[68:71], v[172:175], v[238:241], v[68:71]
	v_mfma_f32_16x16x32_bf16 v[64:67], v[180:183], v[238:241], v[64:67]
	v_mfma_f32_16x16x32_bf16 v[116:119], v[176:179], v[200:203], v[116:119]
	v_mfma_f32_16x16x32_bf16 v[108:111], v[184:187], v[200:203], v[108:111]
	v_mfma_f32_16x16x32_bf16 v[100:103], v[176:179], v[208:211], v[100:103]
	v_mfma_f32_16x16x32_bf16 v[96:99], v[184:187], v[208:211], v[96:99]
	v_mfma_f32_16x16x32_bf16 v[84:87], v[176:179], v[234:237], v[84:87]
	v_mfma_f32_16x16x32_bf16 v[76:79], v[184:187], v[234:237], v[76:79]
	v_mfma_f32_16x16x32_bf16 v[68:71], v[176:179], v[242:245], v[68:71]
	v_mfma_f32_16x16x32_bf16 v[64:67], v[184:187], v[242:245], v[64:67]
	s_setprio 0
	s_barrier
	s_add_i32 s30, s52, s37
	v_lshl_add_u64 v[154:155], v[154:155], 0, s[20:21]
	s_mov_b32 m0, s30
	ds_read_b128 v[196:199], v159 offset:49152
	ds_read_b128 v[200:203], v159 offset:50176
	ds_read_b128 v[204:207], v159 offset:51200
	ds_read_b128 v[208:211], v159 offset:52224
	ds_read_b128 v[212:215], v159 offset:53248
	ds_read_b128 v[234:237], v159 offset:54272
	ds_read_b128 v[238:241], v159 offset:55296
	ds_read_b128 v[242:245], v159 offset:56320
	global_load_lds_dwordx4 v[154:155], off
	s_add_i32 m0, s30, 0x2000
	s_add_u32 s28, s28, 0x80080
	v_lshl_add_u64 v[154:155], v[188:189], 0, s[20:21]
	s_addc_u32 s29, s29, 0
	s_add_i32 s30, s53, s37
	global_load_lds_dwordx4 v[154:155], off
	s_mov_b32 m0, s30
	s_nop 0
	global_load_lds_dwordx4 v160, s[28:29]
	s_add_i32 m0, s30, 0x2000
	s_nop 0
	global_load_lds_dwordx4 v144, s[28:29]
	v_lshl_add_u64 v[154:155], v[216:217], 0, s[20:21]
	s_mov_b32 m0, s44
	s_nop 0
	global_load_lds_dwordx4 v[154:155], off
	v_lshl_add_u64 v[154:155], v[246:247], 0, s[20:21]
	s_mov_b32 m0, s45
	s_nop 0
	global_load_lds_dwordx4 v[154:155], off
	s_waitcnt vmcnt(8)
	s_waitcnt lgkmcnt(0)
	s_barrier
	s_setprio 1
	s_waitcnt lgkmcnt(0)
	v_mfma_f32_16x16x32_bf16 v[60:63], v[128:131], v[196:199], v[60:63]
	v_mfma_f32_16x16x32_bf16 v[56:59], v[136:139], v[196:199], v[56:59]
	v_mfma_f32_16x16x32_bf16 v[48:51], v[128:131], v[204:207], v[48:51]
	v_mfma_f32_16x16x32_bf16 v[40:43], v[136:139], v[204:207], v[40:43]
	v_mfma_f32_16x16x32_bf16 v[28:31], v[128:131], v[212:215], v[28:31]
	v_mfma_f32_16x16x32_bf16 v[24:27], v[136:139], v[212:215], v[24:27]
	v_mfma_f32_16x16x32_bf16 v[16:19], v[128:131], v[238:241], v[16:19]
	v_mfma_f32_16x16x32_bf16 v[8:11], v[136:139], v[238:241], v[8:11]
	v_mfma_f32_16x16x32_bf16 v[60:63], v[132:135], v[200:203], v[60:63]
	v_mfma_f32_16x16x32_bf16 v[56:59], v[140:143], v[200:203], v[56:59]
	v_mfma_f32_16x16x32_bf16 v[48:51], v[132:135], v[208:211], v[48:51]
	v_mfma_f32_16x16x32_bf16 v[40:43], v[140:143], v[208:211], v[40:43]
	v_mfma_f32_16x16x32_bf16 v[28:31], v[132:135], v[234:237], v[28:31]
	v_mfma_f32_16x16x32_bf16 v[24:27], v[140:143], v[234:237], v[24:27]
	v_mfma_f32_16x16x32_bf16 v[16:19], v[132:135], v[242:245], v[16:19]
	v_mfma_f32_16x16x32_bf16 v[8:11], v[140:143], v[242:245], v[8:11]
	s_setprio 0
	s_setprio 1
	v_mfma_f32_16x16x32_bf16 v[52:55], v[172:175], v[196:199], v[52:55]
	v_mfma_f32_16x16x32_bf16 v[44:47], v[180:183], v[196:199], v[44:47]
	v_mfma_f32_16x16x32_bf16 v[36:39], v[172:175], v[204:207], v[36:39]
	v_mfma_f32_16x16x32_bf16 v[32:35], v[180:183], v[204:207], v[32:35]
	v_mfma_f32_16x16x32_bf16 v[20:23], v[172:175], v[212:215], v[20:23]
	v_mfma_f32_16x16x32_bf16 v[12:15], v[180:183], v[212:215], v[12:15]
	v_mfma_f32_16x16x32_bf16 v[4:7], v[172:175], v[238:241], v[4:7]
	v_mfma_f32_16x16x32_bf16 v[0:3], v[180:183], v[238:241], v[0:3]
	v_mfma_f32_16x16x32_bf16 v[52:55], v[176:179], v[200:203], v[52:55]
	v_mfma_f32_16x16x32_bf16 v[44:47], v[184:187], v[200:203], v[44:47]
	v_mfma_f32_16x16x32_bf16 v[36:39], v[176:179], v[208:211], v[36:39]
	v_mfma_f32_16x16x32_bf16 v[32:35], v[184:187], v[208:211], v[32:35]
	v_mfma_f32_16x16x32_bf16 v[20:23], v[176:179], v[234:237], v[20:23]
	v_mfma_f32_16x16x32_bf16 v[12:15], v[184:187], v[234:237], v[12:15]
	v_mfma_f32_16x16x32_bf16 v[4:7], v[176:179], v[242:245], v[4:7]
	v_mfma_f32_16x16x32_bf16 v[0:3], v[184:187], v[242:245], v[0:3]
	s_setprio 0
	s_barrier
	s_add_i32 s51, s51, 2
	s_add_u32 s26, s26, 0x100
	s_addc_u32 s27, s27, 0
	s_add_u32 s49, s49, 0x100
	s_addc_u32 s50, s50, 0
	s_cmp_gt_u32 s51, 29
	s_cbranch_scc0 .LBB0_1314
	s_and_b64 vcc, exec, s[10:11]
	s_cbranch_vccz .LBB0_1317
	s_barrier

.LBB0_1451:
	s_add_u32 s30, s28, 0xfff80080
	s_addc_u32 s31, s29, -1
	s_add_i32 s55, 0, 0x10000
	s_cmp_eq_u32 s54, 28
	s_cselect_b32 s35, s15, s31
	s_cselect_b32 s34, s50, s30
	s_cselect_b32 s31, s13, s53
	s_cselect_b32 s30, s51, s52
	s_add_i32 s58, 0, 0x14000
	v_add_u32_e32 v154, s55, v139
	v_add_u32_e32 v158, s58, v139
	ds_read_b128 v[142:145], v154
	ds_read_b128 v[146:149], v154 offset:1024
	ds_read_b128 v[150:153], v154 offset:2048
	ds_read_b128 v[154:157], v154 offset:3072
	ds_read_b128 v[172:175], v158
	ds_read_b128 v[176:179], v158 offset:1024
	ds_read_b128 v[180:183], v158 offset:2048
	ds_read_b128 v[184:187], v158 offset:3072
	s_add_i32 m0, s27, 0xc000
	ds_read_b128 v[196:199], v141
	ds_read_b128 v[200:203], v141 offset:1024
	ds_read_b128 v[204:207], v141 offset:2048
	ds_read_b128 v[208:211], v141 offset:3072
	ds_read_b128 v[212:215], v141 offset:4096
	ds_read_b128 v[234:237], v141 offset:5120
	ds_read_b128 v[238:241], v141 offset:6144
	ds_read_b128 v[242:245], v141 offset:7168
	global_load_lds_dwordx4 v134, s[28:29]
	s_add_i32 m0, s27, 0xe000
	s_nop 0
	global_load_lds_dwordx4 v136, s[28:29]
	s_waitcnt vmcnt(8)
	s_waitcnt lgkmcnt(0)
	s_barrier
	s_setprio 1
	s_waitcnt lgkmcnt(0)
	v_mfma_f32_16x16x32_bf16 v[124:127], v[142:145], v[196:199], v[124:127]
	v_mfma_f32_16x16x32_bf16 v[120:123], v[150:153], v[196:199], v[120:123]
	v_mfma_f32_16x16x32_bf16 v[108:111], v[142:145], v[204:207], v[108:111]
	v_mfma_f32_16x16x32_bf16 v[104:107], v[150:153], v[204:207], v[104:107]
	v_mfma_f32_16x16x32_bf16 v[92:95], v[142:145], v[212:215], v[92:95]
	v_mfma_f32_16x16x32_bf16 v[88:91], v[150:153], v[212:215], v[88:91]
	v_mfma_f32_16x16x32_bf16 v[76:79], v[142:145], v[238:241], v[76:79]
	v_mfma_f32_16x16x32_bf16 v[72:75], v[150:153], v[238:241], v[72:75]
	v_mfma_f32_16x16x32_bf16 v[124:127], v[146:149], v[200:203], v[124:127]
	v_mfma_f32_16x16x32_bf16 v[120:123], v[154:157], v[200:203], v[120:123]
	v_mfma_f32_16x16x32_bf16 v[108:111], v[146:149], v[208:211], v[108:111]
	v_mfma_f32_16x16x32_bf16 v[104:107], v[154:157], v[208:211], v[104:107]
	v_mfma_f32_16x16x32_bf16 v[92:95], v[146:149], v[234:237], v[92:95]
	v_mfma_f32_16x16x32_bf16 v[88:91], v[154:157], v[234:237], v[88:91]
	v_mfma_f32_16x16x32_bf16 v[76:79], v[146:149], v[242:245], v[76:79]
	v_mfma_f32_16x16x32_bf16 v[72:75], v[154:157], v[242:245], v[72:75]
	s_setprio 0
	s_setprio 1
	v_mfma_f32_16x16x32_bf16 v[116:119], v[172:175], v[196:199], v[116:119]
	v_mfma_f32_16x16x32_bf16 v[112:115], v[180:183], v[196:199], v[112:115]
	v_mfma_f32_16x16x32_bf16 v[100:103], v[172:175], v[204:207], v[100:103]
	v_mfma_f32_16x16x32_bf16 v[96:99], v[180:183], v[204:207], v[96:99]
	v_mfma_f32_16x16x32_bf16 v[84:87], v[172:175], v[212:215], v[84:87]
	v_mfma_f32_16x16x32_bf16 v[80:83], v[180:183], v[212:215], v[80:83]
	v_mfma_f32_16x16x32_bf16 v[68:71], v[172:175], v[238:241], v[68:71]
	v_mfma_f32_16x16x32_bf16 v[64:67], v[180:183], v[238:241], v[64:67]
	v_mfma_f32_16x16x32_bf16 v[116:119], v[176:179], v[200:203], v[116:119]
	v_mfma_f32_16x16x32_bf16 v[112:115], v[184:187], v[200:203], v[112:115]
	v_mfma_f32_16x16x32_bf16 v[100:103], v[176:179], v[208:211], v[100:103]
	v_mfma_f32_16x16x32_bf16 v[96:99], v[184:187], v[208:211], v[96:99]
	v_mfma_f32_16x16x32_bf16 v[84:87], v[176:179], v[234:237], v[84:87]
	v_mfma_f32_16x16x32_bf16 v[80:83], v[184:187], v[234:237], v[80:83]
	v_mfma_f32_16x16x32_bf16 v[68:71], v[176:179], v[242:245], v[68:71]
	v_mfma_f32_16x16x32_bf16 v[64:67], v[184:187], v[242:245], v[64:67]
	s_setprio 0
	s_barrier
	s_add_i32 s55, s55, s39
	v_lshl_add_u64 v[158:159], s[30:31], 0, v[160:161]
	s_mov_b32 m0, s55
	ds_read_b128 v[196:199], v141 offset:16384
	ds_read_b128 v[200:203], v141 offset:17408
	ds_read_b128 v[204:207], v141 offset:18432
	ds_read_b128 v[208:211], v141 offset:19456
	ds_read_b128 v[212:215], v141 offset:20480
	ds_read_b128 v[234:237], v141 offset:21504
	ds_read_b128 v[238:241], v141 offset:22528
	ds_read_b128 v[242:245], v141 offset:23552
	global_load_lds_dwordx4 v[158:159], off
	s_add_i32 m0, s55, 0x2000
	s_add_u32 s56, s30, 0x80000
	v_lshl_add_u64 v[188:189], s[30:31], 0, v[128:129]
	s_addc_u32 s57, s31, 0
	s_add_i32 s55, s58, s39
	global_load_lds_dwordx4 v[188:189], off
	s_mov_b32 m0, s55
	v_lshl_add_u64 v[246:247], s[34:35], 0, v[130:131]
	global_load_lds_dwordx4 v160, s[56:57]
	s_add_i32 m0, s55, 0x2000
	s_nop 0
	global_load_lds_dwordx4 v128, s[56:57]
	v_lshl_add_u64 v[216:217], s[34:35], 0, v[132:133]
	s_mov_b32 m0, s27
	s_nop 0
	global_load_lds_dwordx4 v[216:217], off
	s_mov_b32 m0, s43
	s_nop 0
	global_load_lds_dwordx4 v[246:247], off
	s_waitcnt vmcnt(8)
	s_waitcnt lgkmcnt(0)
	s_barrier
	s_setprio 1
	s_waitcnt lgkmcnt(0)
	v_mfma_f32_16x16x32_bf16 v[60:63], v[142:145], v[196:199], v[60:63]
	v_mfma_f32_16x16x32_bf16 v[56:59], v[150:153], v[196:199], v[56:59]
	v_mfma_f32_16x16x32_bf16 v[44:47], v[142:145], v[204:207], v[44:47]
	v_mfma_f32_16x16x32_bf16 v[40:43], v[150:153], v[204:207], v[40:43]
	v_mfma_f32_16x16x32_bf16 v[28:31], v[142:145], v[212:215], v[28:31]
	v_mfma_f32_16x16x32_bf16 v[24:27], v[150:153], v[212:215], v[24:27]
	v_mfma_f32_16x16x32_bf16 v[12:15], v[142:145], v[238:241], v[12:15]
	v_mfma_f32_16x16x32_bf16 v[8:11], v[150:153], v[238:241], v[8:11]
	v_mfma_f32_16x16x32_bf16 v[60:63], v[146:149], v[200:203], v[60:63]
	v_mfma_f32_16x16x32_bf16 v[56:59], v[154:157], v[200:203], v[56:59]
	v_mfma_f32_16x16x32_bf16 v[44:47], v[146:149], v[208:211], v[44:47]
	v_mfma_f32_16x16x32_bf16 v[40:43], v[154:157], v[208:211], v[40:43]
	v_mfma_f32_16x16x32_bf16 v[28:31], v[146:149], v[234:237], v[28:31]
	v_mfma_f32_16x16x32_bf16 v[24:27], v[154:157], v[234:237], v[24:27]
	v_mfma_f32_16x16x32_bf16 v[12:15], v[146:149], v[242:245], v[12:15]
	v_mfma_f32_16x16x32_bf16 v[8:11], v[154:157], v[242:245], v[8:11]
	s_setprio 0
	s_setprio 1
	v_mfma_f32_16x16x32_bf16 v[52:55], v[172:175], v[196:199], v[52:55]
	v_mfma_f32_16x16x32_bf16 v[48:51], v[180:183], v[196:199], v[48:51]
	v_mfma_f32_16x16x32_bf16 v[36:39], v[172:175], v[204:207], v[36:39]
	v_mfma_f32_16x16x32_bf16 v[32:35], v[180:183], v[204:207], v[32:35]
	v_mfma_f32_16x16x32_bf16 v[20:23], v[172:175], v[212:215], v[20:23]
	v_mfma_f32_16x16x32_bf16 v[16:19], v[180:183], v[212:215], v[16:19]
	v_mfma_f32_16x16x32_bf16 v[4:7], v[172:175], v[238:241], v[4:7]
	v_mfma_f32_16x16x32_bf16 v[0:3], v[180:183], v[238:241], v[0:3]
	v_mfma_f32_16x16x32_bf16 v[52:55], v[176:179], v[200:203], v[52:55]
	v_mfma_f32_16x16x32_bf16 v[48:51], v[184:187], v[200:203], v[48:51]
	v_mfma_f32_16x16x32_bf16 v[36:39], v[176:179], v[208:211], v[36:39]
	v_mfma_f32_16x16x32_bf16 v[32:35], v[184:187], v[208:211], v[32:35]
	v_mfma_f32_16x16x32_bf16 v[20:23], v[176:179], v[234:237], v[20:23]
	v_mfma_f32_16x16x32_bf16 v[16:19], v[184:187], v[234:237], v[16:19]
	v_mfma_f32_16x16x32_bf16 v[4:7], v[176:179], v[242:245], v[4:7]
	v_mfma_f32_16x16x32_bf16 v[0:3], v[184:187], v[242:245], v[0:3]
	s_setprio 0
	s_barrier
	s_add_i32 s55, 0, 0x18000
	s_add_i32 s56, 0, 0x1c000
	v_add_u32_e32 v154, s55, v139
	v_add_u32_e32 v162, s56, v139
	ds_read_b128 v[142:145], v154
	ds_read_b128 v[146:149], v154 offset:1024
	ds_read_b128 v[150:153], v154 offset:2048
	ds_read_b128 v[154:157], v154 offset:3072
	ds_read_b128 v[172:175], v162
	ds_read_b128 v[176:179], v162 offset:1024
	ds_read_b128 v[180:183], v162 offset:2048
	ds_read_b128 v[184:187], v162 offset:3072
	s_add_u32 s34, s34, 0x80000
	s_addc_u32 s35, s35, 0
	s_mov_b32 m0, s44
	ds_read_b128 v[196:199], v141 offset:32768
	ds_read_b128 v[200:203], v141 offset:33792
	ds_read_b128 v[204:207], v141 offset:34816
	ds_read_b128 v[208:211], v141 offset:35840
	ds_read_b128 v[212:215], v141 offset:36864
	ds_read_b128 v[234:237], v141 offset:37888
	ds_read_b128 v[238:241], v141 offset:38912
	ds_read_b128 v[242:245], v141 offset:39936
	global_load_lds_dwordx4 v132, s[34:35]
	s_mov_b32 m0, s45
	s_nop 0
	global_load_lds_dwordx4 v130, s[34:35]
	s_waitcnt vmcnt(8)
	s_waitcnt lgkmcnt(0)
	s_barrier
	s_setprio 1
	s_waitcnt lgkmcnt(0)
	v_mfma_f32_16x16x32_bf16 v[124:127], v[142:145], v[196:199], v[124:127]
	v_mfma_f32_16x16x32_bf16 v[120:123], v[150:153], v[196:199], v[120:123]
	v_mfma_f32_16x16x32_bf16 v[108:111], v[142:145], v[204:207], v[108:111]
	v_mfma_f32_16x16x32_bf16 v[104:107], v[150:153], v[204:207], v[104:107]
	v_mfma_f32_16x16x32_bf16 v[92:95], v[142:145], v[212:215], v[92:95]
	v_mfma_f32_16x16x32_bf16 v[88:91], v[150:153], v[212:215], v[88:91]
	v_mfma_f32_16x16x32_bf16 v[76:79], v[142:145], v[238:241], v[76:79]
	v_mfma_f32_16x16x32_bf16 v[72:75], v[150:153], v[238:241], v[72:75]
	v_mfma_f32_16x16x32_bf16 v[124:127], v[146:149], v[200:203], v[124:127]
	v_mfma_f32_16x16x32_bf16 v[120:123], v[154:157], v[200:203], v[120:123]
	v_mfma_f32_16x16x32_bf16 v[108:111], v[146:149], v[208:211], v[108:111]
	v_mfma_f32_16x16x32_bf16 v[104:107], v[154:157], v[208:211], v[104:107]
	v_mfma_f32_16x16x32_bf16 v[92:95], v[146:149], v[234:237], v[92:95]
	v_mfma_f32_16x16x32_bf16 v[88:91], v[154:157], v[234:237], v[88:91]
	v_mfma_f32_16x16x32_bf16 v[76:79], v[146:149], v[242:245], v[76:79]
	v_mfma_f32_16x16x32_bf16 v[72:75], v[154:157], v[242:245], v[72:75]
	s_setprio 0
	s_setprio 1
	v_mfma_f32_16x16x32_bf16 v[116:119], v[172:175], v[196:199], v[116:119]
	v_mfma_f32_16x16x32_bf16 v[112:115], v[180:183], v[196:199], v[112:115]
	v_mfma_f32_16x16x32_bf16 v[100:103], v[172:175], v[204:207], v[100:103]
	v_mfma_f32_16x16x32_bf16 v[96:99], v[180:183], v[204:207], v[96:99]
	v_mfma_f32_16x16x32_bf16 v[84:87], v[172:175], v[212:215], v[84:87]
	v_mfma_f32_16x16x32_bf16 v[80:83], v[180:183], v[212:215], v[80:83]
	v_mfma_f32_16x16x32_bf16 v[68:71], v[172:175], v[238:241], v[68:71]
	v_mfma_f32_16x16x32_bf16 v[64:67], v[180:183], v[238:241], v[64:67]
	v_mfma_f32_16x16x32_bf16 v[116:119], v[176:179], v[200:203], v[116:119]
	v_mfma_f32_16x16x32_bf16 v[112:115], v[184:187], v[200:203], v[112:115]
	v_mfma_f32_16x16x32_bf16 v[100:103], v[176:179], v[208:211], v[100:103]
	v_mfma_f32_16x16x32_bf16 v[96:99], v[184:187], v[208:211], v[96:99]
	v_mfma_f32_16x16x32_bf16 v[84:87], v[176:179], v[234:237], v[84:87]
	v_mfma_f32_16x16x32_bf16 v[80:83], v[184:187], v[234:237], v[80:83]
	v_mfma_f32_16x16x32_bf16 v[68:71], v[176:179], v[242:245], v[68:71]
	v_mfma_f32_16x16x32_bf16 v[64:67], v[184:187], v[242:245], v[64:67]
	s_setprio 0
	s_barrier
	s_add_i32 s34, s55, s39
	v_lshl_add_u64 v[158:159], v[158:159], 0, s[20:21]
	s_mov_b32 m0, s34
	ds_read_b128 v[196:199], v141 offset:49152
	ds_read_b128 v[200:203], v141 offset:50176
	ds_read_b128 v[204:207], v141 offset:51200
	ds_read_b128 v[208:211], v141 offset:52224
	ds_read_b128 v[212:215], v141 offset:53248
	ds_read_b128 v[234:237], v141 offset:54272
	ds_read_b128 v[238:241], v141 offset:55296
	ds_read_b128 v[242:245], v141 offset:56320
	global_load_lds_dwordx4 v[158:159], off
	s_add_i32 m0, s34, 0x2000
	s_add_u32 s30, s30, 0x80080
	v_lshl_add_u64 v[158:159], v[188:189], 0, s[20:21]
	s_addc_u32 s31, s31, 0
	s_add_i32 s34, s56, s39
	global_load_lds_dwordx4 v[158:159], off
	s_mov_b32 m0, s34
	s_nop 0
	global_load_lds_dwordx4 v160, s[30:31]
	s_add_i32 m0, s34, 0x2000
	s_nop 0
	global_load_lds_dwordx4 v128, s[30:31]
	v_lshl_add_u64 v[158:159], v[216:217], 0, s[20:21]
	s_mov_b32 m0, s46
	s_nop 0
	global_load_lds_dwordx4 v[158:159], off
	v_lshl_add_u64 v[158:159], v[246:247], 0, s[20:21]
	s_mov_b32 m0, s47
	s_nop 0
	global_load_lds_dwordx4 v[158:159], off
	s_waitcnt vmcnt(8)
	s_waitcnt lgkmcnt(0)
	s_barrier
	s_setprio 1
	s_waitcnt lgkmcnt(0)
	v_mfma_f32_16x16x32_bf16 v[60:63], v[142:145], v[196:199], v[60:63]
	v_mfma_f32_16x16x32_bf16 v[56:59], v[150:153], v[196:199], v[56:59]
	v_mfma_f32_16x16x32_bf16 v[44:47], v[142:145], v[204:207], v[44:47]
	v_mfma_f32_16x16x32_bf16 v[40:43], v[150:153], v[204:207], v[40:43]
	v_mfma_f32_16x16x32_bf16 v[28:31], v[142:145], v[212:215], v[28:31]
	v_mfma_f32_16x16x32_bf16 v[24:27], v[150:153], v[212:215], v[24:27]
	v_mfma_f32_16x16x32_bf16 v[12:15], v[142:145], v[238:241], v[12:15]
	v_mfma_f32_16x16x32_bf16 v[8:11], v[150:153], v[238:241], v[8:11]
	v_mfma_f32_16x16x32_bf16 v[60:63], v[146:149], v[200:203], v[60:63]
	v_mfma_f32_16x16x32_bf16 v[56:59], v[154:157], v[200:203], v[56:59]
	v_mfma_f32_16x16x32_bf16 v[44:47], v[146:149], v[208:211], v[44:47]
	v_mfma_f32_16x16x32_bf16 v[40:43], v[154:157], v[208:211], v[40:43]
	v_mfma_f32_16x16x32_bf16 v[28:31], v[146:149], v[234:237], v[28:31]
	v_mfma_f32_16x16x32_bf16 v[24:27], v[154:157], v[234:237], v[24:27]
	v_mfma_f32_16x16x32_bf16 v[12:15], v[146:149], v[242:245], v[12:15]
	v_mfma_f32_16x16x32_bf16 v[8:11], v[154:157], v[242:245], v[8:11]
	s_setprio 0
	s_setprio 1
	v_mfma_f32_16x16x32_bf16 v[52:55], v[172:175], v[196:199], v[52:55]
	v_mfma_f32_16x16x32_bf16 v[48:51], v[180:183], v[196:199], v[48:51]
	v_mfma_f32_16x16x32_bf16 v[36:39], v[172:175], v[204:207], v[36:39]
	v_mfma_f32_16x16x32_bf16 v[32:35], v[180:183], v[204:207], v[32:35]
	v_mfma_f32_16x16x32_bf16 v[20:23], v[172:175], v[212:215], v[20:23]
	v_mfma_f32_16x16x32_bf16 v[16:19], v[180:183], v[212:215], v[16:19]
	v_mfma_f32_16x16x32_bf16 v[4:7], v[172:175], v[238:241], v[4:7]
	v_mfma_f32_16x16x32_bf16 v[0:3], v[180:183], v[238:241], v[0:3]
	v_mfma_f32_16x16x32_bf16 v[52:55], v[176:179], v[200:203], v[52:55]
	v_mfma_f32_16x16x32_bf16 v[48:51], v[184:187], v[200:203], v[48:51]
	v_mfma_f32_16x16x32_bf16 v[36:39], v[176:179], v[208:211], v[36:39]
	v_mfma_f32_16x16x32_bf16 v[32:35], v[184:187], v[208:211], v[32:35]
	v_mfma_f32_16x16x32_bf16 v[20:23], v[176:179], v[234:237], v[20:23]
	v_mfma_f32_16x16x32_bf16 v[16:19], v[184:187], v[234:237], v[16:19]
	v_mfma_f32_16x16x32_bf16 v[4:7], v[176:179], v[242:245], v[4:7]
	v_mfma_f32_16x16x32_bf16 v[0:3], v[184:187], v[242:245], v[0:3]
	s_setprio 0
	s_barrier
	s_add_i32 s54, s54, 2
	s_add_u32 s28, s28, 0x100
	s_addc_u32 s29, s29, 0
	s_add_u32 s52, s52, 0x100
	s_addc_u32 s53, s53, 0
	s_cmp_gt_u32 s54, 29
	s_cbranch_scc0 .LBB0_1451
	s_and_b64 vcc, exec, s[10:11]
	s_cbranch_vccz .LBB0_1454
	s_barrier

.LBB0_1522:
	s_add_u32 s28, s26, 0xffe00080
	s_addc_u32 s29, s27, -1
	s_add_i32 s53, 0, 0x10000
	s_cmpk_eq_i32 s52, 0x7c
	s_cselect_b32 s31, s13, s29
	s_cselect_b32 s30, s48, s28
	s_cselect_b32 s29, s11, s51
	s_cselect_b32 s28, s49, s50
	s_add_i32 s56, 0, 0x14000
	v_add_u32_e32 v140, s53, v157
	v_add_u32_e32 v154, s56, v157
	ds_read_b128 v[128:131], v140
	ds_read_b128 v[132:135], v140 offset:1024
	ds_read_b128 v[136:139], v140 offset:2048
	ds_read_b128 v[140:143], v140 offset:3072
	ds_read_b128 v[172:175], v154
	ds_read_b128 v[176:179], v154 offset:1024
	ds_read_b128 v[180:183], v154 offset:2048
	ds_read_b128 v[184:187], v154 offset:3072
	s_add_i32 m0, s19, 0xc000
	ds_read_b128 v[196:199], v159
	ds_read_b128 v[200:203], v159 offset:1024
	ds_read_b128 v[204:207], v159 offset:2048
	ds_read_b128 v[208:211], v159 offset:3072
	ds_read_b128 v[212:215], v159 offset:4096
	ds_read_b128 v[234:237], v159 offset:5120
	ds_read_b128 v[238:241], v159 offset:6144
	ds_read_b128 v[242:245], v159 offset:7168
	global_load_lds_dwordx4 v150, s[26:27]
	s_add_i32 m0, s19, 0xe000
	s_nop 0
	global_load_lds_dwordx4 v152, s[26:27]
	s_waitcnt vmcnt(8)
	s_waitcnt lgkmcnt(0)
	s_barrier
	s_setprio 1
	s_waitcnt lgkmcnt(0)
	v_mfma_f32_16x16x32_bf16 v[124:127], v[128:131], v[196:199], v[124:127]
	v_mfma_f32_16x16x32_bf16 v[120:123], v[136:139], v[196:199], v[120:123]
	v_mfma_f32_16x16x32_bf16 v[116:119], v[128:131], v[204:207], v[116:119]
	v_mfma_f32_16x16x32_bf16 v[108:111], v[136:139], v[204:207], v[108:111]
	v_mfma_f32_16x16x32_bf16 v[92:95], v[128:131], v[212:215], v[92:95]
	v_mfma_f32_16x16x32_bf16 v[88:91], v[136:139], v[212:215], v[88:91]
	v_mfma_f32_16x16x32_bf16 v[84:87], v[128:131], v[238:241], v[84:87]
	v_mfma_f32_16x16x32_bf16 v[76:79], v[136:139], v[238:241], v[76:79]
	v_mfma_f32_16x16x32_bf16 v[124:127], v[132:135], v[200:203], v[124:127]
	v_mfma_f32_16x16x32_bf16 v[120:123], v[140:143], v[200:203], v[120:123]
	v_mfma_f32_16x16x32_bf16 v[116:119], v[132:135], v[208:211], v[116:119]
	v_mfma_f32_16x16x32_bf16 v[108:111], v[140:143], v[208:211], v[108:111]
	v_mfma_f32_16x16x32_bf16 v[92:95], v[132:135], v[234:237], v[92:95]
	v_mfma_f32_16x16x32_bf16 v[88:91], v[140:143], v[234:237], v[88:91]
	v_mfma_f32_16x16x32_bf16 v[84:87], v[132:135], v[242:245], v[84:87]
	v_mfma_f32_16x16x32_bf16 v[76:79], v[140:143], v[242:245], v[76:79]
	s_setprio 0
	s_setprio 1
	v_mfma_f32_16x16x32_bf16 v[112:115], v[172:175], v[196:199], v[112:115]
	v_mfma_f32_16x16x32_bf16 v[104:107], v[180:183], v[196:199], v[104:107]
	v_mfma_f32_16x16x32_bf16 v[100:103], v[172:175], v[204:207], v[100:103]
	v_mfma_f32_16x16x32_bf16 v[96:99], v[180:183], v[204:207], v[96:99]
	v_mfma_f32_16x16x32_bf16 v[80:83], v[172:175], v[212:215], v[80:83]
	v_mfma_f32_16x16x32_bf16 v[72:75], v[180:183], v[212:215], v[72:75]
	v_mfma_f32_16x16x32_bf16 v[68:71], v[172:175], v[238:241], v[68:71]
	v_mfma_f32_16x16x32_bf16 v[64:67], v[180:183], v[238:241], v[64:67]
	v_mfma_f32_16x16x32_bf16 v[112:115], v[176:179], v[200:203], v[112:115]
	v_mfma_f32_16x16x32_bf16 v[104:107], v[184:187], v[200:203], v[104:107]
	v_mfma_f32_16x16x32_bf16 v[100:103], v[176:179], v[208:211], v[100:103]
	v_mfma_f32_16x16x32_bf16 v[96:99], v[184:187], v[208:211], v[96:99]
	v_mfma_f32_16x16x32_bf16 v[80:83], v[176:179], v[234:237], v[80:83]
	v_mfma_f32_16x16x32_bf16 v[72:75], v[184:187], v[234:237], v[72:75]
	v_mfma_f32_16x16x32_bf16 v[68:71], v[176:179], v[242:245], v[68:71]
	v_mfma_f32_16x16x32_bf16 v[64:67], v[184:187], v[242:245], v[64:67]
	s_setprio 0
	s_barrier
	s_add_i32 s53, s53, s39
	v_lshl_add_u64 v[154:155], s[28:29], 0, v[160:161]
	s_mov_b32 m0, s53
	ds_read_b128 v[196:199], v159 offset:16384
	ds_read_b128 v[200:203], v159 offset:17408
	ds_read_b128 v[204:207], v159 offset:18432
	ds_read_b128 v[208:211], v159 offset:19456
	ds_read_b128 v[212:215], v159 offset:20480
	ds_read_b128 v[234:237], v159 offset:21504
	ds_read_b128 v[238:241], v159 offset:22528
	ds_read_b128 v[242:245], v159 offset:23552
	global_load_lds_dwordx4 v[154:155], off
	s_add_i32 m0, s53, 0x2000
	s_add_u32 s54, s28, 0x200000
	v_lshl_add_u64 v[188:189], s[28:29], 0, v[144:145]
	s_addc_u32 s55, s29, 0
	s_add_i32 s53, s56, s39
	global_load_lds_dwordx4 v[188:189], off
	s_mov_b32 m0, s53
	v_lshl_add_u64 v[246:247], s[30:31], 0, v[146:147]
	global_load_lds_dwordx4 v160, s[54:55]
	s_add_i32 m0, s53, 0x2000
	s_nop 0
	global_load_lds_dwordx4 v144, s[54:55]
	v_lshl_add_u64 v[216:217], s[30:31], 0, v[148:149]
	s_mov_b32 m0, s19
	s_nop 0
	global_load_lds_dwordx4 v[216:217], off
	s_mov_b32 m0, s41
	s_nop 0
	global_load_lds_dwordx4 v[246:247], off
	s_waitcnt vmcnt(8)
	s_waitcnt lgkmcnt(0)
	s_barrier
	s_setprio 1
	s_waitcnt lgkmcnt(0)
	v_mfma_f32_16x16x32_bf16 v[60:63], v[128:131], v[196:199], v[60:63]
	v_mfma_f32_16x16x32_bf16 v[56:59], v[136:139], v[196:199], v[56:59]
	v_mfma_f32_16x16x32_bf16 v[52:55], v[128:131], v[204:207], v[52:55]
	v_mfma_f32_16x16x32_bf16 v[44:47], v[136:139], v[204:207], v[44:47]
	v_mfma_f32_16x16x32_bf16 v[28:31], v[128:131], v[212:215], v[28:31]
	v_mfma_f32_16x16x32_bf16 v[24:27], v[136:139], v[212:215], v[24:27]
	v_mfma_f32_16x16x32_bf16 v[20:23], v[128:131], v[238:241], v[20:23]
	v_mfma_f32_16x16x32_bf16 v[12:15], v[136:139], v[238:241], v[12:15]
	v_mfma_f32_16x16x32_bf16 v[60:63], v[132:135], v[200:203], v[60:63]
	v_mfma_f32_16x16x32_bf16 v[56:59], v[140:143], v[200:203], v[56:59]
	v_mfma_f32_16x16x32_bf16 v[52:55], v[132:135], v[208:211], v[52:55]
	v_mfma_f32_16x16x32_bf16 v[44:47], v[140:143], v[208:211], v[44:47]
	v_mfma_f32_16x16x32_bf16 v[28:31], v[132:135], v[234:237], v[28:31]
	v_mfma_f32_16x16x32_bf16 v[24:27], v[140:143], v[234:237], v[24:27]
	v_mfma_f32_16x16x32_bf16 v[20:23], v[132:135], v[242:245], v[20:23]
	v_mfma_f32_16x16x32_bf16 v[12:15], v[140:143], v[242:245], v[12:15]
	s_setprio 0
	s_setprio 1
	v_mfma_f32_16x16x32_bf16 v[48:51], v[172:175], v[196:199], v[48:51]
	v_mfma_f32_16x16x32_bf16 v[40:43], v[180:183], v[196:199], v[40:43]
	v_mfma_f32_16x16x32_bf16 v[36:39], v[172:175], v[204:207], v[36:39]
	v_mfma_f32_16x16x32_bf16 v[32:35], v[180:183], v[204:207], v[32:35]
	v_mfma_f32_16x16x32_bf16 v[16:19], v[172:175], v[212:215], v[16:19]
	v_mfma_f32_16x16x32_bf16 v[8:11], v[180:183], v[212:215], v[8:11]
	v_mfma_f32_16x16x32_bf16 v[4:7], v[172:175], v[238:241], v[4:7]
	v_mfma_f32_16x16x32_bf16 v[0:3], v[180:183], v[238:241], v[0:3]
	v_mfma_f32_16x16x32_bf16 v[48:51], v[176:179], v[200:203], v[48:51]
	v_mfma_f32_16x16x32_bf16 v[40:43], v[184:187], v[200:203], v[40:43]
	v_mfma_f32_16x16x32_bf16 v[36:39], v[176:179], v[208:211], v[36:39]
	v_mfma_f32_16x16x32_bf16 v[32:35], v[184:187], v[208:211], v[32:35]
	v_mfma_f32_16x16x32_bf16 v[16:19], v[176:179], v[234:237], v[16:19]
	v_mfma_f32_16x16x32_bf16 v[8:11], v[184:187], v[234:237], v[8:11]
	v_mfma_f32_16x16x32_bf16 v[4:7], v[176:179], v[242:245], v[4:7]
	v_mfma_f32_16x16x32_bf16 v[0:3], v[184:187], v[242:245], v[0:3]
	s_setprio 0
	s_barrier
	s_add_i32 s53, 0, 0x18000
	s_add_i32 s54, 0, 0x1c000
	v_add_u32_e32 v140, s53, v157
	v_add_u32_e32 v162, s54, v157
	ds_read_b128 v[128:131], v140
	ds_read_b128 v[132:135], v140 offset:1024
	ds_read_b128 v[136:139], v140 offset:2048
	ds_read_b128 v[140:143], v140 offset:3072
	ds_read_b128 v[172:175], v162
	ds_read_b128 v[176:179], v162 offset:1024
	ds_read_b128 v[180:183], v162 offset:2048
	ds_read_b128 v[184:187], v162 offset:3072
	s_add_u32 s30, s30, 0x200000
	s_addc_u32 s31, s31, 0
	s_mov_b32 m0, s42
	ds_read_b128 v[196:199], v159 offset:32768
	ds_read_b128 v[200:203], v159 offset:33792
	ds_read_b128 v[204:207], v159 offset:34816
	ds_read_b128 v[208:211], v159 offset:35840
	ds_read_b128 v[212:215], v159 offset:36864
	ds_read_b128 v[234:237], v159 offset:37888
	ds_read_b128 v[238:241], v159 offset:38912
	ds_read_b128 v[242:245], v159 offset:39936
	global_load_lds_dwordx4 v148, s[30:31]
	s_mov_b32 m0, s43
	s_nop 0
	global_load_lds_dwordx4 v146, s[30:31]
	s_waitcnt vmcnt(8)
	s_waitcnt lgkmcnt(0)
	s_barrier
	s_setprio 1
	s_waitcnt lgkmcnt(0)
	v_mfma_f32_16x16x32_bf16 v[124:127], v[128:131], v[196:199], v[124:127]
	v_mfma_f32_16x16x32_bf16 v[120:123], v[136:139], v[196:199], v[120:123]
	v_mfma_f32_16x16x32_bf16 v[116:119], v[128:131], v[204:207], v[116:119]
	v_mfma_f32_16x16x32_bf16 v[108:111], v[136:139], v[204:207], v[108:111]
	v_mfma_f32_16x16x32_bf16 v[92:95], v[128:131], v[212:215], v[92:95]
	v_mfma_f32_16x16x32_bf16 v[88:91], v[136:139], v[212:215], v[88:91]
	v_mfma_f32_16x16x32_bf16 v[84:87], v[128:131], v[238:241], v[84:87]
	v_mfma_f32_16x16x32_bf16 v[76:79], v[136:139], v[238:241], v[76:79]
	v_mfma_f32_16x16x32_bf16 v[124:127], v[132:135], v[200:203], v[124:127]
	v_mfma_f32_16x16x32_bf16 v[120:123], v[140:143], v[200:203], v[120:123]
	v_mfma_f32_16x16x32_bf16 v[116:119], v[132:135], v[208:211], v[116:119]
	v_mfma_f32_16x16x32_bf16 v[108:111], v[140:143], v[208:211], v[108:111]
	v_mfma_f32_16x16x32_bf16 v[92:95], v[132:135], v[234:237], v[92:95]
	v_mfma_f32_16x16x32_bf16 v[88:91], v[140:143], v[234:237], v[88:91]
	v_mfma_f32_16x16x32_bf16 v[84:87], v[132:135], v[242:245], v[84:87]
	v_mfma_f32_16x16x32_bf16 v[76:79], v[140:143], v[242:245], v[76:79]
	s_setprio 0
	s_setprio 1
	v_mfma_f32_16x16x32_bf16 v[112:115], v[172:175], v[196:199], v[112:115]
	v_mfma_f32_16x16x32_bf16 v[104:107], v[180:183], v[196:199], v[104:107]
	v_mfma_f32_16x16x32_bf16 v[100:103], v[172:175], v[204:207], v[100:103]
	v_mfma_f32_16x16x32_bf16 v[96:99], v[180:183], v[204:207], v[96:99]
	v_mfma_f32_16x16x32_bf16 v[80:83], v[172:175], v[212:215], v[80:83]
	v_mfma_f32_16x16x32_bf16 v[72:75], v[180:183], v[212:215], v[72:75]
	v_mfma_f32_16x16x32_bf16 v[68:71], v[172:175], v[238:241], v[68:71]
	v_mfma_f32_16x16x32_bf16 v[64:67], v[180:183], v[238:241], v[64:67]
	v_mfma_f32_16x16x32_bf16 v[112:115], v[176:179], v[200:203], v[112:115]
	v_mfma_f32_16x16x32_bf16 v[104:107], v[184:187], v[200:203], v[104:107]
	v_mfma_f32_16x16x32_bf16 v[100:103], v[176:179], v[208:211], v[100:103]
	v_mfma_f32_16x16x32_bf16 v[96:99], v[184:187], v[208:211], v[96:99]
	v_mfma_f32_16x16x32_bf16 v[80:83], v[176:179], v[234:237], v[80:83]
	v_mfma_f32_16x16x32_bf16 v[72:75], v[184:187], v[234:237], v[72:75]
	v_mfma_f32_16x16x32_bf16 v[68:71], v[176:179], v[242:245], v[68:71]
	v_mfma_f32_16x16x32_bf16 v[64:67], v[184:187], v[242:245], v[64:67]
	s_setprio 0
	s_barrier
	s_add_i32 s30, s53, s39
	v_lshl_add_u64 v[154:155], v[154:155], 0, s[20:21]
	s_mov_b32 m0, s30
	ds_read_b128 v[196:199], v159 offset:49152
	ds_read_b128 v[200:203], v159 offset:50176
	ds_read_b128 v[204:207], v159 offset:51200
	ds_read_b128 v[208:211], v159 offset:52224
	ds_read_b128 v[212:215], v159 offset:53248
	ds_read_b128 v[234:237], v159 offset:54272
	ds_read_b128 v[238:241], v159 offset:55296
	ds_read_b128 v[242:245], v159 offset:56320
	global_load_lds_dwordx4 v[154:155], off
	s_add_i32 m0, s30, 0x2000
	s_add_u32 s28, s28, 0x200080
	v_lshl_add_u64 v[154:155], v[188:189], 0, s[20:21]
	s_addc_u32 s29, s29, 0
	s_add_i32 s30, s54, s39
	global_load_lds_dwordx4 v[154:155], off
	s_mov_b32 m0, s30
	s_nop 0
	global_load_lds_dwordx4 v160, s[28:29]
	s_add_i32 m0, s30, 0x2000
	s_nop 0
	global_load_lds_dwordx4 v144, s[28:29]
	v_lshl_add_u64 v[154:155], v[216:217], 0, s[20:21]
	s_mov_b32 m0, s44
	s_nop 0
	global_load_lds_dwordx4 v[154:155], off
	v_lshl_add_u64 v[154:155], v[246:247], 0, s[20:21]
	s_mov_b32 m0, s45
	s_nop 0
	global_load_lds_dwordx4 v[154:155], off
	s_waitcnt vmcnt(8)
	s_waitcnt lgkmcnt(0)
	s_barrier
	s_setprio 1
	s_waitcnt lgkmcnt(0)
	v_mfma_f32_16x16x32_bf16 v[60:63], v[128:131], v[196:199], v[60:63]
	v_mfma_f32_16x16x32_bf16 v[56:59], v[136:139], v[196:199], v[56:59]
	v_mfma_f32_16x16x32_bf16 v[52:55], v[128:131], v[204:207], v[52:55]
	v_mfma_f32_16x16x32_bf16 v[44:47], v[136:139], v[204:207], v[44:47]
	v_mfma_f32_16x16x32_bf16 v[28:31], v[128:131], v[212:215], v[28:31]
	v_mfma_f32_16x16x32_bf16 v[24:27], v[136:139], v[212:215], v[24:27]
	v_mfma_f32_16x16x32_bf16 v[20:23], v[128:131], v[238:241], v[20:23]
	v_mfma_f32_16x16x32_bf16 v[12:15], v[136:139], v[238:241], v[12:15]
	v_mfma_f32_16x16x32_bf16 v[60:63], v[132:135], v[200:203], v[60:63]
	v_mfma_f32_16x16x32_bf16 v[56:59], v[140:143], v[200:203], v[56:59]
	v_mfma_f32_16x16x32_bf16 v[52:55], v[132:135], v[208:211], v[52:55]
	v_mfma_f32_16x16x32_bf16 v[44:47], v[140:143], v[208:211], v[44:47]
	v_mfma_f32_16x16x32_bf16 v[28:31], v[132:135], v[234:237], v[28:31]
	v_mfma_f32_16x16x32_bf16 v[24:27], v[140:143], v[234:237], v[24:27]
	v_mfma_f32_16x16x32_bf16 v[20:23], v[132:135], v[242:245], v[20:23]
	v_mfma_f32_16x16x32_bf16 v[12:15], v[140:143], v[242:245], v[12:15]
	s_setprio 0
	s_setprio 1
	v_mfma_f32_16x16x32_bf16 v[48:51], v[172:175], v[196:199], v[48:51]
	v_mfma_f32_16x16x32_bf16 v[40:43], v[180:183], v[196:199], v[40:43]
	v_mfma_f32_16x16x32_bf16 v[36:39], v[172:175], v[204:207], v[36:39]
	v_mfma_f32_16x16x32_bf16 v[32:35], v[180:183], v[204:207], v[32:35]
	v_mfma_f32_16x16x32_bf16 v[16:19], v[172:175], v[212:215], v[16:19]
	v_mfma_f32_16x16x32_bf16 v[8:11], v[180:183], v[212:215], v[8:11]
	v_mfma_f32_16x16x32_bf16 v[4:7], v[172:175], v[238:241], v[4:7]
	v_mfma_f32_16x16x32_bf16 v[0:3], v[180:183], v[238:241], v[0:3]
	v_mfma_f32_16x16x32_bf16 v[48:51], v[176:179], v[200:203], v[48:51]
	v_mfma_f32_16x16x32_bf16 v[40:43], v[184:187], v[200:203], v[40:43]
	v_mfma_f32_16x16x32_bf16 v[36:39], v[176:179], v[208:211], v[36:39]
	v_mfma_f32_16x16x32_bf16 v[32:35], v[184:187], v[208:211], v[32:35]
	v_mfma_f32_16x16x32_bf16 v[16:19], v[176:179], v[234:237], v[16:19]
	v_mfma_f32_16x16x32_bf16 v[8:11], v[184:187], v[234:237], v[8:11]
	v_mfma_f32_16x16x32_bf16 v[4:7], v[176:179], v[242:245], v[4:7]
	v_mfma_f32_16x16x32_bf16 v[0:3], v[184:187], v[242:245], v[0:3]
	s_setprio 0
	s_barrier
	s_add_i32 s52, s52, 2
	s_add_u32 s26, s26, 0x100
	s_addc_u32 s27, s27, 0
	s_add_u32 s50, s50, 0x100
	s_addc_u32 s51, s51, 0
	s_cmpk_gt_u32 s52, 0x7d
	s_cbranch_scc0 .LBB0_1522
	s_and_b64 vcc, exec, s[8:9]
	s_cbranch_vccz .LBB0_1525
	s_barrier
